# stack9 + residual epilogue: second column group's row loads issued with the first group's (one HBM round trip per row block) in 28 of 64 row blocks
# baseline (speedup 1.0000x reference)
; DEVI unsigned pk2(float lo, float hi) { unsigned r; asm("v_cvt_pk_bf16_f32 %0, %1, %2" : "=v"(r) : "v"(lo), "v"(hi)); return r; }
; DEVI void row_stats(const float* stats, int row, float& mu, float& rs) {
;     if (stats) { const float2 st = *(const float2*)(stats + 2 * (size_t)row); mu = st.x * (1.0f / 1024.0f); const float var = st.y * (1.0f / 1024.0f) - mu * mu; rs = rsqrtf(fmaxf(var, 0.f) + LN_EPS); }
;     DEVI void operator()(const f32x4 (&acc)[2][2][4][2], const pg8::Unit& u, int wr, int wc, int fr, int fq) const {
;     ...
;                 const int row = row0 + ai * 128 + m * 16; float mu, rs; row_stats(stin, row, mu, rs);
;                 float sum = 0.f, sq = 0.f;
; #pragma unroll
;                 for (int bj = 0; bj < 2; ++bj) {
;                     f32x4 z[2];
; #pragma unroll
;                     for (int n = 0; n < 2; ++n) {
;                         const int col = colb + bj * 128 + 4 * n;
;                         f32x4 xv = *(const f32x4*)(zsrc + (size_t)row * DM + col);
;                         if (stin) { const f32x4 gv = *(const f32x4*)(gin + col), bv = *(const f32x4*)(bin + col); xv = (xv - mu) * rs * gv + bv; }
;                         f32x4 zz = ALPHA * xv + acc[ai][bj][m][n];
;                         if (bias) zz += *(const f32x4*)(bias + col);
;                         *(f32x4*)(zdst + (size_t)row * DM + col) = zz;
;                         sum += zz[0] + zz[1] + zz[2] + zz[3]; sq += zz[0] * zz[0] + zz[1] * zz[1] + zz[2] * zz[2] + zz[3] * zz[3];
;                         z[n] = zz;
;                     }
;                     u32x4 o; o.x = pk2(z[0][0], z[0][1]); o.y = pk2(z[0][2], z[0][3]); o.z = pk2(z[1][0], z[1][1]); o.w = pk2(z[1][2], z[1][3]);
;                     if (zb) *(u32x4*)(zb + (size_t)row * DM + colb + bj * 128) = o;
;                 }
;                 sum += __shfl_xor(sum, 16); sq += __shfl_xor(sq, 16);
;                 sum += __shfl_xor(sum, 32); sq += __shfl_xor(sq, 32);
;                 if (fq == 0) { atomicAdd(stout + 2 * (size_t)row, sum); atomicAdd(stout + 2 * (size_t)row + 1, sq); }
.LBB0_1331:
	s_or_b64 exec, exec, s[30:31]
	v_or_b32_e32 v126, 16, v150
	v_ashrrev_i32_e32 v127, 31, v126
	v_lshlrev_b64 v[112:113], 3, v[126:127]
	s_waitcnt lgkmcnt(0)
	v_lshl_add_u64 v[114:115], s[6:7], 0, v[112:113]
	flat_load_dwordx2 v[160:161], v[114:115]
	v_lshlrev_b64 v[114:115], 12, v[126:127]
	v_lshl_add_u64 v[114:115], s[46:47], 0, v[114:115]
	v_lshl_add_u64 v[114:115], v[148:149], 2, v[114:115]
	global_load_dwordx4 v[122:125], v[114:115], off
	global_load_dwordx4 v[156:159], v[144:145], off
	global_load_dwordx4 v[170:173], v[146:147], off
	global_load_dwordx4 v[174:177], v[152:153], off
	global_load_dwordx4 v[178:181], v[114:115], off offset:16
	v_lshlrev_b64 v[126:127], 11, v[126:127]
	v_lshl_add_u64 v[126:127], s[10:11], 0, v[126:127]
	v_lshl_add_u64 v[126:127], v[148:149], 1, v[126:127]
	global_load_dwordx4 v[196:199], v[144:145], off offset:16
	global_load_dwordx4 v[200:203], v[146:147], off offset:16
	global_load_dwordx4 v[204:207], v[154:155], off
	global_load_dwordx4 v[208:211], v[114:115], off offset:512
	global_load_dwordx4 v[212:215], v[114:115], off offset:528
	s_waitcnt vmcnt(0) lgkmcnt(0)
	v_pk_mul_f32 v[160:161], v[160:161], s[18:19] op_sel:[1,0] op_sel_hi:[0,0]
	v_fma_f32 v151, -v161, v161, v160
	v_max_f32_e32 v151, 0, v151
	v_add_f32_e32 v151, 0x3727c5ac, v151
	v_mul_f32_e32 v160, 0x4b800000, v151
	v_cmp_gt_f32_e32 vcc, s64, v151
	v_sub_f32_e32 v125, v125, v161
	v_sub_f32_e32 v124, v124, v161
	v_cndmask_b32_e32 v151, v151, v160, vcc
	v_rsq_f32_e32 v151, v151
	v_sub_f32_e32 v123, v123, v161
	v_sub_f32_e32 v122, v122, v161
	v_mul_f32_e32 v160, 0x45800000, v151
	v_cndmask_b32_e32 v160, v151, v160, vcc
	v_pk_mul_f32 v[122:123], v[122:123], v[160:161] op_sel_hi:[1,0]
	v_pk_mul_f32 v[124:125], v[124:125], v[160:161] op_sel_hi:[1,0]
	v_pk_fma_f32 v[122:123], v[156:157], v[122:123], v[170:171]
	v_pk_fma_f32 v[124:125], v[158:159], v[124:125], v[172:173]
	v_pk_fma_f32 v[108:109], v[122:123], s[20:21], v[108:109] op_sel_hi:[1,0,1]
	v_pk_fma_f32 v[110:111], v[124:125], s[20:21], v[110:111] op_sel_hi:[1,0,1]
	v_pk_add_f32 v[108:109], v[174:175], v[108:109]
	v_pk_add_f32 v[110:111], v[176:177], v[110:111]
	global_store_dwordx4 v[114:115], v[108:111], off
	v_sub_f32_e32 v175, v181, v161
	v_sub_f32_e32 v174, v180, v161
	v_sub_f32_e32 v177, v179, v161
	v_sub_f32_e32 v176, v178, v161
	v_pk_mul_f32 v[176:177], v[176:177], v[160:161] op_sel_hi:[1,0]
	v_pk_mul_f32 v[178:179], v[174:175], v[160:161] op_sel_hi:[1,0]
	v_cvt_pk_bf16_f32 v174, v108, v109
	v_cvt_pk_bf16_f32 v175, v110, v111
	v_add_f32_e32 v151, v108, v109
	v_mul_f32_e32 v109, v109, v109
	v_fmac_f32_e32 v109, v108, v108
	v_add_f32_e32 v151, v110, v151
	v_fmac_f32_e32 v109, v110, v110
	v_add_f32_e32 v108, v111, v151
	v_add_f32_e32 v108, 0, v108
	v_fmac_f32_e32 v109, v111, v111
	v_pk_fma_f32 v[124:125], v[198:199], v[178:179], v[202:203]
	v_pk_fma_f32 v[122:123], v[196:197], v[176:177], v[200:201]
	v_pk_fma_f32 v[106:107], v[124:125], s[20:21], v[106:107] op_sel_hi:[1,0,1]
	v_pk_fma_f32 v[104:105], v[122:123], s[20:21], v[104:105] op_sel_hi:[1,0,1]
	v_pk_add_f32 v[106:107], v[206:207], v[106:107]
	v_pk_add_f32 v[104:105], v[204:205], v[104:105]
	global_store_dwordx4 v[114:115], v[104:107], off offset:16
	v_cvt_pk_bf16_f32 v176, v104, v105
	v_cvt_pk_bf16_f32 v177, v106, v107
	flat_store_dwordx4 v[126:127], v[174:177]
	global_load_dwordx4 v[156:159], v[144:145], off offset:512
	global_load_dwordx4 v[170:173], v[146:147], off offset:512
	s_nop 0
	global_load_dwordx4 v[174:177], v[120:121], off
	v_add_f32_e32 v110, v104, v105
	v_mul_f32_e32 v105, v105, v105
	v_fmac_f32_e32 v105, v104, v104
	v_add_f32_e32 v110, v106, v110
	v_fmac_f32_e32 v105, v106, v106
	v_add_f32_e32 v104, v107, v110
	v_fmac_f32_e32 v105, v107, v107
	v_add_f32_e32 v108, v104, v108
	v_add_f32_e32 v109, v109, v105
	global_load_dwordx4 v[196:199], v[144:145], off offset:528
	global_load_dwordx4 v[200:203], v[146:147], off offset:528
	global_load_dwordx4 v[204:207], v[116:117], off
	s_waitcnt vmcnt(0)
	v_sub_f32_e32 v125, v211, v161
	v_sub_f32_e32 v124, v210, v161
	v_sub_f32_e32 v123, v209, v161
	v_sub_f32_e32 v122, v208, v161
	v_pk_mul_f32 v[122:123], v[160:161], v[122:123] op_sel_hi:[0,1]
	v_pk_mul_f32 v[124:125], v[160:161], v[124:125] op_sel_hi:[0,1]
	v_pk_fma_f32 v[124:125], v[158:159], v[124:125], v[172:173]
	v_pk_fma_f32 v[122:123], v[156:157], v[122:123], v[170:171]
	v_pk_fma_f32 v[102:103], v[124:125], s[20:21], v[102:103] op_sel_hi:[1,0,1]
	v_pk_fma_f32 v[100:101], v[122:123], s[20:21], v[100:101] op_sel_hi:[1,0,1]
	v_pk_add_f32 v[102:103], v[176:177], v[102:103]
	v_pk_add_f32 v[100:101], v[174:175], v[100:101]
	global_store_dwordx4 v[114:115], v[100:103], off offset:512
	v_sub_f32_e32 v107, v213, v161
	v_sub_f32_e32 v106, v212, v161
	v_sub_f32_e32 v105, v215, v161
	v_sub_f32_e32 v104, v214, v161
	v_pk_mul_f32 v[106:107], v[160:161], v[106:107] op_sel_hi:[0,1]
	v_pk_mul_f32 v[104:105], v[160:161], v[104:105] op_sel_hi:[0,1]
	v_mul_f32_e32 v111, v101, v101
	v_add_f32_e32 v110, v100, v101
	v_fmac_f32_e32 v111, v100, v100
	v_add_f32_e32 v110, v102, v110
	v_fmac_f32_e32 v111, v102, v102
	v_add_f32_e32 v110, v103, v110
	v_fmac_f32_e32 v111, v103, v103
	v_add_f32_e32 v108, v108, v110
	v_add_f32_e32 v109, v109, v111
	v_cvt_pk_bf16_f32 v100, v100, v101
	v_cvt_pk_bf16_f32 v101, v102, v103
	v_pk_fma_f32 v[106:107], v[196:197], v[106:107], v[200:201]
	v_pk_fma_f32 v[104:105], v[198:199], v[104:105], v[202:203]
	v_pk_fma_f32 v[96:97], v[106:107], s[20:21], v[96:97] op_sel_hi:[1,0,1]
	v_pk_fma_f32 v[98:99], v[104:105], s[20:21], v[98:99] op_sel_hi:[1,0,1]
	v_pk_add_f32 v[104:105], v[204:205], v[96:97]
	v_pk_add_f32 v[106:107], v[206:207], v[98:99]
	v_mul_f32_e32 v97, v105, v105
	v_add_f32_e32 v96, v104, v105
	v_fmac_f32_e32 v97, v104, v104
	v_add_f32_e32 v96, v106, v96
	v_fmac_f32_e32 v97, v106, v106
	v_add_f32_e32 v96, v107, v96
	v_fmac_f32_e32 v97, v107, v107
	v_add_f32_e32 v96, v108, v96
	v_add_f32_e32 v97, v109, v97
	ds_bpermute_b32 v98, v118, v96
	ds_bpermute_b32 v99, v118, v97
	global_store_dwordx4 v[114:115], v[104:107], off offset:528
	v_cvt_pk_bf16_f32 v102, v104, v105
	v_cvt_pk_bf16_f32 v103, v106, v107
	s_waitcnt lgkmcnt(0)
	v_add_f32_e32 v96, v96, v98
	v_add_f32_e32 v97, v97, v99
	ds_bpermute_b32 v98, v119, v96
	ds_bpermute_b32 v99, v119, v97
	flat_store_dwordx4 v[126:127], v[100:103] offset:256
	s_and_saveexec_b64 s[30:31], s[2:3]
	s_cbranch_execz .LBB0_1333
	v_lshl_add_u64 v[100:101], s[8:9], 0, v[112:113]
	s_waitcnt lgkmcnt(0)
	v_add_f32_e32 v96, v96, v98
	v_add_f32_e32 v97, v97, v99
	flat_atomic_add_f32 v[100:101], v96
	flat_atomic_add_f32 v[100:101], v97 offset:4
; DEVI unsigned pk2(float lo, float hi) { unsigned r; asm("v_cvt_pk_bf16_f32 %0, %1, %2" : "=v"(r) : "v"(lo), "v"(hi)); return r; }
; DEVI void row_stats(const float* stats, int row, float& mu, float& rs) {
;     if (stats) { const float2 st = *(const float2*)(stats + 2 * (size_t)row); mu = st.x * (1.0f / 1024.0f); const float var = st.y * (1.0f / 1024.0f) - mu * mu; rs = rsqrtf(fmaxf(var, 0.f) + LN_EPS); }
;     DEVI void operator()(const f32x4 (&acc)[2][2][4][2], const pg8::Unit& u, int wr, int wc, int fr, int fq) const {
;     ...
;                 const int row = row0 + ai * 128 + m * 16; float mu, rs; row_stats(stin, row, mu, rs);
;                 float sum = 0.f, sq = 0.f;
; #pragma unroll
;                 for (int bj = 0; bj < 2; ++bj) {
;                     f32x4 z[2];
; #pragma unroll
;                     for (int n = 0; n < 2; ++n) {
;                         const int col = colb + bj * 128 + 4 * n;
;                         f32x4 xv = *(const f32x4*)(zsrc + (size_t)row * DM + col);
;                         if (stin) { const f32x4 gv = *(const f32x4*)(gin + col), bv = *(const f32x4*)(bin + col); xv = (xv - mu) * rs * gv + bv; }
;                         f32x4 zz = ALPHA * xv + acc[ai][bj][m][n];
;                         if (bias) zz += *(const f32x4*)(bias + col);
;                         *(f32x4*)(zdst + (size_t)row * DM + col) = zz;
;                         sum += zz[0] + zz[1] + zz[2] + zz[3]; sq += zz[0] * zz[0] + zz[1] * zz[1] + zz[2] * zz[2] + zz[3] * zz[3];
;                         z[n] = zz;
;                     }
;                     u32x4 o; o.x = pk2(z[0][0], z[0][1]); o.y = pk2(z[0][2], z[0][3]); o.z = pk2(z[1][0], z[1][1]); o.w = pk2(z[1][2], z[1][3]);
;                     if (zb) *(u32x4*)(zb + (size_t)row * DM + colb + bj * 128) = o;
;                 }
;                 sum += __shfl_xor(sum, 16); sq += __shfl_xor(sq, 16);
;                 sum += __shfl_xor(sum, 32); sq += __shfl_xor(sq, 32);
;                 if (fq == 0) { atomicAdd(stout + 2 * (size_t)row, sum); atomicAdd(stout + 2 * (size_t)row + 1, sq); }
.LBB0_1333:
	s_or_b64 exec, exec, s[30:31]
	v_or_b32_e32 v126, 32, v150
	v_ashrrev_i32_e32 v127, 31, v126
	v_lshlrev_b64 v[96:97], 3, v[126:127]
	s_waitcnt lgkmcnt(0)
	v_lshl_add_u64 v[98:99], s[6:7], 0, v[96:97]
	flat_load_dwordx2 v[156:157], v[98:99]
	v_lshlrev_b64 v[98:99], 12, v[126:127]
	v_lshl_add_u64 v[98:99], s[46:47], 0, v[98:99]
	v_lshl_add_u64 v[98:99], v[148:149], 2, v[98:99]
	global_load_dwordx4 v[100:103], v[98:99], off
	global_load_dwordx4 v[104:107], v[144:145], off
	global_load_dwordx4 v[108:111], v[146:147], off
	global_load_dwordx4 v[112:115], v[152:153], off
	global_load_dwordx4 v[122:125], v[98:99], off offset:16
	global_load_dwordx4 v[196:199], v[144:145], off offset:16
	global_load_dwordx4 v[200:203], v[146:147], off offset:16
	global_load_dwordx4 v[204:207], v[154:155], off
	global_load_dwordx4 v[208:211], v[98:99], off offset:512
	global_load_dwordx4 v[212:215], v[98:99], off offset:528
	s_waitcnt vmcnt(0) lgkmcnt(0)
	v_pk_mul_f32 v[156:157], v[156:157], s[18:19] op_sel:[1,0] op_sel_hi:[0,0]
	v_fma_f32 v151, -v157, v157, v156
	v_max_f32_e32 v151, 0, v151
	v_add_f32_e32 v151, 0x3727c5ac, v151
	v_mul_f32_e32 v156, 0x4b800000, v151
	v_cmp_gt_f32_e32 vcc, s64, v151
	v_sub_f32_e32 v103, v103, v157
	v_sub_f32_e32 v102, v102, v157
	v_cndmask_b32_e32 v151, v151, v156, vcc
	v_rsq_f32_e32 v151, v151
	v_sub_f32_e32 v101, v101, v157
	v_sub_f32_e32 v100, v100, v157
	v_mul_f32_e32 v156, 0x45800000, v151
	v_cndmask_b32_e32 v156, v151, v156, vcc
	v_pk_mul_f32 v[100:101], v[100:101], v[156:157] op_sel_hi:[1,0]
	v_pk_mul_f32 v[102:103], v[102:103], v[156:157] op_sel_hi:[1,0]
	v_pk_fma_f32 v[100:101], v[104:105], v[100:101], v[108:109]
	v_pk_fma_f32 v[102:103], v[106:107], v[102:103], v[110:111]
	v_pk_fma_f32 v[92:93], v[100:101], s[20:21], v[92:93] op_sel_hi:[1,0,1]
	v_pk_fma_f32 v[94:95], v[102:103], s[20:21], v[94:95] op_sel_hi:[1,0,1]
	v_pk_add_f32 v[92:93], v[112:113], v[92:93]
	v_pk_add_f32 v[94:95], v[114:115], v[94:95]
	global_store_dwordx4 v[98:99], v[92:95], off
	v_lshlrev_b64 v[112:113], 11, v[126:127]
	v_lshl_add_u64 v[112:113], s[10:11], 0, v[112:113]
	v_lshl_add_u64 v[126:127], v[148:149], 1, v[112:113]
	v_sub_f32_e32 v113, v125, v157
	v_sub_f32_e32 v112, v124, v157
	v_sub_f32_e32 v115, v123, v157
	v_sub_f32_e32 v114, v122, v157
	v_pk_mul_f32 v[114:115], v[114:115], v[156:157] op_sel_hi:[1,0]
	v_pk_mul_f32 v[122:123], v[112:113], v[156:157] op_sel_hi:[1,0]
	v_cvt_pk_bf16_f32 v112, v92, v93
	v_cvt_pk_bf16_f32 v113, v94, v95
	v_pk_fma_f32 v[100:101], v[196:197], v[114:115], v[200:201]
	v_pk_fma_f32 v[102:103], v[198:199], v[122:123], v[202:203]
	v_pk_fma_f32 v[88:89], v[100:101], s[20:21], v[88:89] op_sel_hi:[1,0,1]
	v_pk_fma_f32 v[90:91], v[102:103], s[20:21], v[90:91] op_sel_hi:[1,0,1]
	v_pk_add_f32 v[88:89], v[204:205], v[88:89]
	v_pk_add_f32 v[90:91], v[206:207], v[90:91]
	global_store_dwordx4 v[98:99], v[88:91], off offset:16
	v_cvt_pk_bf16_f32 v114, v88, v89
	v_cvt_pk_bf16_f32 v115, v90, v91
	flat_store_dwordx4 v[126:127], v[112:115]
	global_load_dwordx4 v[104:107], v[144:145], off offset:512
	global_load_dwordx4 v[108:111], v[146:147], off offset:512
	s_nop 0
	global_load_dwordx4 v[112:115], v[120:121], off
	global_load_dwordx4 v[196:199], v[144:145], off offset:528
	global_load_dwordx4 v[200:203], v[146:147], off offset:528
	global_load_dwordx4 v[204:207], v[116:117], off
	s_waitcnt vmcnt(0)
	v_sub_f32_e32 v103, v211, v157
	v_sub_f32_e32 v102, v210, v157
	v_sub_f32_e32 v101, v209, v157
	v_sub_f32_e32 v100, v208, v157
	v_pk_mul_f32 v[100:101], v[156:157], v[100:101] op_sel_hi:[0,1]
	v_pk_mul_f32 v[102:103], v[156:157], v[102:103] op_sel_hi:[0,1]
	v_pk_fma_f32 v[102:103], v[106:107], v[102:103], v[110:111]
	v_pk_fma_f32 v[100:101], v[104:105], v[100:101], v[108:109]
	v_pk_fma_f32 v[86:87], v[102:103], s[20:21], v[86:87] op_sel_hi:[1,0,1]
	v_pk_fma_f32 v[84:85], v[100:101], s[20:21], v[84:85] op_sel_hi:[1,0,1]
	v_pk_add_f32 v[86:87], v[114:115], v[86:87]
	v_pk_add_f32 v[84:85], v[112:113], v[84:85]
	global_store_dwordx4 v[98:99], v[84:87], off offset:512
	v_add_f32_e32 v112, v92, v93
	v_mul_f32_e32 v93, v93, v93
	v_fmac_f32_e32 v93, v92, v92
	v_add_f32_e32 v112, v94, v112
	v_fmac_f32_e32 v93, v94, v94
	v_add_f32_e32 v94, v88, v89
	v_mul_f32_e32 v89, v89, v89
	v_fmac_f32_e32 v89, v88, v88
	v_add_f32_e32 v92, v95, v112
	v_add_f32_e32 v94, v90, v94
	v_fmac_f32_e32 v89, v90, v90
	v_add_f32_e32 v92, 0, v92
	v_fmac_f32_e32 v93, v95, v95
	v_add_f32_e32 v88, v91, v94
	v_fmac_f32_e32 v89, v91, v91
	v_sub_f32_e32 v91, v213, v157
	v_sub_f32_e32 v90, v212, v157
	v_add_f32_e32 v92, v88, v92
	v_add_f32_e32 v93, v93, v89
	v_sub_f32_e32 v89, v215, v157
	v_sub_f32_e32 v88, v214, v157
	v_pk_mul_f32 v[90:91], v[156:157], v[90:91] op_sel_hi:[0,1]
	v_pk_mul_f32 v[88:89], v[156:157], v[88:89] op_sel_hi:[0,1]
	v_mul_f32_e32 v95, v85, v85
	v_add_f32_e32 v94, v84, v85
	v_fmac_f32_e32 v95, v84, v84
	v_add_f32_e32 v94, v86, v94
	v_fmac_f32_e32 v95, v86, v86
	v_add_f32_e32 v94, v87, v94
	v_fmac_f32_e32 v95, v87, v87
	v_add_f32_e32 v92, v92, v94
	v_add_f32_e32 v93, v93, v95
	v_cvt_pk_bf16_f32 v84, v84, v85
	v_cvt_pk_bf16_f32 v85, v86, v87
	v_pk_fma_f32 v[90:91], v[196:197], v[90:91], v[200:201]
	v_pk_fma_f32 v[88:89], v[198:199], v[88:89], v[202:203]
	v_pk_fma_f32 v[80:81], v[90:91], s[20:21], v[80:81] op_sel_hi:[1,0,1]
	v_pk_fma_f32 v[82:83], v[88:89], s[20:21], v[82:83] op_sel_hi:[1,0,1]
	v_pk_add_f32 v[88:89], v[204:205], v[80:81]
	v_pk_add_f32 v[90:91], v[206:207], v[82:83]
	v_mul_f32_e32 v81, v89, v89
	v_add_f32_e32 v80, v88, v89
	v_fmac_f32_e32 v81, v88, v88
	v_add_f32_e32 v80, v90, v80
	v_fmac_f32_e32 v81, v90, v90
	v_add_f32_e32 v80, v91, v80
	v_fmac_f32_e32 v81, v91, v91
	v_add_f32_e32 v80, v92, v80
	v_add_f32_e32 v81, v93, v81
	ds_bpermute_b32 v82, v118, v80
	ds_bpermute_b32 v83, v118, v81
	global_store_dwordx4 v[98:99], v[88:91], off offset:528
	v_cvt_pk_bf16_f32 v86, v88, v89
	v_cvt_pk_bf16_f32 v87, v90, v91
	s_waitcnt lgkmcnt(0)
	v_add_f32_e32 v80, v80, v82
	v_add_f32_e32 v81, v81, v83
	ds_bpermute_b32 v82, v119, v80
	ds_bpermute_b32 v83, v119, v81
	flat_store_dwordx4 v[126:127], v[84:87] offset:256
	s_and_saveexec_b64 s[30:31], s[2:3]
	s_cbranch_execz .LBB0_1335
	v_lshl_add_u64 v[84:85], s[8:9], 0, v[96:97]
	s_waitcnt lgkmcnt(0)
	v_add_f32_e32 v80, v80, v82
	v_add_f32_e32 v81, v81, v83
	flat_atomic_add_f32 v[84:85], v80
	flat_atomic_add_f32 v[84:85], v81 offset:4
; DEVI unsigned pk2(float lo, float hi) { unsigned r; asm("v_cvt_pk_bf16_f32 %0, %1, %2" : "=v"(r) : "v"(lo), "v"(hi)); return r; }
; DEVI void row_stats(const float* stats, int row, float& mu, float& rs) {
;     if (stats) { const float2 st = *(const float2*)(stats + 2 * (size_t)row); mu = st.x * (1.0f / 1024.0f); const float var = st.y * (1.0f / 1024.0f) - mu * mu; rs = rsqrtf(fmaxf(var, 0.f) + LN_EPS); }
;     DEVI void operator()(const f32x4 (&acc)[2][2][4][2], const pg8::Unit& u, int wr, int wc, int fr, int fq) const {
;     ...
;                 const int row = row0 + ai * 128 + m * 16; float mu, rs; row_stats(stin, row, mu, rs);
;                 float sum = 0.f, sq = 0.f;
; #pragma unroll
;                 for (int bj = 0; bj < 2; ++bj) {
;                     f32x4 z[2];
; #pragma unroll
;                     for (int n = 0; n < 2; ++n) {
;                         const int col = colb + bj * 128 + 4 * n;
;                         f32x4 xv = *(const f32x4*)(zsrc + (size_t)row * DM + col);
;                         if (stin) { const f32x4 gv = *(const f32x4*)(gin + col), bv = *(const f32x4*)(bin + col); xv = (xv - mu) * rs * gv + bv; }
;                         f32x4 zz = ALPHA * xv + acc[ai][bj][m][n];
;                         if (bias) zz += *(const f32x4*)(bias + col);
;                         *(f32x4*)(zdst + (size_t)row * DM + col) = zz;
;                         sum += zz[0] + zz[1] + zz[2] + zz[3]; sq += zz[0] * zz[0] + zz[1] * zz[1] + zz[2] * zz[2] + zz[3] * zz[3];
;                         z[n] = zz;
;                     }
;                     u32x4 o; o.x = pk2(z[0][0], z[0][1]); o.y = pk2(z[0][2], z[0][3]); o.z = pk2(z[1][0], z[1][1]); o.w = pk2(z[1][2], z[1][3]);
;                     if (zb) *(u32x4*)(zb + (size_t)row * DM + colb + bj * 128) = o;
;                 }
;                 sum += __shfl_xor(sum, 16); sq += __shfl_xor(sq, 16);
;                 sum += __shfl_xor(sum, 32); sq += __shfl_xor(sq, 32);
;                 if (fq == 0) { atomicAdd(stout + 2 * (size_t)row, sum); atomicAdd(stout + 2 * (size_t)row + 1, sq); }
.LBB0_1335:
	s_or_b64 exec, exec, s[30:31]
	v_or_b32_e32 v104, 48, v150
	v_ashrrev_i32_e32 v105, 31, v104
	v_lshlrev_b64 v[80:81], 3, v[104:105]
	s_waitcnt lgkmcnt(0)
	v_lshl_add_u64 v[82:83], s[6:7], 0, v[80:81]
	flat_load_dwordx2 v[106:107], v[82:83]
	v_lshlrev_b64 v[82:83], 12, v[104:105]
	v_lshl_add_u64 v[82:83], s[46:47], 0, v[82:83]
	v_lshl_add_u64 v[82:83], v[148:149], 2, v[82:83]
	global_load_dwordx4 v[84:87], v[82:83], off
	global_load_dwordx4 v[88:91], v[144:145], off
	global_load_dwordx4 v[92:95], v[146:147], off
	global_load_dwordx4 v[96:99], v[152:153], off
	global_load_dwordx4 v[100:103], v[82:83], off offset:16
	global_load_dwordx4 v[196:199], v[144:145], off offset:16
	global_load_dwordx4 v[200:203], v[146:147], off offset:16
	global_load_dwordx4 v[204:207], v[154:155], off
	global_load_dwordx4 v[208:211], v[82:83], off offset:512
	global_load_dwordx4 v[212:215], v[82:83], off offset:528
	s_waitcnt vmcnt(0) lgkmcnt(0)
	v_pk_mul_f32 v[106:107], v[106:107], s[18:19] op_sel:[1,0] op_sel_hi:[0,0]
	v_fma_f32 v106, -v107, v107, v106
	v_max_f32_e32 v106, 0, v106
	v_add_f32_e32 v106, 0x3727c5ac, v106
	v_mul_f32_e32 v108, 0x4b800000, v106
	v_cmp_gt_f32_e32 vcc, s64, v106
	v_sub_f32_e32 v87, v87, v107
	v_sub_f32_e32 v86, v86, v107
	v_cndmask_b32_e32 v106, v106, v108, vcc
	v_rsq_f32_e32 v106, v106
	v_sub_f32_e32 v85, v85, v107
	v_sub_f32_e32 v84, v84, v107
	v_mul_f32_e32 v108, 0x45800000, v106
	v_cndmask_b32_e32 v106, v106, v108, vcc
	v_pk_mul_f32 v[84:85], v[84:85], v[106:107] op_sel_hi:[1,0]
	v_pk_mul_f32 v[86:87], v[86:87], v[106:107] op_sel_hi:[1,0]
	v_pk_fma_f32 v[84:85], v[88:89], v[84:85], v[92:93]
	v_pk_fma_f32 v[86:87], v[90:91], v[86:87], v[94:95]
	v_pk_fma_f32 v[76:77], v[84:85], s[20:21], v[76:77] op_sel_hi:[1,0,1]
	v_pk_fma_f32 v[78:79], v[86:87], s[20:21], v[78:79] op_sel_hi:[1,0,1]
	v_pk_add_f32 v[76:77], v[96:97], v[76:77]
	v_pk_add_f32 v[78:79], v[98:99], v[78:79]
	global_store_dwordx4 v[82:83], v[76:79], off
	v_lshlrev_b64 v[96:97], 11, v[104:105]
	v_lshl_add_u64 v[96:97], s[10:11], 0, v[96:97]
	v_lshl_add_u64 v[104:105], v[148:149], 1, v[96:97]
	v_sub_f32_e32 v97, v103, v107
	v_sub_f32_e32 v96, v102, v107
	v_sub_f32_e32 v99, v101, v107
	v_sub_f32_e32 v98, v100, v107
	v_pk_mul_f32 v[98:99], v[98:99], v[106:107] op_sel_hi:[1,0]
	v_pk_mul_f32 v[100:101], v[96:97], v[106:107] op_sel_hi:[1,0]
	v_cvt_pk_bf16_f32 v96, v76, v77
	v_cvt_pk_bf16_f32 v97, v78, v79
	v_pk_fma_f32 v[84:85], v[196:197], v[98:99], v[200:201]
	v_pk_fma_f32 v[86:87], v[198:199], v[100:101], v[202:203]
	v_pk_fma_f32 v[72:73], v[84:85], s[20:21], v[72:73] op_sel_hi:[1,0,1]
	v_pk_fma_f32 v[74:75], v[86:87], s[20:21], v[74:75] op_sel_hi:[1,0,1]
	v_pk_add_f32 v[72:73], v[204:205], v[72:73]
	v_pk_add_f32 v[74:75], v[206:207], v[74:75]
	global_store_dwordx4 v[82:83], v[72:75], off offset:16
	v_cvt_pk_bf16_f32 v98, v72, v73
	v_cvt_pk_bf16_f32 v99, v74, v75
	flat_store_dwordx4 v[104:105], v[96:99]
	global_load_dwordx4 v[88:91], v[144:145], off offset:512
	global_load_dwordx4 v[92:95], v[146:147], off offset:512
	s_nop 0
	global_load_dwordx4 v[96:99], v[120:121], off
	global_load_dwordx4 v[196:199], v[144:145], off offset:528
	global_load_dwordx4 v[200:203], v[146:147], off offset:528
	global_load_dwordx4 v[204:207], v[116:117], off
	s_waitcnt vmcnt(0)
	v_sub_f32_e32 v87, v211, v107
	v_sub_f32_e32 v86, v210, v107
	v_sub_f32_e32 v85, v209, v107
	v_sub_f32_e32 v84, v208, v107
	v_pk_mul_f32 v[84:85], v[106:107], v[84:85] op_sel_hi:[0,1]
	v_pk_mul_f32 v[86:87], v[106:107], v[86:87] op_sel_hi:[0,1]
	v_pk_fma_f32 v[86:87], v[90:91], v[86:87], v[94:95]
	v_pk_fma_f32 v[84:85], v[88:89], v[84:85], v[92:93]
	v_pk_fma_f32 v[70:71], v[86:87], s[20:21], v[70:71] op_sel_hi:[1,0,1]
	v_pk_fma_f32 v[68:69], v[84:85], s[20:21], v[68:69] op_sel_hi:[1,0,1]
	v_pk_add_f32 v[70:71], v[98:99], v[70:71]
	v_pk_add_f32 v[68:69], v[96:97], v[68:69]
	global_store_dwordx4 v[82:83], v[68:71], off offset:512
	v_add_f32_e32 v96, v76, v77
	v_mul_f32_e32 v77, v77, v77
	v_fmac_f32_e32 v77, v76, v76
	v_add_f32_e32 v96, v78, v96
	v_fmac_f32_e32 v77, v78, v78
	v_add_f32_e32 v78, v72, v73
	v_mul_f32_e32 v73, v73, v73
	v_fmac_f32_e32 v73, v72, v72
	v_add_f32_e32 v76, v79, v96
	v_add_f32_e32 v78, v74, v78
	v_fmac_f32_e32 v73, v74, v74
	v_add_f32_e32 v76, 0, v76
	v_fmac_f32_e32 v77, v79, v79
	v_add_f32_e32 v72, v75, v78
	v_fmac_f32_e32 v73, v75, v75
	v_sub_f32_e32 v75, v213, v107
	v_sub_f32_e32 v74, v212, v107
	v_add_f32_e32 v76, v72, v76
	v_add_f32_e32 v77, v77, v73
	v_sub_f32_e32 v73, v215, v107
	v_sub_f32_e32 v72, v214, v107
	v_pk_mul_f32 v[74:75], v[106:107], v[74:75] op_sel_hi:[0,1]
	v_pk_mul_f32 v[72:73], v[106:107], v[72:73] op_sel_hi:[0,1]
	v_mul_f32_e32 v79, v69, v69
	v_add_f32_e32 v78, v68, v69
	v_fmac_f32_e32 v79, v68, v68
	v_add_f32_e32 v78, v70, v78
	v_fmac_f32_e32 v79, v70, v70
	v_add_f32_e32 v78, v71, v78
	v_fmac_f32_e32 v79, v71, v71
	v_add_f32_e32 v76, v76, v78
	v_add_f32_e32 v77, v77, v79
	v_cvt_pk_bf16_f32 v68, v68, v69
	v_cvt_pk_bf16_f32 v69, v70, v71
	v_pk_fma_f32 v[74:75], v[196:197], v[74:75], v[200:201]
	v_pk_fma_f32 v[72:73], v[198:199], v[72:73], v[202:203]
	v_pk_fma_f32 v[64:65], v[74:75], s[20:21], v[64:65] op_sel_hi:[1,0,1]
	v_pk_fma_f32 v[66:67], v[72:73], s[20:21], v[66:67] op_sel_hi:[1,0,1]
	v_pk_add_f32 v[72:73], v[204:205], v[64:65]
	v_pk_add_f32 v[74:75], v[206:207], v[66:67]
	v_mul_f32_e32 v65, v73, v73
	v_add_f32_e32 v64, v72, v73
	v_fmac_f32_e32 v65, v72, v72
	v_add_f32_e32 v64, v74, v64
	v_fmac_f32_e32 v65, v74, v74
	v_add_f32_e32 v64, v75, v64
	v_fmac_f32_e32 v65, v75, v75
	v_add_f32_e32 v64, v76, v64
	v_add_f32_e32 v65, v77, v65
	ds_bpermute_b32 v66, v118, v64
	ds_bpermute_b32 v67, v118, v65
	global_store_dwordx4 v[82:83], v[72:75], off offset:528
	v_cvt_pk_bf16_f32 v70, v72, v73
	v_cvt_pk_bf16_f32 v71, v74, v75
	s_waitcnt lgkmcnt(0)
	v_add_f32_e32 v64, v64, v66
	v_add_f32_e32 v65, v65, v67
	ds_bpermute_b32 v66, v119, v64
	ds_bpermute_b32 v67, v119, v65
	flat_store_dwordx4 v[104:105], v[68:71] offset:256
	s_and_saveexec_b64 s[30:31], s[2:3]
	s_cbranch_execz .LBB0_1337
	v_lshl_add_u64 v[68:69], s[8:9], 0, v[80:81]
	s_waitcnt lgkmcnt(0)
	v_add_f32_e32 v64, v64, v66
	v_add_f32_e32 v65, v65, v67
	flat_atomic_add_f32 v[68:69], v64
	flat_atomic_add_f32 v[68:69], v65 offset:4
; DEVI unsigned pk2(float lo, float hi) { unsigned r; asm("v_cvt_pk_bf16_f32 %0, %1, %2" : "=v"(r) : "v"(lo), "v"(hi)); return r; }
; DEVI void row_stats(const float* stats, int row, float& mu, float& rs) {
;     if (stats) { const float2 st = *(const float2*)(stats + 2 * (size_t)row); mu = st.x * (1.0f / 1024.0f); const float var = st.y * (1.0f / 1024.0f) - mu * mu; rs = rsqrtf(fmaxf(var, 0.f) + LN_EPS); }
;     DEVI void operator()(const f32x4 (&acc)[2][2][4][2], const pg8::Unit& u, int wr, int wc, int fr, int fq) const {
;     ...
;                 const int row = row0 + ai * 128 + m * 16; float mu, rs; row_stats(stin, row, mu, rs);
;                 float sum = 0.f, sq = 0.f;
; #pragma unroll
;                 for (int bj = 0; bj < 2; ++bj) {
;                     f32x4 z[2];
; #pragma unroll
;                     for (int n = 0; n < 2; ++n) {
;                         const int col = colb + bj * 128 + 4 * n;
;                         f32x4 xv = *(const f32x4*)(zsrc + (size_t)row * DM + col);
;                         if (stin) { const f32x4 gv = *(const f32x4*)(gin + col), bv = *(const f32x4*)(bin + col); xv = (xv - mu) * rs * gv + bv; }
;                         f32x4 zz = ALPHA * xv + acc[ai][bj][m][n];
;                         if (bias) zz += *(const f32x4*)(bias + col);
;                         *(f32x4*)(zdst + (size_t)row * DM + col) = zz;
;                         sum += zz[0] + zz[1] + zz[2] + zz[3]; sq += zz[0] * zz[0] + zz[1] * zz[1] + zz[2] * zz[2] + zz[3] * zz[3];
;                         z[n] = zz;
;                     }
;                     u32x4 o; o.x = pk2(z[0][0], z[0][1]); o.y = pk2(z[0][2], z[0][3]); o.z = pk2(z[1][0], z[1][1]); o.w = pk2(z[1][2], z[1][3]);
;                     if (zb) *(u32x4*)(zb + (size_t)row * DM + colb + bj * 128) = o;
;                 }
;                 sum += __shfl_xor(sum, 16); sq += __shfl_xor(sq, 16);
;                 sum += __shfl_xor(sum, 32); sq += __shfl_xor(sq, 32);
;                 if (fq == 0) { atomicAdd(stout + 2 * (size_t)row, sum); atomicAdd(stout + 2 * (size_t)row + 1, sq); }
.LBB0_1337:
	s_or_b64 exec, exec, s[30:31]
	v_add_u32_e32 v88, 0x80, v150
	v_ashrrev_i32_e32 v89, 31, v88
	v_lshlrev_b64 v[64:65], 3, v[88:89]
	s_waitcnt lgkmcnt(0)
	v_lshl_add_u64 v[66:67], s[6:7], 0, v[64:65]
	flat_load_dwordx2 v[90:91], v[66:67]
	v_lshlrev_b64 v[66:67], 12, v[88:89]
	v_lshl_add_u64 v[66:67], s[46:47], 0, v[66:67]
	v_lshl_add_u64 v[66:67], v[148:149], 2, v[66:67]
	global_load_dwordx4 v[68:71], v[66:67], off
	global_load_dwordx4 v[72:75], v[144:145], off
	global_load_dwordx4 v[76:79], v[146:147], off
	global_load_dwordx4 v[80:83], v[152:153], off
	global_load_dwordx4 v[84:87], v[66:67], off offset:16
	global_load_dwordx4 v[196:199], v[144:145], off offset:16
	global_load_dwordx4 v[200:203], v[146:147], off offset:16
	global_load_dwordx4 v[204:207], v[154:155], off
	global_load_dwordx4 v[208:211], v[66:67], off offset:512
	global_load_dwordx4 v[212:215], v[66:67], off offset:528
	s_waitcnt vmcnt(0) lgkmcnt(0)
	v_pk_mul_f32 v[90:91], v[90:91], s[18:19] op_sel:[1,0] op_sel_hi:[0,0]
	v_fma_f32 v90, -v91, v91, v90
	v_max_f32_e32 v90, 0, v90
	v_add_f32_e32 v90, 0x3727c5ac, v90
	v_mul_f32_e32 v92, 0x4b800000, v90
	v_cmp_gt_f32_e32 vcc, s64, v90
	v_sub_f32_e32 v71, v71, v91
	v_sub_f32_e32 v70, v70, v91
	v_cndmask_b32_e32 v90, v90, v92, vcc
	v_rsq_f32_e32 v90, v90
	v_sub_f32_e32 v69, v69, v91
	v_sub_f32_e32 v68, v68, v91
	v_mul_f32_e32 v92, 0x45800000, v90
	v_cndmask_b32_e32 v90, v90, v92, vcc
	v_pk_mul_f32 v[68:69], v[68:69], v[90:91] op_sel_hi:[1,0]
	v_pk_mul_f32 v[70:71], v[70:71], v[90:91] op_sel_hi:[1,0]
	v_pk_fma_f32 v[68:69], v[72:73], v[68:69], v[76:77]
	v_pk_fma_f32 v[70:71], v[74:75], v[70:71], v[78:79]
	v_pk_fma_f32 v[60:61], v[68:69], s[20:21], v[60:61] op_sel_hi:[1,0,1]
	v_pk_fma_f32 v[62:63], v[70:71], s[20:21], v[62:63] op_sel_hi:[1,0,1]
	v_pk_add_f32 v[60:61], v[80:81], v[60:61]
	v_pk_add_f32 v[62:63], v[82:83], v[62:63]
	global_store_dwordx4 v[66:67], v[60:63], off
	v_lshlrev_b64 v[80:81], 11, v[88:89]
	v_lshl_add_u64 v[80:81], s[10:11], 0, v[80:81]
	v_lshl_add_u64 v[88:89], v[148:149], 1, v[80:81]
	v_sub_f32_e32 v81, v87, v91
	v_sub_f32_e32 v80, v86, v91
	v_sub_f32_e32 v83, v85, v91
	v_sub_f32_e32 v82, v84, v91
	v_pk_mul_f32 v[82:83], v[82:83], v[90:91] op_sel_hi:[1,0]
	v_pk_mul_f32 v[84:85], v[80:81], v[90:91] op_sel_hi:[1,0]
	v_cvt_pk_bf16_f32 v80, v60, v61
	v_cvt_pk_bf16_f32 v81, v62, v63
	v_pk_fma_f32 v[68:69], v[196:197], v[82:83], v[200:201]
	v_pk_fma_f32 v[70:71], v[198:199], v[84:85], v[202:203]
	v_pk_fma_f32 v[56:57], v[68:69], s[20:21], v[56:57] op_sel_hi:[1,0,1]
	v_pk_fma_f32 v[58:59], v[70:71], s[20:21], v[58:59] op_sel_hi:[1,0,1]
	v_pk_add_f32 v[56:57], v[204:205], v[56:57]
	v_pk_add_f32 v[58:59], v[206:207], v[58:59]
	global_store_dwordx4 v[66:67], v[56:59], off offset:16
	v_cvt_pk_bf16_f32 v82, v56, v57
	v_cvt_pk_bf16_f32 v83, v58, v59
	flat_store_dwordx4 v[88:89], v[80:83]
	global_load_dwordx4 v[72:75], v[144:145], off offset:512
	global_load_dwordx4 v[76:79], v[146:147], off offset:512
	s_nop 0
	global_load_dwordx4 v[80:83], v[120:121], off
	global_load_dwordx4 v[196:199], v[144:145], off offset:528
	global_load_dwordx4 v[200:203], v[146:147], off offset:528
	global_load_dwordx4 v[204:207], v[116:117], off
	s_waitcnt vmcnt(0)
	v_sub_f32_e32 v71, v211, v91
	v_sub_f32_e32 v70, v210, v91
	v_sub_f32_e32 v69, v209, v91
	v_sub_f32_e32 v68, v208, v91
	v_pk_mul_f32 v[68:69], v[90:91], v[68:69] op_sel_hi:[0,1]
	v_pk_mul_f32 v[70:71], v[90:91], v[70:71] op_sel_hi:[0,1]
	v_pk_fma_f32 v[70:71], v[74:75], v[70:71], v[78:79]
	v_pk_fma_f32 v[68:69], v[72:73], v[68:69], v[76:77]
	v_pk_fma_f32 v[54:55], v[70:71], s[20:21], v[54:55] op_sel_hi:[1,0,1]
	v_pk_fma_f32 v[52:53], v[68:69], s[20:21], v[52:53] op_sel_hi:[1,0,1]
	v_pk_add_f32 v[54:55], v[82:83], v[54:55]
	v_pk_add_f32 v[52:53], v[80:81], v[52:53]
	global_store_dwordx4 v[66:67], v[52:55], off offset:512
	v_add_f32_e32 v80, v60, v61
	v_mul_f32_e32 v61, v61, v61
	v_fmac_f32_e32 v61, v60, v60
	v_add_f32_e32 v80, v62, v80
	v_fmac_f32_e32 v61, v62, v62
	v_add_f32_e32 v62, v56, v57
	v_mul_f32_e32 v57, v57, v57
	v_fmac_f32_e32 v57, v56, v56
	v_add_f32_e32 v60, v63, v80
	v_add_f32_e32 v62, v58, v62
	v_fmac_f32_e32 v57, v58, v58
	v_add_f32_e32 v60, 0, v60
	v_fmac_f32_e32 v61, v63, v63
	v_add_f32_e32 v56, v59, v62
	v_fmac_f32_e32 v57, v59, v59
	v_sub_f32_e32 v59, v213, v91
	v_sub_f32_e32 v58, v212, v91
	v_add_f32_e32 v60, v56, v60
	v_add_f32_e32 v61, v61, v57
	v_sub_f32_e32 v57, v215, v91
	v_sub_f32_e32 v56, v214, v91
	v_pk_mul_f32 v[58:59], v[90:91], v[58:59] op_sel_hi:[0,1]
	v_pk_mul_f32 v[56:57], v[90:91], v[56:57] op_sel_hi:[0,1]
	v_mul_f32_e32 v63, v53, v53
	v_add_f32_e32 v62, v52, v53
	v_fmac_f32_e32 v63, v52, v52
	v_add_f32_e32 v62, v54, v62
	v_fmac_f32_e32 v63, v54, v54
	v_add_f32_e32 v62, v55, v62
	v_fmac_f32_e32 v63, v55, v55
	v_add_f32_e32 v60, v60, v62
	v_add_f32_e32 v61, v61, v63
	v_cvt_pk_bf16_f32 v52, v52, v53
	v_cvt_pk_bf16_f32 v53, v54, v55
	v_pk_fma_f32 v[58:59], v[196:197], v[58:59], v[200:201]
	v_pk_fma_f32 v[56:57], v[198:199], v[56:57], v[202:203]
	v_pk_fma_f32 v[48:49], v[58:59], s[20:21], v[48:49] op_sel_hi:[1,0,1]
	v_pk_fma_f32 v[50:51], v[56:57], s[20:21], v[50:51] op_sel_hi:[1,0,1]
	v_pk_add_f32 v[56:57], v[204:205], v[48:49]
	v_pk_add_f32 v[58:59], v[206:207], v[50:51]
	v_mul_f32_e32 v49, v57, v57
	v_add_f32_e32 v48, v56, v57
	v_fmac_f32_e32 v49, v56, v56
	v_add_f32_e32 v48, v58, v48
	v_fmac_f32_e32 v49, v58, v58
	v_add_f32_e32 v48, v59, v48
	v_fmac_f32_e32 v49, v59, v59
	v_add_f32_e32 v48, v60, v48
	v_add_f32_e32 v49, v61, v49
	ds_bpermute_b32 v50, v118, v48
	ds_bpermute_b32 v51, v118, v49
	global_store_dwordx4 v[66:67], v[56:59], off offset:528
	v_cvt_pk_bf16_f32 v54, v56, v57
	v_cvt_pk_bf16_f32 v55, v58, v59
	s_waitcnt lgkmcnt(0)
	v_add_f32_e32 v48, v48, v50
	v_add_f32_e32 v49, v49, v51
	ds_bpermute_b32 v50, v119, v48
	ds_bpermute_b32 v51, v119, v49
	flat_store_dwordx4 v[88:89], v[52:55] offset:256
	s_and_saveexec_b64 s[30:31], s[2:3]
	s_cbranch_execz .LBB0_1339
	v_lshl_add_u64 v[52:53], s[8:9], 0, v[64:65]
	s_waitcnt lgkmcnt(0)
	v_add_f32_e32 v48, v48, v50
	v_add_f32_e32 v49, v49, v51
	flat_atomic_add_f32 v[52:53], v48
	flat_atomic_add_f32 v[52:53], v49 offset:4
; DEVI unsigned pk2(float lo, float hi) { unsigned r; asm("v_cvt_pk_bf16_f32 %0, %1, %2" : "=v"(r) : "v"(lo), "v"(hi)); return r; }
; DEVI void row_stats(const float* stats, int row, float& mu, float& rs) {
;     if (stats) { const float2 st = *(const float2*)(stats + 2 * (size_t)row); mu = st.x * (1.0f / 1024.0f); const float var = st.y * (1.0f / 1024.0f) - mu * mu; rs = rsqrtf(fmaxf(var, 0.f) + LN_EPS); }
;     else { mu = 0.f; rs = 1.f; }
;     DEVI void operator()(const f32x4 (&acc)[2][2][4][2], const pg8::Unit& u, int wr, int wc, int fr, int fq) const {
;     ...
;                 const int row = row0 + ai * 128 + m * 16; float mu, rs; row_stats(stin, row, mu, rs);
;                 float sum = 0.f, sq = 0.f;
; #pragma unroll
;                 for (int bj = 0; bj < 2; ++bj) {
;                     f32x4 z[2];
; #pragma unroll
;                     for (int n = 0; n < 2; ++n) {
;                         const int col = colb + bj * 128 + 4 * n;
;                         f32x4 xv = *(const f32x4*)(zsrc + (size_t)row * DM + col);
;                         if (stin) { const f32x4 gv = *(const f32x4*)(gin + col), bv = *(const f32x4*)(bin + col); xv = (xv - mu) * rs * gv + bv; }
;                         f32x4 zz = ALPHA * xv + acc[ai][bj][m][n];
;                         if (bias) zz += *(const f32x4*)(bias + col);
;                         *(f32x4*)(zdst + (size_t)row * DM + col) = zz;
;                         sum += zz[0] + zz[1] + zz[2] + zz[3]; sq += zz[0] * zz[0] + zz[1] * zz[1] + zz[2] * zz[2] + zz[3] * zz[3];
;                         z[n] = zz;
;                     }
;                     u32x4 o; o.x = pk2(z[0][0], z[0][1]); o.y = pk2(z[0][2], z[0][3]); o.z = pk2(z[1][0], z[1][1]); o.w = pk2(z[1][2], z[1][3]);
;                     if (zb) *(u32x4*)(zb + (size_t)row * DM + colb + bj * 128) = o;
;                 }
;                 sum += __shfl_xor(sum, 16); sq += __shfl_xor(sq, 16);
;                 sum += __shfl_xor(sum, 32); sq += __shfl_xor(sq, 32);
;                 if (fq == 0) { atomicAdd(stout + 2 * (size_t)row, sum); atomicAdd(stout + 2 * (size_t)row + 1, sq); }
.LBB0_1339:
	s_or_b64 exec, exec, s[30:31]
	v_add_u32_e32 v72, 0x90, v150
	v_ashrrev_i32_e32 v73, 31, v72
	v_lshlrev_b64 v[48:49], 3, v[72:73]
	s_waitcnt lgkmcnt(0)
	v_lshl_add_u64 v[50:51], s[6:7], 0, v[48:49]
	flat_load_dwordx2 v[74:75], v[50:51]
	v_lshlrev_b64 v[50:51], 12, v[72:73]
	v_lshl_add_u64 v[50:51], s[46:47], 0, v[50:51]
	v_lshl_add_u64 v[50:51], v[148:149], 2, v[50:51]
	global_load_dwordx4 v[52:55], v[50:51], off
	global_load_dwordx4 v[56:59], v[144:145], off
	global_load_dwordx4 v[60:63], v[146:147], off
	global_load_dwordx4 v[64:67], v[152:153], off
	global_load_dwordx4 v[68:71], v[50:51], off offset:16
	global_load_dwordx4 v[196:199], v[144:145], off offset:16
	global_load_dwordx4 v[200:203], v[146:147], off offset:16
	global_load_dwordx4 v[204:207], v[154:155], off
	global_load_dwordx4 v[208:211], v[50:51], off offset:512
	global_load_dwordx4 v[212:215], v[50:51], off offset:528
	s_waitcnt vmcnt(0) lgkmcnt(0)
	v_pk_mul_f32 v[74:75], v[74:75], s[18:19] op_sel:[1,0] op_sel_hi:[0,0]
	v_fma_f32 v74, -v75, v75, v74
	v_max_f32_e32 v74, 0, v74
	v_add_f32_e32 v74, 0x3727c5ac, v74
	v_mul_f32_e32 v76, 0x4b800000, v74
	v_cmp_gt_f32_e32 vcc, s64, v74
	v_sub_f32_e32 v55, v55, v75
	v_sub_f32_e32 v54, v54, v75
	v_cndmask_b32_e32 v74, v74, v76, vcc
	v_rsq_f32_e32 v74, v74
	v_sub_f32_e32 v53, v53, v75
	v_sub_f32_e32 v52, v52, v75
	v_mul_f32_e32 v76, 0x45800000, v74
	v_cndmask_b32_e32 v74, v74, v76, vcc
	v_pk_mul_f32 v[52:53], v[52:53], v[74:75] op_sel_hi:[1,0]
	v_pk_mul_f32 v[54:55], v[54:55], v[74:75] op_sel_hi:[1,0]
	v_pk_fma_f32 v[52:53], v[56:57], v[52:53], v[60:61]
	v_pk_fma_f32 v[54:55], v[58:59], v[54:55], v[62:63]
	v_pk_fma_f32 v[44:45], v[52:53], s[20:21], v[44:45] op_sel_hi:[1,0,1]
	v_pk_fma_f32 v[46:47], v[54:55], s[20:21], v[46:47] op_sel_hi:[1,0,1]
	v_pk_add_f32 v[44:45], v[64:65], v[44:45]
	v_pk_add_f32 v[46:47], v[66:67], v[46:47]
	global_store_dwordx4 v[50:51], v[44:47], off
	v_lshlrev_b64 v[64:65], 11, v[72:73]
	v_lshl_add_u64 v[64:65], s[10:11], 0, v[64:65]
	v_lshl_add_u64 v[72:73], v[148:149], 1, v[64:65]
	v_sub_f32_e32 v65, v71, v75
	v_sub_f32_e32 v64, v70, v75
	v_sub_f32_e32 v67, v69, v75
	v_sub_f32_e32 v66, v68, v75
	v_pk_mul_f32 v[66:67], v[66:67], v[74:75] op_sel_hi:[1,0]
	v_pk_mul_f32 v[68:69], v[64:65], v[74:75] op_sel_hi:[1,0]
	v_cvt_pk_bf16_f32 v64, v44, v45
	v_cvt_pk_bf16_f32 v65, v46, v47
	v_pk_fma_f32 v[52:53], v[196:197], v[66:67], v[200:201]
	v_pk_fma_f32 v[54:55], v[198:199], v[68:69], v[202:203]
	v_pk_fma_f32 v[40:41], v[52:53], s[20:21], v[40:41] op_sel_hi:[1,0,1]
	v_pk_fma_f32 v[42:43], v[54:55], s[20:21], v[42:43] op_sel_hi:[1,0,1]
	v_pk_add_f32 v[40:41], v[204:205], v[40:41]
	v_pk_add_f32 v[42:43], v[206:207], v[42:43]
	global_store_dwordx4 v[50:51], v[40:43], off offset:16
	v_cvt_pk_bf16_f32 v66, v40, v41
	v_cvt_pk_bf16_f32 v67, v42, v43
	flat_store_dwordx4 v[72:73], v[64:67]
	global_load_dwordx4 v[56:59], v[144:145], off offset:512
	global_load_dwordx4 v[60:63], v[146:147], off offset:512
	s_nop 0
	global_load_dwordx4 v[64:67], v[120:121], off
	global_load_dwordx4 v[196:199], v[144:145], off offset:528
	global_load_dwordx4 v[200:203], v[146:147], off offset:528
	global_load_dwordx4 v[204:207], v[116:117], off
	s_waitcnt vmcnt(0)
	v_sub_f32_e32 v55, v211, v75
	v_sub_f32_e32 v54, v210, v75
	v_sub_f32_e32 v53, v209, v75
	v_sub_f32_e32 v52, v208, v75
	v_pk_mul_f32 v[52:53], v[74:75], v[52:53] op_sel_hi:[0,1]
	v_pk_mul_f32 v[54:55], v[74:75], v[54:55] op_sel_hi:[0,1]
	v_pk_fma_f32 v[54:55], v[58:59], v[54:55], v[62:63]
	v_pk_fma_f32 v[52:53], v[56:57], v[52:53], v[60:61]
	v_pk_fma_f32 v[38:39], v[54:55], s[20:21], v[38:39] op_sel_hi:[1,0,1]
	v_pk_fma_f32 v[36:37], v[52:53], s[20:21], v[36:37] op_sel_hi:[1,0,1]
	v_pk_add_f32 v[38:39], v[66:67], v[38:39]
	v_pk_add_f32 v[36:37], v[64:65], v[36:37]
	global_store_dwordx4 v[50:51], v[36:39], off offset:512
	v_add_f32_e32 v64, v44, v45
	v_mul_f32_e32 v45, v45, v45
	v_fmac_f32_e32 v45, v44, v44
	v_add_f32_e32 v64, v46, v64
	v_fmac_f32_e32 v45, v46, v46
	v_add_f32_e32 v46, v40, v41
	v_mul_f32_e32 v41, v41, v41
	v_fmac_f32_e32 v41, v40, v40
	v_add_f32_e32 v44, v47, v64
	v_add_f32_e32 v46, v42, v46
	v_fmac_f32_e32 v41, v42, v42
	v_add_f32_e32 v44, 0, v44
	v_fmac_f32_e32 v45, v47, v47
	v_add_f32_e32 v40, v43, v46
	v_fmac_f32_e32 v41, v43, v43
	v_sub_f32_e32 v43, v213, v75
	v_sub_f32_e32 v42, v212, v75
	v_add_f32_e32 v44, v40, v44
	v_add_f32_e32 v45, v45, v41
	v_sub_f32_e32 v41, v215, v75
	v_sub_f32_e32 v40, v214, v75
	v_pk_mul_f32 v[42:43], v[74:75], v[42:43] op_sel_hi:[0,1]
	v_pk_mul_f32 v[40:41], v[74:75], v[40:41] op_sel_hi:[0,1]
	v_mul_f32_e32 v47, v37, v37
	v_add_f32_e32 v46, v36, v37
	v_fmac_f32_e32 v47, v36, v36
	v_add_f32_e32 v46, v38, v46
	v_fmac_f32_e32 v47, v38, v38
	v_add_f32_e32 v46, v39, v46
	v_fmac_f32_e32 v47, v39, v39
	v_add_f32_e32 v44, v44, v46
	v_add_f32_e32 v45, v45, v47
	v_cvt_pk_bf16_f32 v36, v36, v37
	v_cvt_pk_bf16_f32 v37, v38, v39
	v_pk_fma_f32 v[42:43], v[196:197], v[42:43], v[200:201]
	v_pk_fma_f32 v[40:41], v[198:199], v[40:41], v[202:203]
	v_pk_fma_f32 v[32:33], v[42:43], s[20:21], v[32:33] op_sel_hi:[1,0,1]
	v_pk_fma_f32 v[34:35], v[40:41], s[20:21], v[34:35] op_sel_hi:[1,0,1]
	v_pk_add_f32 v[40:41], v[204:205], v[32:33]
	v_pk_add_f32 v[42:43], v[206:207], v[34:35]
	v_mul_f32_e32 v33, v41, v41
	v_add_f32_e32 v32, v40, v41
	v_fmac_f32_e32 v33, v40, v40
	v_add_f32_e32 v32, v42, v32
	v_fmac_f32_e32 v33, v42, v42
	v_add_f32_e32 v32, v43, v32
	v_fmac_f32_e32 v33, v43, v43
	v_add_f32_e32 v32, v44, v32
	v_add_f32_e32 v33, v45, v33
	ds_bpermute_b32 v34, v118, v32
	ds_bpermute_b32 v35, v118, v33
	global_store_dwordx4 v[50:51], v[40:43], off offset:528
	v_cvt_pk_bf16_f32 v38, v40, v41
	v_cvt_pk_bf16_f32 v39, v42, v43
	s_waitcnt lgkmcnt(0)
	v_add_f32_e32 v32, v32, v34
	v_add_f32_e32 v33, v33, v35
	ds_bpermute_b32 v34, v119, v32
	ds_bpermute_b32 v35, v119, v33
	flat_store_dwordx4 v[72:73], v[36:39] offset:256
	s_and_saveexec_b64 s[30:31], s[2:3]
	s_cbranch_execz .LBB0_1341
	v_lshl_add_u64 v[36:37], s[8:9], 0, v[48:49]
	s_waitcnt lgkmcnt(0)
	v_add_f32_e32 v32, v32, v34
	v_add_f32_e32 v33, v33, v35
	flat_atomic_add_f32 v[36:37], v32
	flat_atomic_add_f32 v[36:37], v33 offset:4
; DEVI unsigned pk2(float lo, float hi) { unsigned r; asm("v_cvt_pk_bf16_f32 %0, %1, %2" : "=v"(r) : "v"(lo), "v"(hi)); return r; }
; DEVI void row_stats(const float* stats, int row, float& mu, float& rs) {
;     if (stats) { const float2 st = *(const float2*)(stats + 2 * (size_t)row); mu = st.x * (1.0f / 1024.0f); const float var = st.y * (1.0f / 1024.0f) - mu * mu; rs = rsqrtf(fmaxf(var, 0.f) + LN_EPS); }
;     else { mu = 0.f; rs = 1.f; }
;     DEVI void operator()(const f32x4 (&acc)[2][2][4][2], const pg8::Unit& u, int wr, int wc, int fr, int fq) const {
;     ...
;                 const int row = row0 + ai * 128 + m * 16; float mu, rs; row_stats(stin, row, mu, rs);
;                 float sum = 0.f, sq = 0.f;
; #pragma unroll
;                 for (int bj = 0; bj < 2; ++bj) {
;                     f32x4 z[2];
; #pragma unroll
;                     for (int n = 0; n < 2; ++n) {
;                         const int col = colb + bj * 128 + 4 * n;
;                         f32x4 xv = *(const f32x4*)(zsrc + (size_t)row * DM + col);
;                         if (stin) { const f32x4 gv = *(const f32x4*)(gin + col), bv = *(const f32x4*)(bin + col); xv = (xv - mu) * rs * gv + bv; }
;                         f32x4 zz = ALPHA * xv + acc[ai][bj][m][n];
;                         if (bias) zz += *(const f32x4*)(bias + col);
;                         *(f32x4*)(zdst + (size_t)row * DM + col) = zz;
;                         sum += zz[0] + zz[1] + zz[2] + zz[3]; sq += zz[0] * zz[0] + zz[1] * zz[1] + zz[2] * zz[2] + zz[3] * zz[3];
;                         z[n] = zz;
;                     }
;                     u32x4 o; o.x = pk2(z[0][0], z[0][1]); o.y = pk2(z[0][2], z[0][3]); o.z = pk2(z[1][0], z[1][1]); o.w = pk2(z[1][2], z[1][3]);
;                     if (zb) *(u32x4*)(zb + (size_t)row * DM + colb + bj * 128) = o;
;                 }
;                 sum += __shfl_xor(sum, 16); sq += __shfl_xor(sq, 16);
;                 sum += __shfl_xor(sum, 32); sq += __shfl_xor(sq, 32);
;                 if (fq == 0) { atomicAdd(stout + 2 * (size_t)row, sum); atomicAdd(stout + 2 * (size_t)row + 1, sq); }
.LBB0_1341:
	s_or_b64 exec, exec, s[30:31]
	v_add_u32_e32 v56, 0xa0, v150
	v_ashrrev_i32_e32 v57, 31, v56
	v_lshlrev_b64 v[32:33], 3, v[56:57]
	s_waitcnt lgkmcnt(0)
	v_lshl_add_u64 v[34:35], s[6:7], 0, v[32:33]
	flat_load_dwordx2 v[58:59], v[34:35]
	v_lshlrev_b64 v[34:35], 12, v[56:57]
	v_lshl_add_u64 v[34:35], s[46:47], 0, v[34:35]
	v_lshl_add_u64 v[34:35], v[148:149], 2, v[34:35]
	global_load_dwordx4 v[36:39], v[34:35], off
	global_load_dwordx4 v[40:43], v[144:145], off
	global_load_dwordx4 v[44:47], v[146:147], off
	global_load_dwordx4 v[48:51], v[152:153], off
	global_load_dwordx4 v[52:55], v[34:35], off offset:16
	global_load_dwordx4 v[196:199], v[144:145], off offset:16
	global_load_dwordx4 v[200:203], v[146:147], off offset:16
	global_load_dwordx4 v[204:207], v[154:155], off
	global_load_dwordx4 v[208:211], v[34:35], off offset:512
	global_load_dwordx4 v[212:215], v[34:35], off offset:528
	s_waitcnt vmcnt(0) lgkmcnt(0)
	v_pk_mul_f32 v[58:59], v[58:59], s[18:19] op_sel:[1,0] op_sel_hi:[0,0]
	v_fma_f32 v58, -v59, v59, v58
	v_max_f32_e32 v58, 0, v58
	v_add_f32_e32 v58, 0x3727c5ac, v58
	v_mul_f32_e32 v60, 0x4b800000, v58
	v_cmp_gt_f32_e32 vcc, s64, v58
	v_sub_f32_e32 v39, v39, v59
	v_sub_f32_e32 v38, v38, v59
	v_cndmask_b32_e32 v58, v58, v60, vcc
	v_rsq_f32_e32 v58, v58
	v_sub_f32_e32 v37, v37, v59
	v_sub_f32_e32 v36, v36, v59
	v_mul_f32_e32 v60, 0x45800000, v58
	v_cndmask_b32_e32 v58, v58, v60, vcc
	v_pk_mul_f32 v[36:37], v[36:37], v[58:59] op_sel_hi:[1,0]
	v_pk_mul_f32 v[38:39], v[38:39], v[58:59] op_sel_hi:[1,0]
	v_pk_fma_f32 v[36:37], v[40:41], v[36:37], v[44:45]
	v_pk_fma_f32 v[38:39], v[42:43], v[38:39], v[46:47]
	v_pk_fma_f32 v[28:29], v[36:37], s[20:21], v[28:29] op_sel_hi:[1,0,1]
	v_pk_fma_f32 v[30:31], v[38:39], s[20:21], v[30:31] op_sel_hi:[1,0,1]
	v_pk_add_f32 v[28:29], v[48:49], v[28:29]
	v_pk_add_f32 v[30:31], v[50:51], v[30:31]
	global_store_dwordx4 v[34:35], v[28:31], off
	v_lshlrev_b64 v[48:49], 11, v[56:57]
	v_lshl_add_u64 v[48:49], s[10:11], 0, v[48:49]
	v_lshl_add_u64 v[56:57], v[148:149], 1, v[48:49]
	v_sub_f32_e32 v49, v55, v59
	v_sub_f32_e32 v48, v54, v59
	v_sub_f32_e32 v51, v53, v59
	v_sub_f32_e32 v50, v52, v59
	v_pk_mul_f32 v[50:51], v[50:51], v[58:59] op_sel_hi:[1,0]
	v_pk_mul_f32 v[52:53], v[48:49], v[58:59] op_sel_hi:[1,0]
	v_cvt_pk_bf16_f32 v48, v28, v29
	v_cvt_pk_bf16_f32 v49, v30, v31
	v_pk_fma_f32 v[36:37], v[196:197], v[50:51], v[200:201]
	v_pk_fma_f32 v[38:39], v[198:199], v[52:53], v[202:203]
	v_pk_fma_f32 v[24:25], v[36:37], s[20:21], v[24:25] op_sel_hi:[1,0,1]
	v_pk_fma_f32 v[26:27], v[38:39], s[20:21], v[26:27] op_sel_hi:[1,0,1]
	v_pk_add_f32 v[24:25], v[204:205], v[24:25]
	v_pk_add_f32 v[26:27], v[206:207], v[26:27]
	global_store_dwordx4 v[34:35], v[24:27], off offset:16
	v_cvt_pk_bf16_f32 v50, v24, v25
	v_cvt_pk_bf16_f32 v51, v26, v27
	flat_store_dwordx4 v[56:57], v[48:51]
	global_load_dwordx4 v[40:43], v[144:145], off offset:512
	global_load_dwordx4 v[44:47], v[146:147], off offset:512
	s_nop 0
	global_load_dwordx4 v[48:51], v[120:121], off
	global_load_dwordx4 v[196:199], v[144:145], off offset:528
	global_load_dwordx4 v[200:203], v[146:147], off offset:528
	global_load_dwordx4 v[204:207], v[116:117], off
	s_waitcnt vmcnt(0)
	v_sub_f32_e32 v39, v211, v59
	v_sub_f32_e32 v38, v210, v59
	v_sub_f32_e32 v37, v209, v59
	v_sub_f32_e32 v36, v208, v59
	v_pk_mul_f32 v[36:37], v[58:59], v[36:37] op_sel_hi:[0,1]
	v_pk_mul_f32 v[38:39], v[58:59], v[38:39] op_sel_hi:[0,1]
	v_pk_fma_f32 v[38:39], v[42:43], v[38:39], v[46:47]
	v_pk_fma_f32 v[36:37], v[40:41], v[36:37], v[44:45]
	v_pk_fma_f32 v[22:23], v[38:39], s[20:21], v[22:23] op_sel_hi:[1,0,1]
	v_pk_fma_f32 v[20:21], v[36:37], s[20:21], v[20:21] op_sel_hi:[1,0,1]
	v_pk_add_f32 v[22:23], v[50:51], v[22:23]
	v_pk_add_f32 v[20:21], v[48:49], v[20:21]
	global_store_dwordx4 v[34:35], v[20:23], off offset:512
	v_add_f32_e32 v48, v28, v29
	v_mul_f32_e32 v29, v29, v29
	v_fmac_f32_e32 v29, v28, v28
	v_add_f32_e32 v48, v30, v48
	v_fmac_f32_e32 v29, v30, v30
	v_add_f32_e32 v30, v24, v25
	v_mul_f32_e32 v25, v25, v25
	v_fmac_f32_e32 v25, v24, v24
	v_add_f32_e32 v28, v31, v48
	v_add_f32_e32 v30, v26, v30
	v_fmac_f32_e32 v25, v26, v26
	v_add_f32_e32 v28, 0, v28
	v_fmac_f32_e32 v29, v31, v31
	v_add_f32_e32 v24, v27, v30
	v_fmac_f32_e32 v25, v27, v27
	v_sub_f32_e32 v27, v213, v59
	v_sub_f32_e32 v26, v212, v59
	v_add_f32_e32 v28, v24, v28
	v_add_f32_e32 v29, v29, v25
	v_sub_f32_e32 v25, v215, v59
	v_sub_f32_e32 v24, v214, v59
	v_pk_mul_f32 v[26:27], v[58:59], v[26:27] op_sel_hi:[0,1]
	v_pk_mul_f32 v[24:25], v[58:59], v[24:25] op_sel_hi:[0,1]
	v_mul_f32_e32 v31, v21, v21
	v_add_f32_e32 v30, v20, v21
	v_fmac_f32_e32 v31, v20, v20
	v_add_f32_e32 v30, v22, v30
	v_fmac_f32_e32 v31, v22, v22
	v_add_f32_e32 v30, v23, v30
	v_fmac_f32_e32 v31, v23, v23
	v_add_f32_e32 v28, v28, v30
	v_add_f32_e32 v29, v29, v31
	v_cvt_pk_bf16_f32 v20, v20, v21
	v_cvt_pk_bf16_f32 v21, v22, v23
	v_pk_fma_f32 v[26:27], v[196:197], v[26:27], v[200:201]
	v_pk_fma_f32 v[24:25], v[198:199], v[24:25], v[202:203]
	v_pk_fma_f32 v[16:17], v[26:27], s[20:21], v[16:17] op_sel_hi:[1,0,1]
	v_pk_fma_f32 v[18:19], v[24:25], s[20:21], v[18:19] op_sel_hi:[1,0,1]
	v_pk_add_f32 v[24:25], v[204:205], v[16:17]
	v_pk_add_f32 v[26:27], v[206:207], v[18:19]
	v_mul_f32_e32 v17, v25, v25
	v_add_f32_e32 v16, v24, v25
	v_fmac_f32_e32 v17, v24, v24
	v_add_f32_e32 v16, v26, v16
	v_fmac_f32_e32 v17, v26, v26
	v_add_f32_e32 v16, v27, v16
	v_fmac_f32_e32 v17, v27, v27
	v_add_f32_e32 v16, v28, v16
	v_add_f32_e32 v17, v29, v17
	ds_bpermute_b32 v18, v118, v16
	ds_bpermute_b32 v19, v118, v17
	global_store_dwordx4 v[34:35], v[24:27], off offset:528
	v_cvt_pk_bf16_f32 v22, v24, v25
	v_cvt_pk_bf16_f32 v23, v26, v27
	s_waitcnt lgkmcnt(0)
	v_add_f32_e32 v16, v16, v18
	v_add_f32_e32 v17, v17, v19
	ds_bpermute_b32 v18, v119, v16
	ds_bpermute_b32 v19, v119, v17
	flat_store_dwordx4 v[56:57], v[20:23] offset:256
	s_and_saveexec_b64 s[30:31], s[2:3]
	s_cbranch_execz .LBB0_1343
	v_lshl_add_u64 v[20:21], s[8:9], 0, v[32:33]
	s_waitcnt lgkmcnt(0)
	v_add_f32_e32 v16, v16, v18
	v_add_f32_e32 v17, v17, v19
	flat_atomic_add_f32 v[20:21], v16
	flat_atomic_add_f32 v[20:21], v17 offset:4
; DEVI unsigned pk2(float lo, float hi) { unsigned r; asm("v_cvt_pk_bf16_f32 %0, %1, %2" : "=v"(r) : "v"(lo), "v"(hi)); return r; }
; DEVI void row_stats(const float* stats, int row, float& mu, float& rs) {
;     if (stats) { const float2 st = *(const float2*)(stats + 2 * (size_t)row); mu = st.x * (1.0f / 1024.0f); const float var = st.y * (1.0f / 1024.0f) - mu * mu; rs = rsqrtf(fmaxf(var, 0.f) + LN_EPS); }
;     else { mu = 0.f; rs = 1.f; }
;     DEVI void operator()(const f32x4 (&acc)[2][2][4][2], const pg8::Unit& u, int wr, int wc, int fr, int fq) const {
;     ...
;                 const int row = row0 + ai * 128 + m * 16; float mu, rs; row_stats(stin, row, mu, rs);
;                 float sum = 0.f, sq = 0.f;
; #pragma unroll
;                 for (int bj = 0; bj < 2; ++bj) {
;                     f32x4 z[2];
; #pragma unroll
;                     for (int n = 0; n < 2; ++n) {
;                         const int col = colb + bj * 128 + 4 * n;
;                         f32x4 xv = *(const f32x4*)(zsrc + (size_t)row * DM + col);
;                         if (stin) { const f32x4 gv = *(const f32x4*)(gin + col), bv = *(const f32x4*)(bin + col); xv = (xv - mu) * rs * gv + bv; }
;                         f32x4 zz = ALPHA * xv + acc[ai][bj][m][n];
;                         if (bias) zz += *(const f32x4*)(bias + col);
;                         *(f32x4*)(zdst + (size_t)row * DM + col) = zz;
;                         sum += zz[0] + zz[1] + zz[2] + zz[3]; sq += zz[0] * zz[0] + zz[1] * zz[1] + zz[2] * zz[2] + zz[3] * zz[3];
;                         z[n] = zz;
;                     }
;                     u32x4 o; o.x = pk2(z[0][0], z[0][1]); o.y = pk2(z[0][2], z[0][3]); o.z = pk2(z[1][0], z[1][1]); o.w = pk2(z[1][2], z[1][3]);
;                     if (zb) *(u32x4*)(zb + (size_t)row * DM + colb + bj * 128) = o;
;                 }
;                 sum += __shfl_xor(sum, 16); sq += __shfl_xor(sq, 16);
;                 sum += __shfl_xor(sum, 32); sq += __shfl_xor(sq, 32);
;                 if (fq == 0) { atomicAdd(stout + 2 * (size_t)row, sum); atomicAdd(stout + 2 * (size_t)row + 1, sq); }
.LBB0_1343:
	s_or_b64 exec, exec, s[30:31]
	v_add_u32_e32 v40, 0xb0, v150
	v_ashrrev_i32_e32 v41, 31, v40
	v_lshlrev_b64 v[16:17], 3, v[40:41]
	s_waitcnt lgkmcnt(0)
	v_lshl_add_u64 v[18:19], s[6:7], 0, v[16:17]
	flat_load_dwordx2 v[42:43], v[18:19]
	v_lshlrev_b64 v[18:19], 12, v[40:41]
	v_lshl_add_u64 v[18:19], s[46:47], 0, v[18:19]
	v_lshl_add_u64 v[18:19], v[148:149], 2, v[18:19]
	global_load_dwordx4 v[20:23], v[18:19], off
	global_load_dwordx4 v[24:27], v[144:145], off
	global_load_dwordx4 v[28:31], v[146:147], off
	global_load_dwordx4 v[32:35], v[152:153], off
	global_load_dwordx4 v[36:39], v[18:19], off offset:16
	global_load_dwordx4 v[196:199], v[144:145], off offset:16
	global_load_dwordx4 v[200:203], v[146:147], off offset:16
	global_load_dwordx4 v[204:207], v[154:155], off
	global_load_dwordx4 v[208:211], v[18:19], off offset:512
	global_load_dwordx4 v[212:215], v[18:19], off offset:528
	s_waitcnt vmcnt(0) lgkmcnt(0)
	v_pk_mul_f32 v[42:43], v[42:43], s[18:19] op_sel:[1,0] op_sel_hi:[0,0]
	v_fma_f32 v42, -v43, v43, v42
	v_max_f32_e32 v42, 0, v42
	v_add_f32_e32 v42, 0x3727c5ac, v42
	v_mul_f32_e32 v44, 0x4b800000, v42
	v_cmp_gt_f32_e32 vcc, s64, v42
	v_sub_f32_e32 v23, v23, v43
	v_sub_f32_e32 v22, v22, v43
	v_cndmask_b32_e32 v42, v42, v44, vcc
	v_rsq_f32_e32 v42, v42
	v_sub_f32_e32 v21, v21, v43
	v_sub_f32_e32 v20, v20, v43
	v_mul_f32_e32 v44, 0x45800000, v42
	v_cndmask_b32_e32 v42, v42, v44, vcc
	v_pk_mul_f32 v[20:21], v[20:21], v[42:43] op_sel_hi:[1,0]
	v_pk_mul_f32 v[22:23], v[22:23], v[42:43] op_sel_hi:[1,0]
	v_pk_fma_f32 v[20:21], v[24:25], v[20:21], v[28:29]
	v_pk_fma_f32 v[22:23], v[26:27], v[22:23], v[30:31]
	v_pk_fma_f32 v[12:13], v[20:21], s[20:21], v[12:13] op_sel_hi:[1,0,1]
	v_pk_fma_f32 v[14:15], v[22:23], s[20:21], v[14:15] op_sel_hi:[1,0,1]
	v_pk_add_f32 v[12:13], v[32:33], v[12:13]
	v_pk_add_f32 v[14:15], v[34:35], v[14:15]
	global_store_dwordx4 v[18:19], v[12:15], off
	v_lshlrev_b64 v[32:33], 11, v[40:41]
	v_lshl_add_u64 v[32:33], s[10:11], 0, v[32:33]
	v_lshl_add_u64 v[40:41], v[148:149], 1, v[32:33]
	v_sub_f32_e32 v33, v39, v43
	v_sub_f32_e32 v32, v38, v43
	v_sub_f32_e32 v35, v37, v43
	v_sub_f32_e32 v34, v36, v43
	v_pk_mul_f32 v[34:35], v[34:35], v[42:43] op_sel_hi:[1,0]
	v_pk_mul_f32 v[36:37], v[32:33], v[42:43] op_sel_hi:[1,0]
	v_cvt_pk_bf16_f32 v32, v12, v13
	v_cvt_pk_bf16_f32 v33, v14, v15
	v_pk_fma_f32 v[20:21], v[196:197], v[34:35], v[200:201]
	v_pk_fma_f32 v[22:23], v[198:199], v[36:37], v[202:203]
	v_pk_fma_f32 v[8:9], v[20:21], s[20:21], v[8:9] op_sel_hi:[1,0,1]
	v_pk_fma_f32 v[10:11], v[22:23], s[20:21], v[10:11] op_sel_hi:[1,0,1]
	v_pk_add_f32 v[8:9], v[204:205], v[8:9]
	v_pk_add_f32 v[10:11], v[206:207], v[10:11]
	global_store_dwordx4 v[18:19], v[8:11], off offset:16
	v_cvt_pk_bf16_f32 v34, v8, v9
	v_cvt_pk_bf16_f32 v35, v10, v11
	flat_store_dwordx4 v[40:41], v[32:35]
	global_load_dwordx4 v[24:27], v[144:145], off offset:512
	global_load_dwordx4 v[28:31], v[146:147], off offset:512
	s_nop 0
	global_load_dwordx4 v[32:35], v[120:121], off
	global_load_dwordx4 v[196:199], v[144:145], off offset:528
	global_load_dwordx4 v[200:203], v[146:147], off offset:528
	global_load_dwordx4 v[204:207], v[116:117], off
	s_waitcnt vmcnt(0)
	v_sub_f32_e32 v23, v211, v43
	v_sub_f32_e32 v22, v210, v43
	v_sub_f32_e32 v21, v209, v43
	v_sub_f32_e32 v20, v208, v43
	v_pk_mul_f32 v[20:21], v[42:43], v[20:21] op_sel_hi:[0,1]
	v_pk_mul_f32 v[22:23], v[42:43], v[22:23] op_sel_hi:[0,1]
	v_pk_fma_f32 v[22:23], v[26:27], v[22:23], v[30:31]
	v_pk_fma_f32 v[20:21], v[24:25], v[20:21], v[28:29]
	v_pk_fma_f32 v[6:7], v[22:23], s[20:21], v[6:7] op_sel_hi:[1,0,1]
	v_pk_fma_f32 v[4:5], v[20:21], s[20:21], v[4:5] op_sel_hi:[1,0,1]
	v_pk_add_f32 v[6:7], v[34:35], v[6:7]
	v_pk_add_f32 v[4:5], v[32:33], v[4:5]
	global_store_dwordx4 v[18:19], v[4:7], off offset:512
	v_add_f32_e32 v32, v12, v13
	v_mul_f32_e32 v13, v13, v13
	v_fmac_f32_e32 v13, v12, v12
	v_add_f32_e32 v32, v14, v32
	v_fmac_f32_e32 v13, v14, v14
	v_add_f32_e32 v14, v8, v9
	v_mul_f32_e32 v9, v9, v9
	v_fmac_f32_e32 v9, v8, v8
	v_add_f32_e32 v12, v15, v32
	v_add_f32_e32 v14, v10, v14
	v_fmac_f32_e32 v9, v10, v10
	v_add_f32_e32 v12, 0, v12
	v_fmac_f32_e32 v13, v15, v15
	v_add_f32_e32 v8, v11, v14
	v_fmac_f32_e32 v9, v11, v11
	v_sub_f32_e32 v11, v213, v43
	v_sub_f32_e32 v10, v212, v43
	v_add_f32_e32 v12, v8, v12
	v_add_f32_e32 v13, v13, v9
	v_sub_f32_e32 v9, v215, v43
	v_sub_f32_e32 v8, v214, v43
	v_pk_mul_f32 v[10:11], v[42:43], v[10:11] op_sel_hi:[0,1]
	v_pk_mul_f32 v[8:9], v[42:43], v[8:9] op_sel_hi:[0,1]
	v_mul_f32_e32 v15, v5, v5
	v_add_f32_e32 v14, v4, v5
	v_fmac_f32_e32 v15, v4, v4
	v_add_f32_e32 v14, v6, v14
	v_fmac_f32_e32 v15, v6, v6
	v_add_f32_e32 v14, v7, v14
	v_fmac_f32_e32 v15, v7, v7
	v_add_f32_e32 v12, v12, v14
	v_add_f32_e32 v13, v13, v15
	v_cvt_pk_bf16_f32 v4, v4, v5
	v_cvt_pk_bf16_f32 v5, v6, v7
	v_pk_fma_f32 v[10:11], v[196:197], v[10:11], v[200:201]
	v_pk_fma_f32 v[8:9], v[198:199], v[8:9], v[202:203]
	v_pk_fma_f32 v[0:1], v[10:11], s[20:21], v[0:1] op_sel_hi:[1,0,1]
	v_pk_fma_f32 v[2:3], v[8:9], s[20:21], v[2:3] op_sel_hi:[1,0,1]
	v_pk_add_f32 v[8:9], v[204:205], v[0:1]
	v_pk_add_f32 v[10:11], v[206:207], v[2:3]
	v_mul_f32_e32 v1, v9, v9
	v_add_f32_e32 v0, v8, v9
	v_fmac_f32_e32 v1, v8, v8
	v_add_f32_e32 v0, v10, v0
	v_fmac_f32_e32 v1, v10, v10
	v_add_f32_e32 v0, v11, v0
	v_fmac_f32_e32 v1, v11, v11
	v_add_f32_e32 v0, v12, v0
	v_add_f32_e32 v1, v13, v1
	ds_bpermute_b32 v2, v118, v0
	ds_bpermute_b32 v3, v118, v1
	global_store_dwordx4 v[18:19], v[8:11], off offset:528
	v_cvt_pk_bf16_f32 v6, v8, v9
	v_cvt_pk_bf16_f32 v7, v10, v11
	s_waitcnt lgkmcnt(0)
	v_add_f32_e32 v0, v0, v2
	v_add_f32_e32 v1, v1, v3
	ds_bpermute_b32 v2, v119, v0
	ds_bpermute_b32 v3, v119, v1
	flat_store_dwordx4 v[40:41], v[4:7] offset:256
	s_and_saveexec_b64 s[30:31], s[2:3]
	s_cbranch_execz .LBB0_1345
	v_lshl_add_u64 v[4:5], s[8:9], 0, v[16:17]
	s_waitcnt lgkmcnt(0)
	v_add_f32_e32 v0, v0, v2
	v_add_f32_e32 v1, v1, v3
	flat_atomic_add_f32 v[4:5], v0
	flat_atomic_add_f32 v[4:5], v1 offset:4

; DEVI unsigned pk2(float lo, float hi) { unsigned r; asm("v_cvt_pk_bf16_f32 %0, %1, %2" : "=v"(r) : "v"(lo), "v"(hi)); return r; }
; DEVI void row_stats(const float* stats, int row, float& mu, float& rs) {
;     if (stats) { const float2 st = *(const float2*)(stats + 2 * (size_t)row); mu = st.x * (1.0f / 1024.0f); const float var = st.y * (1.0f / 1024.0f) - mu * mu; rs = rsqrtf(fmaxf(var, 0.f) + LN_EPS); }
;     else { mu = 0.f; rs = 1.f; }
;     DEVI void operator()(const f32x4 (&acc)[2][2][4][2], const pg8::Unit& u, int wr, int wc, int fr, int fq) const {
;     ...
;                 const int row = row0 + ai * 128 + m * 16; float mu, rs; row_stats(stin, row, mu, rs);
;                 float sum = 0.f, sq = 0.f;
; #pragma unroll
;                 for (int bj = 0; bj < 2; ++bj) {
;                     f32x4 z[2];
; #pragma unroll
;                     for (int n = 0; n < 2; ++n) {
;                         const int col = colb + bj * 128 + 4 * n;
;                         f32x4 xv = *(const f32x4*)(zsrc + (size_t)row * DM + col);
;                         if (stin) { const f32x4 gv = *(const f32x4*)(gin + col), bv = *(const f32x4*)(bin + col); xv = (xv - mu) * rs * gv + bv; }
;                         f32x4 zz = ALPHA * xv + acc[ai][bj][m][n];
;                         if (bias) zz += *(const f32x4*)(bias + col);
;                         *(f32x4*)(zdst + (size_t)row * DM + col) = zz;
;                         sum += zz[0] + zz[1] + zz[2] + zz[3]; sq += zz[0] * zz[0] + zz[1] * zz[1] + zz[2] * zz[2] + zz[3] * zz[3];
;                         z[n] = zz;
;                     }
;                     u32x4 o; o.x = pk2(z[0][0], z[0][1]); o.y = pk2(z[0][2], z[0][3]); o.z = pk2(z[1][0], z[1][1]); o.w = pk2(z[1][2], z[1][3]);
;                     if (zb) *(u32x4*)(zb + (size_t)row * DM + colb + bj * 128) = o;
;                 }
;                 sum += __shfl_xor(sum, 16); sq += __shfl_xor(sq, 16);
;                 sum += __shfl_xor(sum, 32); sq += __shfl_xor(sq, 32);
;                 if (fq == 0) { atomicAdd(stout + 2 * (size_t)row, sum); atomicAdd(stout + 2 * (size_t)row + 1, sq); }
.LBB0_1540:
	s_or_b64 exec, exec, s[30:31]
	v_or_b32_e32 v118, 16, v154
	v_ashrrev_i32_e32 v119, 31, v118
	v_lshlrev_b64 v[112:113], 3, v[118:119]
	s_waitcnt lgkmcnt(0)
	v_lshl_add_u64 v[114:115], s[12:13], 0, v[112:113]
	flat_load_dwordx2 v[160:161], v[114:115]
	v_lshlrev_b64 v[114:115], 12, v[118:119]
	v_lshl_add_u64 v[114:115], s[46:47], 0, v[114:115]
	v_lshl_add_u64 v[114:115], v[144:145], 2, v[114:115]
	global_load_dwordx4 v[156:159], v[114:115], off
	global_load_dwordx4 v[170:173], v[150:151], off
	global_load_dwordx4 v[174:177], v[152:153], off
	global_load_dwordx4 v[178:181], v[114:115], off offset:16
	v_lshlrev_b64 v[118:119], 11, v[118:119]
	v_lshl_add_u64 v[118:119], s[14:15], 0, v[118:119]
	v_lshl_add_u64 v[118:119], v[144:145], 1, v[118:119]
	global_load_dwordx4 v[196:199], v[146:147], off
	global_load_dwordx4 v[200:203], v[148:149], off
	global_load_dwordx4 v[204:207], v[114:115], off offset:512
	global_load_dwordx4 v[208:211], v[114:115], off offset:528
	s_waitcnt vmcnt(0) lgkmcnt(0)
	v_pk_mul_f32 v[160:161], v[160:161], s[24:25] op_sel:[1,0] op_sel_hi:[0,0]
	v_fma_f32 v155, -v161, v161, v160
	v_max_f32_e32 v155, 0, v155
	v_add_f32_e32 v155, 0x3727c5ac, v155
	v_mul_f32_e32 v160, 0x4b800000, v155
	v_cmp_gt_f32_e32 vcc, s61, v155
	v_sub_f32_e32 v157, v157, v161
	v_sub_f32_e32 v156, v156, v161
	v_cndmask_b32_e32 v155, v155, v160, vcc
	v_rsq_f32_e32 v155, v155
	v_sub_f32_e32 v159, v159, v161
	v_sub_f32_e32 v158, v158, v161
	v_mul_f32_e32 v160, 0x45800000, v155
	v_cndmask_b32_e32 v160, v155, v160, vcc
	v_pk_mul_f32 v[158:159], v[158:159], v[160:161] op_sel_hi:[1,0]
	v_pk_mul_f32 v[156:157], v[156:157], v[160:161] op_sel_hi:[1,0]
	v_pk_fma_f32 v[158:159], v[172:173], v[158:159], v[176:177]
	v_pk_fma_f32 v[156:157], v[170:171], v[156:157], v[174:175]
	v_pk_fma_f32 v[110:111], v[158:159], s[26:27], v[110:111] op_sel_hi:[1,0,1]
	v_pk_fma_f32 v[108:109], v[156:157], s[26:27], v[108:109] op_sel_hi:[1,0,1]
	global_store_dwordx4 v[114:115], v[108:111], off
	v_sub_f32_e32 v175, v179, v161
	v_sub_f32_e32 v174, v178, v161
	v_sub_f32_e32 v177, v181, v161
	v_sub_f32_e32 v176, v180, v161
	v_pk_mul_f32 v[176:177], v[176:177], v[160:161] op_sel_hi:[1,0]
	v_pk_mul_f32 v[178:179], v[174:175], v[160:161] op_sel_hi:[1,0]
	v_cvt_pk_bf16_f32 v174, v108, v109
	v_cvt_pk_bf16_f32 v175, v110, v111
	v_add_f32_e32 v155, v108, v109
	v_mul_f32_e32 v109, v109, v109
	v_fmac_f32_e32 v109, v108, v108
	v_add_f32_e32 v155, v110, v155
	v_fmac_f32_e32 v109, v110, v110
	v_add_f32_e32 v108, v111, v155
	v_add_f32_e32 v108, 0, v108
	v_fmac_f32_e32 v109, v111, v111
	v_pk_fma_f32 v[156:157], v[196:197], v[178:179], v[200:201]
	v_pk_fma_f32 v[158:159], v[198:199], v[176:177], v[202:203]
	v_pk_fma_f32 v[104:105], v[156:157], s[26:27], v[104:105] op_sel_hi:[1,0,1]
	v_pk_fma_f32 v[106:107], v[158:159], s[26:27], v[106:107] op_sel_hi:[1,0,1]
	global_store_dwordx4 v[114:115], v[104:107], off offset:16
	v_cvt_pk_bf16_f32 v176, v104, v105
	v_cvt_pk_bf16_f32 v177, v106, v107
	flat_store_dwordx4 v[118:119], v[174:177]
	global_load_dwordx4 v[170:173], v[120:121], off
	s_nop 0
	global_load_dwordx4 v[174:177], v[122:123], off
	v_add_f32_e32 v110, v104, v105
	v_mul_f32_e32 v105, v105, v105
	v_fmac_f32_e32 v105, v104, v104
	v_add_f32_e32 v110, v106, v110
	v_fmac_f32_e32 v105, v106, v106
	v_add_f32_e32 v104, v107, v110
	v_fmac_f32_e32 v105, v107, v107
	v_add_f32_e32 v108, v104, v108
	v_add_f32_e32 v109, v109, v105
	global_load_dwordx4 v[196:199], v[124:125], off
	global_load_dwordx4 v[200:203], v[126:127], off
	s_waitcnt vmcnt(0)
	v_sub_f32_e32 v157, v205, v161
	v_sub_f32_e32 v156, v204, v161
	v_sub_f32_e32 v159, v207, v161
	v_sub_f32_e32 v158, v206, v161
	v_pk_mul_f32 v[158:159], v[160:161], v[158:159] op_sel_hi:[0,1]
	v_pk_mul_f32 v[156:157], v[160:161], v[156:157] op_sel_hi:[0,1]
	v_pk_fma_f32 v[156:157], v[170:171], v[156:157], v[174:175]
	v_pk_fma_f32 v[158:159], v[172:173], v[158:159], v[176:177]
	v_pk_fma_f32 v[100:101], v[156:157], s[26:27], v[100:101] op_sel_hi:[1,0,1]
	v_pk_fma_f32 v[102:103], v[158:159], s[26:27], v[102:103] op_sel_hi:[1,0,1]
	global_store_dwordx4 v[114:115], v[100:103], off offset:512
	v_sub_f32_e32 v105, v209, v161
	v_sub_f32_e32 v104, v208, v161
	v_pk_mul_f32 v[104:105], v[160:161], v[104:105] op_sel_hi:[0,1]
	v_sub_f32_e32 v107, v211, v161
	v_sub_f32_e32 v106, v210, v161
	v_pk_mul_f32 v[106:107], v[160:161], v[106:107] op_sel_hi:[0,1]
	v_mul_f32_e32 v111, v101, v101
	v_add_f32_e32 v110, v100, v101
	v_fmac_f32_e32 v111, v100, v100
	v_add_f32_e32 v110, v102, v110
	v_fmac_f32_e32 v111, v102, v102
	v_add_f32_e32 v110, v103, v110
	v_fmac_f32_e32 v111, v103, v103
	v_add_f32_e32 v108, v108, v110
	v_add_f32_e32 v109, v109, v111
	v_cvt_pk_bf16_f32 v100, v100, v101
	v_cvt_pk_bf16_f32 v101, v102, v103
	v_pk_fma_f32 v[104:105], v[196:197], v[104:105], v[200:201]
	s_nop 0
	v_pk_fma_f32 v[104:105], v[104:105], s[26:27], v[96:97] op_sel_hi:[1,0,1]
	v_pk_fma_f32 v[106:107], v[198:199], v[106:107], v[202:203]
	v_mul_f32_e32 v97, v105, v105
	v_pk_fma_f32 v[106:107], v[106:107], s[26:27], v[98:99] op_sel_hi:[1,0,1]
	v_add_f32_e32 v96, v104, v105
	v_fmac_f32_e32 v97, v104, v104
	v_add_f32_e32 v96, v106, v96
	v_fmac_f32_e32 v97, v106, v106
	v_add_f32_e32 v96, v107, v96
	v_fmac_f32_e32 v97, v107, v107
	v_add_f32_e32 v96, v108, v96
	v_add_f32_e32 v97, v109, v97
	ds_bpermute_b32 v98, v116, v96
	ds_bpermute_b32 v99, v116, v97
	global_store_dwordx4 v[114:115], v[104:107], off offset:528
	v_cvt_pk_bf16_f32 v102, v104, v105
	v_cvt_pk_bf16_f32 v103, v106, v107
	s_waitcnt lgkmcnt(0)
	v_add_f32_e32 v96, v96, v98
	v_add_f32_e32 v97, v97, v99
	ds_bpermute_b32 v98, v117, v96
	ds_bpermute_b32 v99, v117, v97
	flat_store_dwordx4 v[118:119], v[100:103] offset:256
	s_and_saveexec_b64 s[30:31], s[2:3]
	s_cbranch_execz .LBB0_1542
	v_lshl_add_u64 v[100:101], s[10:11], 0, v[112:113]
	s_waitcnt lgkmcnt(0)
	v_add_f32_e32 v96, v96, v98
	v_add_f32_e32 v97, v97, v99
	flat_atomic_add_f32 v[100:101], v96
	flat_atomic_add_f32 v[100:101], v97 offset:4
; DEVI unsigned pk2(float lo, float hi) { unsigned r; asm("v_cvt_pk_bf16_f32 %0, %1, %2" : "=v"(r) : "v"(lo), "v"(hi)); return r; }
; DEVI void row_stats(const float* stats, int row, float& mu, float& rs) {
;     if (stats) { const float2 st = *(const float2*)(stats + 2 * (size_t)row); mu = st.x * (1.0f / 1024.0f); const float var = st.y * (1.0f / 1024.0f) - mu * mu; rs = rsqrtf(fmaxf(var, 0.f) + LN_EPS); }
;     else { mu = 0.f; rs = 1.f; }
;     DEVI void operator()(const f32x4 (&acc)[2][2][4][2], const pg8::Unit& u, int wr, int wc, int fr, int fq) const {
;     ...
;                 const int row = row0 + ai * 128 + m * 16; float mu, rs; row_stats(stin, row, mu, rs);
;                 float sum = 0.f, sq = 0.f;
; #pragma unroll
;                 for (int bj = 0; bj < 2; ++bj) {
;                     f32x4 z[2];
; #pragma unroll
;                     for (int n = 0; n < 2; ++n) {
;                         const int col = colb + bj * 128 + 4 * n;
;                         f32x4 xv = *(const f32x4*)(zsrc + (size_t)row * DM + col);
;                         if (stin) { const f32x4 gv = *(const f32x4*)(gin + col), bv = *(const f32x4*)(bin + col); xv = (xv - mu) * rs * gv + bv; }
;                         f32x4 zz = ALPHA * xv + acc[ai][bj][m][n];
;                         if (bias) zz += *(const f32x4*)(bias + col);
;                         *(f32x4*)(zdst + (size_t)row * DM + col) = zz;
;                         sum += zz[0] + zz[1] + zz[2] + zz[3]; sq += zz[0] * zz[0] + zz[1] * zz[1] + zz[2] * zz[2] + zz[3] * zz[3];
;                         z[n] = zz;
;                     }
;                     u32x4 o; o.x = pk2(z[0][0], z[0][1]); o.y = pk2(z[0][2], z[0][3]); o.z = pk2(z[1][0], z[1][1]); o.w = pk2(z[1][2], z[1][3]);
;                     if (zb) *(u32x4*)(zb + (size_t)row * DM + colb + bj * 128) = o;
;                 }
;                 sum += __shfl_xor(sum, 16); sq += __shfl_xor(sq, 16);
;                 sum += __shfl_xor(sum, 32); sq += __shfl_xor(sq, 32);
;                 if (fq == 0) { atomicAdd(stout + 2 * (size_t)row, sum); atomicAdd(stout + 2 * (size_t)row + 1, sq); }
.LBB0_1542:
	s_or_b64 exec, exec, s[30:31]
	v_or_b32_e32 v118, 32, v154
	v_ashrrev_i32_e32 v119, 31, v118
	v_lshlrev_b64 v[96:97], 3, v[118:119]
	s_waitcnt lgkmcnt(0)
	v_lshl_add_u64 v[98:99], s[12:13], 0, v[96:97]
	flat_load_dwordx2 v[156:157], v[98:99]
	v_lshlrev_b64 v[98:99], 12, v[118:119]
	v_lshl_add_u64 v[98:99], s[46:47], 0, v[98:99]
	v_lshl_add_u64 v[98:99], v[144:145], 2, v[98:99]
	global_load_dwordx4 v[100:103], v[98:99], off
	global_load_dwordx4 v[104:107], v[150:151], off
	global_load_dwordx4 v[108:111], v[152:153], off
	global_load_dwordx4 v[112:115], v[98:99], off offset:16
	global_load_dwordx4 v[196:199], v[146:147], off
	global_load_dwordx4 v[200:203], v[148:149], off
	global_load_dwordx4 v[204:207], v[98:99], off offset:512
	global_load_dwordx4 v[208:211], v[98:99], off offset:528
	s_waitcnt vmcnt(0) lgkmcnt(0)
	v_pk_mul_f32 v[156:157], v[156:157], s[24:25] op_sel:[1,0] op_sel_hi:[0,0]
	v_fma_f32 v155, -v157, v157, v156
	v_max_f32_e32 v155, 0, v155
	v_add_f32_e32 v155, 0x3727c5ac, v155
	v_mul_f32_e32 v156, 0x4b800000, v155
	v_cmp_gt_f32_e32 vcc, s61, v155
	v_sub_f32_e32 v101, v101, v157
	v_sub_f32_e32 v100, v100, v157
	v_cndmask_b32_e32 v155, v155, v156, vcc
	v_rsq_f32_e32 v155, v155
	v_sub_f32_e32 v103, v103, v157
	v_sub_f32_e32 v102, v102, v157
	v_mul_f32_e32 v156, 0x45800000, v155
	v_cndmask_b32_e32 v156, v155, v156, vcc
	v_pk_mul_f32 v[102:103], v[102:103], v[156:157] op_sel_hi:[1,0]
	v_pk_mul_f32 v[100:101], v[100:101], v[156:157] op_sel_hi:[1,0]
	v_pk_fma_f32 v[102:103], v[106:107], v[102:103], v[110:111]
	v_pk_fma_f32 v[100:101], v[104:105], v[100:101], v[108:109]
	v_pk_fma_f32 v[94:95], v[102:103], s[26:27], v[94:95] op_sel_hi:[1,0,1]
	v_pk_fma_f32 v[92:93], v[100:101], s[26:27], v[92:93] op_sel_hi:[1,0,1]
	global_store_dwordx4 v[98:99], v[92:95], off
	v_lshlrev_b64 v[108:109], 11, v[118:119]
	v_lshl_add_u64 v[108:109], s[14:15], 0, v[108:109]
	v_lshl_add_u64 v[118:119], v[144:145], 1, v[108:109]
	v_sub_f32_e32 v109, v113, v157
	v_sub_f32_e32 v108, v112, v157
	v_sub_f32_e32 v111, v115, v157
	v_sub_f32_e32 v110, v114, v157
	v_pk_mul_f32 v[110:111], v[110:111], v[156:157] op_sel_hi:[1,0]
	v_pk_mul_f32 v[112:113], v[108:109], v[156:157] op_sel_hi:[1,0]
	v_cvt_pk_bf16_f32 v108, v92, v93
	v_cvt_pk_bf16_f32 v109, v94, v95
	v_pk_fma_f32 v[102:103], v[198:199], v[110:111], v[202:203]
	v_pk_fma_f32 v[100:101], v[196:197], v[112:113], v[200:201]
	v_pk_fma_f32 v[90:91], v[102:103], s[26:27], v[90:91] op_sel_hi:[1,0,1]
	v_pk_fma_f32 v[88:89], v[100:101], s[26:27], v[88:89] op_sel_hi:[1,0,1]
	global_store_dwordx4 v[98:99], v[88:91], off offset:16
	v_cvt_pk_bf16_f32 v110, v88, v89
	v_cvt_pk_bf16_f32 v111, v90, v91
	flat_store_dwordx4 v[118:119], v[108:111]
	global_load_dwordx4 v[104:107], v[120:121], off
	s_nop 0
	global_load_dwordx4 v[108:111], v[122:123], off
	global_load_dwordx4 v[196:199], v[124:125], off
	global_load_dwordx4 v[200:203], v[126:127], off
	s_waitcnt vmcnt(0)
	v_sub_f32_e32 v101, v205, v157
	v_sub_f32_e32 v100, v204, v157
	v_sub_f32_e32 v103, v207, v157
	v_sub_f32_e32 v102, v206, v157
	v_pk_mul_f32 v[102:103], v[156:157], v[102:103] op_sel_hi:[0,1]
	v_pk_mul_f32 v[100:101], v[156:157], v[100:101] op_sel_hi:[0,1]
	v_pk_fma_f32 v[100:101], v[104:105], v[100:101], v[108:109]
	v_pk_fma_f32 v[102:103], v[106:107], v[102:103], v[110:111]
	v_pk_fma_f32 v[84:85], v[100:101], s[26:27], v[84:85] op_sel_hi:[1,0,1]
	v_pk_fma_f32 v[86:87], v[102:103], s[26:27], v[86:87] op_sel_hi:[1,0,1]
	global_store_dwordx4 v[98:99], v[84:87], off offset:512
	v_add_f32_e32 v108, v92, v93
	v_mul_f32_e32 v93, v93, v93
	v_fmac_f32_e32 v93, v92, v92
	v_add_f32_e32 v108, v94, v108
	v_fmac_f32_e32 v93, v94, v94
	v_add_f32_e32 v94, v88, v89
	v_mul_f32_e32 v89, v89, v89
	v_fmac_f32_e32 v89, v88, v88
	v_add_f32_e32 v92, v95, v108
	v_add_f32_e32 v94, v90, v94
	v_fmac_f32_e32 v89, v90, v90
	v_add_f32_e32 v92, 0, v92
	v_fmac_f32_e32 v93, v95, v95
	v_add_f32_e32 v88, v91, v94
	v_fmac_f32_e32 v89, v91, v91
	v_add_f32_e32 v92, v88, v92
	v_add_f32_e32 v93, v93, v89
	v_sub_f32_e32 v89, v209, v157
	v_sub_f32_e32 v88, v208, v157
	v_pk_mul_f32 v[88:89], v[156:157], v[88:89] op_sel_hi:[0,1]
	v_sub_f32_e32 v91, v211, v157
	v_sub_f32_e32 v90, v210, v157
	v_pk_mul_f32 v[90:91], v[156:157], v[90:91] op_sel_hi:[0,1]
	v_mul_f32_e32 v95, v85, v85
	v_add_f32_e32 v94, v84, v85
	v_fmac_f32_e32 v95, v84, v84
	v_add_f32_e32 v94, v86, v94
	v_fmac_f32_e32 v95, v86, v86
	v_add_f32_e32 v94, v87, v94
	v_fmac_f32_e32 v95, v87, v87
	v_add_f32_e32 v92, v92, v94
	v_add_f32_e32 v93, v93, v95
	v_cvt_pk_bf16_f32 v84, v84, v85
	v_cvt_pk_bf16_f32 v85, v86, v87
	v_pk_fma_f32 v[88:89], v[196:197], v[88:89], v[200:201]
	s_nop 0
	v_pk_fma_f32 v[88:89], v[88:89], s[26:27], v[80:81] op_sel_hi:[1,0,1]
	v_pk_fma_f32 v[90:91], v[198:199], v[90:91], v[202:203]
	v_mul_f32_e32 v81, v89, v89
	v_pk_fma_f32 v[90:91], v[90:91], s[26:27], v[82:83] op_sel_hi:[1,0,1]
	v_add_f32_e32 v80, v88, v89
	v_fmac_f32_e32 v81, v88, v88
	v_add_f32_e32 v80, v90, v80
	v_fmac_f32_e32 v81, v90, v90
	v_add_f32_e32 v80, v91, v80
	v_fmac_f32_e32 v81, v91, v91
	v_add_f32_e32 v80, v92, v80
	v_add_f32_e32 v81, v93, v81
	ds_bpermute_b32 v82, v116, v80
	ds_bpermute_b32 v83, v116, v81
	global_store_dwordx4 v[98:99], v[88:91], off offset:528
	v_cvt_pk_bf16_f32 v86, v88, v89
	v_cvt_pk_bf16_f32 v87, v90, v91
	s_waitcnt lgkmcnt(0)
	v_add_f32_e32 v80, v80, v82
	v_add_f32_e32 v81, v81, v83
	ds_bpermute_b32 v82, v117, v80
	ds_bpermute_b32 v83, v117, v81
	flat_store_dwordx4 v[118:119], v[84:87] offset:256
	s_and_saveexec_b64 s[30:31], s[2:3]
	s_cbranch_execz .LBB0_1544
	v_lshl_add_u64 v[84:85], s[10:11], 0, v[96:97]
	s_waitcnt lgkmcnt(0)
	v_add_f32_e32 v80, v80, v82
	v_add_f32_e32 v81, v81, v83
	flat_atomic_add_f32 v[84:85], v80
	flat_atomic_add_f32 v[84:85], v81 offset:4
; DEVI unsigned pk2(float lo, float hi) { unsigned r; asm("v_cvt_pk_bf16_f32 %0, %1, %2" : "=v"(r) : "v"(lo), "v"(hi)); return r; }
; DEVI void row_stats(const float* stats, int row, float& mu, float& rs) {
;     if (stats) { const float2 st = *(const float2*)(stats + 2 * (size_t)row); mu = st.x * (1.0f / 1024.0f); const float var = st.y * (1.0f / 1024.0f) - mu * mu; rs = rsqrtf(fmaxf(var, 0.f) + LN_EPS); }
;     else { mu = 0.f; rs = 1.f; }
;     DEVI void operator()(const f32x4 (&acc)[2][2][4][2], const pg8::Unit& u, int wr, int wc, int fr, int fq) const {
;     ...
;                 const int row = row0 + ai * 128 + m * 16; float mu, rs; row_stats(stin, row, mu, rs);
;                 float sum = 0.f, sq = 0.f;
; #pragma unroll
;                 for (int bj = 0; bj < 2; ++bj) {
;                     f32x4 z[2];
; #pragma unroll
;                     for (int n = 0; n < 2; ++n) {
;                         const int col = colb + bj * 128 + 4 * n;
;                         f32x4 xv = *(const f32x4*)(zsrc + (size_t)row * DM + col);
;                         if (stin) { const f32x4 gv = *(const f32x4*)(gin + col), bv = *(const f32x4*)(bin + col); xv = (xv - mu) * rs * gv + bv; }
;                         f32x4 zz = ALPHA * xv + acc[ai][bj][m][n];
;                         if (bias) zz += *(const f32x4*)(bias + col);
;                         *(f32x4*)(zdst + (size_t)row * DM + col) = zz;
;                         sum += zz[0] + zz[1] + zz[2] + zz[3]; sq += zz[0] * zz[0] + zz[1] * zz[1] + zz[2] * zz[2] + zz[3] * zz[3];
;                         z[n] = zz;
;                     }
;                     u32x4 o; o.x = pk2(z[0][0], z[0][1]); o.y = pk2(z[0][2], z[0][3]); o.z = pk2(z[1][0], z[1][1]); o.w = pk2(z[1][2], z[1][3]);
;                     if (zb) *(u32x4*)(zb + (size_t)row * DM + colb + bj * 128) = o;
;                 }
;                 sum += __shfl_xor(sum, 16); sq += __shfl_xor(sq, 16);
;                 sum += __shfl_xor(sum, 32); sq += __shfl_xor(sq, 32);
;                 if (fq == 0) { atomicAdd(stout + 2 * (size_t)row, sum); atomicAdd(stout + 2 * (size_t)row + 1, sq); }
.LBB0_1544:
	s_or_b64 exec, exec, s[30:31]
	v_or_b32_e32 v100, 48, v154
	v_ashrrev_i32_e32 v101, 31, v100
	v_lshlrev_b64 v[80:81], 3, v[100:101]
	s_waitcnt lgkmcnt(0)
	v_lshl_add_u64 v[82:83], s[12:13], 0, v[80:81]
	flat_load_dwordx2 v[102:103], v[82:83]
	v_lshlrev_b64 v[82:83], 12, v[100:101]
	v_lshl_add_u64 v[82:83], s[46:47], 0, v[82:83]
	v_lshl_add_u64 v[82:83], v[144:145], 2, v[82:83]
	global_load_dwordx4 v[84:87], v[82:83], off
	global_load_dwordx4 v[88:91], v[150:151], off
	global_load_dwordx4 v[92:95], v[152:153], off
	global_load_dwordx4 v[96:99], v[82:83], off offset:16
	global_load_dwordx4 v[196:199], v[146:147], off
	global_load_dwordx4 v[200:203], v[148:149], off
	global_load_dwordx4 v[204:207], v[82:83], off offset:512
	global_load_dwordx4 v[208:211], v[82:83], off offset:528
	s_waitcnt vmcnt(0) lgkmcnt(0)
	v_pk_mul_f32 v[102:103], v[102:103], s[24:25] op_sel:[1,0] op_sel_hi:[0,0]
	v_fma_f32 v102, -v103, v103, v102
	v_max_f32_e32 v102, 0, v102
	v_add_f32_e32 v102, 0x3727c5ac, v102
	v_mul_f32_e32 v104, 0x4b800000, v102
	v_cmp_gt_f32_e32 vcc, s61, v102
	v_sub_f32_e32 v85, v85, v103
	v_sub_f32_e32 v84, v84, v103
	v_cndmask_b32_e32 v102, v102, v104, vcc
	v_rsq_f32_e32 v102, v102
	v_sub_f32_e32 v87, v87, v103
	v_sub_f32_e32 v86, v86, v103
	v_mul_f32_e32 v104, 0x45800000, v102
	v_cndmask_b32_e32 v102, v102, v104, vcc
	v_pk_mul_f32 v[86:87], v[86:87], v[102:103] op_sel_hi:[1,0]
	v_pk_mul_f32 v[84:85], v[84:85], v[102:103] op_sel_hi:[1,0]
	v_pk_fma_f32 v[86:87], v[90:91], v[86:87], v[94:95]
	v_pk_fma_f32 v[84:85], v[88:89], v[84:85], v[92:93]
	v_pk_fma_f32 v[78:79], v[86:87], s[26:27], v[78:79] op_sel_hi:[1,0,1]
	v_pk_fma_f32 v[76:77], v[84:85], s[26:27], v[76:77] op_sel_hi:[1,0,1]
	global_store_dwordx4 v[82:83], v[76:79], off
	v_lshlrev_b64 v[92:93], 11, v[100:101]
	v_lshl_add_u64 v[92:93], s[14:15], 0, v[92:93]
	v_lshl_add_u64 v[100:101], v[144:145], 1, v[92:93]
	v_sub_f32_e32 v93, v97, v103
	v_sub_f32_e32 v92, v96, v103
	v_sub_f32_e32 v95, v99, v103
	v_sub_f32_e32 v94, v98, v103
	v_pk_mul_f32 v[94:95], v[94:95], v[102:103] op_sel_hi:[1,0]
	v_pk_mul_f32 v[96:97], v[92:93], v[102:103] op_sel_hi:[1,0]
	v_cvt_pk_bf16_f32 v92, v76, v77
	v_cvt_pk_bf16_f32 v93, v78, v79
	v_pk_fma_f32 v[86:87], v[198:199], v[94:95], v[202:203]
	v_pk_fma_f32 v[84:85], v[196:197], v[96:97], v[200:201]
	v_pk_fma_f32 v[74:75], v[86:87], s[26:27], v[74:75] op_sel_hi:[1,0,1]
	v_pk_fma_f32 v[72:73], v[84:85], s[26:27], v[72:73] op_sel_hi:[1,0,1]
	global_store_dwordx4 v[82:83], v[72:75], off offset:16
	v_cvt_pk_bf16_f32 v94, v72, v73
	v_cvt_pk_bf16_f32 v95, v74, v75
	flat_store_dwordx4 v[100:101], v[92:95]
	global_load_dwordx4 v[88:91], v[120:121], off
	s_nop 0
	global_load_dwordx4 v[92:95], v[122:123], off
	global_load_dwordx4 v[196:199], v[124:125], off
	global_load_dwordx4 v[200:203], v[126:127], off
	s_waitcnt vmcnt(0)
	v_sub_f32_e32 v85, v205, v103
	v_sub_f32_e32 v84, v204, v103
	v_sub_f32_e32 v87, v207, v103
	v_sub_f32_e32 v86, v206, v103
	v_pk_mul_f32 v[86:87], v[102:103], v[86:87] op_sel_hi:[0,1]
	v_pk_mul_f32 v[84:85], v[102:103], v[84:85] op_sel_hi:[0,1]
	v_pk_fma_f32 v[84:85], v[88:89], v[84:85], v[92:93]
	v_pk_fma_f32 v[86:87], v[90:91], v[86:87], v[94:95]
	v_pk_fma_f32 v[68:69], v[84:85], s[26:27], v[68:69] op_sel_hi:[1,0,1]
	v_pk_fma_f32 v[70:71], v[86:87], s[26:27], v[70:71] op_sel_hi:[1,0,1]
	global_store_dwordx4 v[82:83], v[68:71], off offset:512
	v_add_f32_e32 v92, v76, v77
	v_mul_f32_e32 v77, v77, v77
	v_fmac_f32_e32 v77, v76, v76
	v_add_f32_e32 v92, v78, v92
	v_fmac_f32_e32 v77, v78, v78
	v_add_f32_e32 v78, v72, v73
	v_mul_f32_e32 v73, v73, v73
	v_fmac_f32_e32 v73, v72, v72
	v_add_f32_e32 v76, v79, v92
	v_add_f32_e32 v78, v74, v78
	v_fmac_f32_e32 v73, v74, v74
	v_add_f32_e32 v76, 0, v76
	v_fmac_f32_e32 v77, v79, v79
	v_add_f32_e32 v72, v75, v78
	v_fmac_f32_e32 v73, v75, v75
	v_add_f32_e32 v76, v72, v76
	v_add_f32_e32 v77, v77, v73
	v_sub_f32_e32 v73, v209, v103
	v_sub_f32_e32 v72, v208, v103
	v_pk_mul_f32 v[72:73], v[102:103], v[72:73] op_sel_hi:[0,1]
	v_sub_f32_e32 v75, v211, v103
	v_sub_f32_e32 v74, v210, v103
	v_pk_mul_f32 v[74:75], v[102:103], v[74:75] op_sel_hi:[0,1]
	v_mul_f32_e32 v79, v69, v69
	v_add_f32_e32 v78, v68, v69
	v_fmac_f32_e32 v79, v68, v68
	v_add_f32_e32 v78, v70, v78
	v_fmac_f32_e32 v79, v70, v70
	v_add_f32_e32 v78, v71, v78
	v_fmac_f32_e32 v79, v71, v71
	v_add_f32_e32 v76, v76, v78
	v_add_f32_e32 v77, v77, v79
	v_cvt_pk_bf16_f32 v68, v68, v69
	v_cvt_pk_bf16_f32 v69, v70, v71
	v_pk_fma_f32 v[72:73], v[196:197], v[72:73], v[200:201]
	s_nop 0
	v_pk_fma_f32 v[72:73], v[72:73], s[26:27], v[64:65] op_sel_hi:[1,0,1]
	v_pk_fma_f32 v[74:75], v[198:199], v[74:75], v[202:203]
	v_mul_f32_e32 v65, v73, v73
	v_pk_fma_f32 v[74:75], v[74:75], s[26:27], v[66:67] op_sel_hi:[1,0,1]
	v_add_f32_e32 v64, v72, v73
	v_fmac_f32_e32 v65, v72, v72
	v_add_f32_e32 v64, v74, v64
	v_fmac_f32_e32 v65, v74, v74
	v_add_f32_e32 v64, v75, v64
	v_fmac_f32_e32 v65, v75, v75
	v_add_f32_e32 v64, v76, v64
	v_add_f32_e32 v65, v77, v65
	ds_bpermute_b32 v66, v116, v64
	ds_bpermute_b32 v67, v116, v65
	global_store_dwordx4 v[82:83], v[72:75], off offset:528
	v_cvt_pk_bf16_f32 v70, v72, v73
	v_cvt_pk_bf16_f32 v71, v74, v75
	s_waitcnt lgkmcnt(0)
	v_add_f32_e32 v64, v64, v66
	v_add_f32_e32 v65, v65, v67
	ds_bpermute_b32 v66, v117, v64
	ds_bpermute_b32 v67, v117, v65
	flat_store_dwordx4 v[100:101], v[68:71] offset:256
	s_and_saveexec_b64 s[30:31], s[2:3]
	s_cbranch_execz .LBB0_1546
	v_lshl_add_u64 v[68:69], s[10:11], 0, v[80:81]
	s_waitcnt lgkmcnt(0)
	v_add_f32_e32 v64, v64, v66
	v_add_f32_e32 v65, v65, v67
	flat_atomic_add_f32 v[68:69], v64
	flat_atomic_add_f32 v[68:69], v65 offset:4
; DEVI unsigned pk2(float lo, float hi) { unsigned r; asm("v_cvt_pk_bf16_f32 %0, %1, %2" : "=v"(r) : "v"(lo), "v"(hi)); return r; }
; DEVI void row_stats(const float* stats, int row, float& mu, float& rs) {
;     if (stats) { const float2 st = *(const float2*)(stats + 2 * (size_t)row); mu = st.x * (1.0f / 1024.0f); const float var = st.y * (1.0f / 1024.0f) - mu * mu; rs = rsqrtf(fmaxf(var, 0.f) + LN_EPS); }
;     else { mu = 0.f; rs = 1.f; }
;     DEVI void operator()(const f32x4 (&acc)[2][2][4][2], const pg8::Unit& u, int wr, int wc, int fr, int fq) const {
;     ...
;                 const int row = row0 + ai * 128 + m * 16; float mu, rs; row_stats(stin, row, mu, rs);
;                 float sum = 0.f, sq = 0.f;
; #pragma unroll
;                 for (int bj = 0; bj < 2; ++bj) {
;                     f32x4 z[2];
; #pragma unroll
;                     for (int n = 0; n < 2; ++n) {
;                         const int col = colb + bj * 128 + 4 * n;
;                         f32x4 xv = *(const f32x4*)(zsrc + (size_t)row * DM + col);
;                         if (stin) { const f32x4 gv = *(const f32x4*)(gin + col), bv = *(const f32x4*)(bin + col); xv = (xv - mu) * rs * gv + bv; }
;                         f32x4 zz = ALPHA * xv + acc[ai][bj][m][n];
;                         if (bias) zz += *(const f32x4*)(bias + col);
;                         *(f32x4*)(zdst + (size_t)row * DM + col) = zz;
;                         sum += zz[0] + zz[1] + zz[2] + zz[3]; sq += zz[0] * zz[0] + zz[1] * zz[1] + zz[2] * zz[2] + zz[3] * zz[3];
;                         z[n] = zz;
;                     }
;                     u32x4 o; o.x = pk2(z[0][0], z[0][1]); o.y = pk2(z[0][2], z[0][3]); o.z = pk2(z[1][0], z[1][1]); o.w = pk2(z[1][2], z[1][3]);
;                     if (zb) *(u32x4*)(zb + (size_t)row * DM + colb + bj * 128) = o;
;                 }
;                 sum += __shfl_xor(sum, 16); sq += __shfl_xor(sq, 16);
;                 sum += __shfl_xor(sum, 32); sq += __shfl_xor(sq, 32);
;                 if (fq == 0) { atomicAdd(stout + 2 * (size_t)row, sum); atomicAdd(stout + 2 * (size_t)row + 1, sq); }
.LBB0_1546:
	s_or_b64 exec, exec, s[30:31]
	v_add_u32_e32 v84, 0x80, v154
	v_ashrrev_i32_e32 v85, 31, v84
	v_lshlrev_b64 v[64:65], 3, v[84:85]
	s_waitcnt lgkmcnt(0)
	v_lshl_add_u64 v[66:67], s[12:13], 0, v[64:65]
	flat_load_dwordx2 v[86:87], v[66:67]
	v_lshlrev_b64 v[66:67], 12, v[84:85]
	v_lshl_add_u64 v[66:67], s[46:47], 0, v[66:67]
	v_lshl_add_u64 v[66:67], v[144:145], 2, v[66:67]
	global_load_dwordx4 v[68:71], v[66:67], off
	global_load_dwordx4 v[72:75], v[150:151], off
	global_load_dwordx4 v[76:79], v[152:153], off
	global_load_dwordx4 v[80:83], v[66:67], off offset:16
	global_load_dwordx4 v[196:199], v[146:147], off
	global_load_dwordx4 v[200:203], v[148:149], off
	global_load_dwordx4 v[204:207], v[66:67], off offset:512
	global_load_dwordx4 v[208:211], v[66:67], off offset:528
	s_waitcnt vmcnt(0) lgkmcnt(0)
	v_pk_mul_f32 v[86:87], v[86:87], s[24:25] op_sel:[1,0] op_sel_hi:[0,0]
	v_fma_f32 v86, -v87, v87, v86
	v_max_f32_e32 v86, 0, v86
	v_add_f32_e32 v86, 0x3727c5ac, v86
	v_mul_f32_e32 v88, 0x4b800000, v86
	v_cmp_gt_f32_e32 vcc, s61, v86
	v_sub_f32_e32 v69, v69, v87
	v_sub_f32_e32 v68, v68, v87
	v_cndmask_b32_e32 v86, v86, v88, vcc
	v_rsq_f32_e32 v86, v86
	v_sub_f32_e32 v71, v71, v87
	v_sub_f32_e32 v70, v70, v87
	v_mul_f32_e32 v88, 0x45800000, v86
	v_cndmask_b32_e32 v86, v86, v88, vcc
	v_pk_mul_f32 v[70:71], v[70:71], v[86:87] op_sel_hi:[1,0]
	v_pk_mul_f32 v[68:69], v[68:69], v[86:87] op_sel_hi:[1,0]
	v_pk_fma_f32 v[70:71], v[74:75], v[70:71], v[78:79]
	v_pk_fma_f32 v[68:69], v[72:73], v[68:69], v[76:77]
	v_pk_fma_f32 v[62:63], v[70:71], s[26:27], v[62:63] op_sel_hi:[1,0,1]
	v_pk_fma_f32 v[60:61], v[68:69], s[26:27], v[60:61] op_sel_hi:[1,0,1]
	global_store_dwordx4 v[66:67], v[60:63], off
	v_lshlrev_b64 v[76:77], 11, v[84:85]
	v_lshl_add_u64 v[76:77], s[14:15], 0, v[76:77]
	v_lshl_add_u64 v[84:85], v[144:145], 1, v[76:77]
	v_sub_f32_e32 v77, v81, v87
	v_sub_f32_e32 v76, v80, v87
	v_sub_f32_e32 v79, v83, v87
	v_sub_f32_e32 v78, v82, v87
	v_pk_mul_f32 v[78:79], v[78:79], v[86:87] op_sel_hi:[1,0]
	v_pk_mul_f32 v[80:81], v[76:77], v[86:87] op_sel_hi:[1,0]
	v_cvt_pk_bf16_f32 v76, v60, v61
	v_cvt_pk_bf16_f32 v77, v62, v63
	v_pk_fma_f32 v[70:71], v[198:199], v[78:79], v[202:203]
	v_pk_fma_f32 v[68:69], v[196:197], v[80:81], v[200:201]
	v_pk_fma_f32 v[58:59], v[70:71], s[26:27], v[58:59] op_sel_hi:[1,0,1]
	v_pk_fma_f32 v[56:57], v[68:69], s[26:27], v[56:57] op_sel_hi:[1,0,1]
	global_store_dwordx4 v[66:67], v[56:59], off offset:16
	v_cvt_pk_bf16_f32 v78, v56, v57
	v_cvt_pk_bf16_f32 v79, v58, v59
	flat_store_dwordx4 v[84:85], v[76:79]
	global_load_dwordx4 v[72:75], v[120:121], off
	s_nop 0
	global_load_dwordx4 v[76:79], v[122:123], off
	global_load_dwordx4 v[196:199], v[124:125], off
	global_load_dwordx4 v[200:203], v[126:127], off
	s_waitcnt vmcnt(0)
	v_sub_f32_e32 v69, v205, v87
	v_sub_f32_e32 v68, v204, v87
	v_sub_f32_e32 v71, v207, v87
	v_sub_f32_e32 v70, v206, v87
	v_pk_mul_f32 v[70:71], v[86:87], v[70:71] op_sel_hi:[0,1]
	v_pk_mul_f32 v[68:69], v[86:87], v[68:69] op_sel_hi:[0,1]
	v_pk_fma_f32 v[68:69], v[72:73], v[68:69], v[76:77]
	v_pk_fma_f32 v[70:71], v[74:75], v[70:71], v[78:79]
	v_pk_fma_f32 v[52:53], v[68:69], s[26:27], v[52:53] op_sel_hi:[1,0,1]
	v_pk_fma_f32 v[54:55], v[70:71], s[26:27], v[54:55] op_sel_hi:[1,0,1]
	global_store_dwordx4 v[66:67], v[52:55], off offset:512
	v_add_f32_e32 v76, v60, v61
	v_mul_f32_e32 v61, v61, v61
	v_fmac_f32_e32 v61, v60, v60
	v_add_f32_e32 v76, v62, v76
	v_fmac_f32_e32 v61, v62, v62
	v_add_f32_e32 v62, v56, v57
	v_mul_f32_e32 v57, v57, v57
	v_fmac_f32_e32 v57, v56, v56
	v_add_f32_e32 v60, v63, v76
	v_add_f32_e32 v62, v58, v62
	v_fmac_f32_e32 v57, v58, v58
	v_add_f32_e32 v60, 0, v60
	v_fmac_f32_e32 v61, v63, v63
	v_add_f32_e32 v56, v59, v62
	v_fmac_f32_e32 v57, v59, v59
	v_add_f32_e32 v60, v56, v60
	v_add_f32_e32 v61, v61, v57
	v_sub_f32_e32 v57, v209, v87
	v_sub_f32_e32 v56, v208, v87
	v_pk_mul_f32 v[56:57], v[86:87], v[56:57] op_sel_hi:[0,1]
	v_sub_f32_e32 v59, v211, v87
	v_sub_f32_e32 v58, v210, v87
	v_pk_mul_f32 v[58:59], v[86:87], v[58:59] op_sel_hi:[0,1]
	v_mul_f32_e32 v63, v53, v53
	v_add_f32_e32 v62, v52, v53
	v_fmac_f32_e32 v63, v52, v52
	v_add_f32_e32 v62, v54, v62
	v_fmac_f32_e32 v63, v54, v54
	v_add_f32_e32 v62, v55, v62
	v_fmac_f32_e32 v63, v55, v55
	v_add_f32_e32 v60, v60, v62
	v_add_f32_e32 v61, v61, v63
	v_cvt_pk_bf16_f32 v52, v52, v53
	v_cvt_pk_bf16_f32 v53, v54, v55
	v_pk_fma_f32 v[56:57], v[196:197], v[56:57], v[200:201]
	s_nop 0
	v_pk_fma_f32 v[56:57], v[56:57], s[26:27], v[48:49] op_sel_hi:[1,0,1]
	v_pk_fma_f32 v[58:59], v[198:199], v[58:59], v[202:203]
	v_mul_f32_e32 v49, v57, v57
	v_pk_fma_f32 v[58:59], v[58:59], s[26:27], v[50:51] op_sel_hi:[1,0,1]
	v_add_f32_e32 v48, v56, v57
	v_fmac_f32_e32 v49, v56, v56
	v_add_f32_e32 v48, v58, v48
	v_fmac_f32_e32 v49, v58, v58
	v_add_f32_e32 v48, v59, v48
	v_fmac_f32_e32 v49, v59, v59
	v_add_f32_e32 v48, v60, v48
	v_add_f32_e32 v49, v61, v49
	ds_bpermute_b32 v50, v116, v48
	ds_bpermute_b32 v51, v116, v49
	global_store_dwordx4 v[66:67], v[56:59], off offset:528
	v_cvt_pk_bf16_f32 v54, v56, v57
	v_cvt_pk_bf16_f32 v55, v58, v59
	s_waitcnt lgkmcnt(0)
	v_add_f32_e32 v48, v48, v50
	v_add_f32_e32 v49, v49, v51
	ds_bpermute_b32 v50, v117, v48
	ds_bpermute_b32 v51, v117, v49
	flat_store_dwordx4 v[84:85], v[52:55] offset:256
	s_and_saveexec_b64 s[30:31], s[2:3]
	s_cbranch_execz .LBB0_1548
	v_lshl_add_u64 v[52:53], s[10:11], 0, v[64:65]
	s_waitcnt lgkmcnt(0)
	v_add_f32_e32 v48, v48, v50
	v_add_f32_e32 v49, v49, v51
	flat_atomic_add_f32 v[52:53], v48
	flat_atomic_add_f32 v[52:53], v49 offset:4
; DEVI unsigned pk2(float lo, float hi) { unsigned r; asm("v_cvt_pk_bf16_f32 %0, %1, %2" : "=v"(r) : "v"(lo), "v"(hi)); return r; }
; DEVI void row_stats(const float* stats, int row, float& mu, float& rs) {
;     if (stats) { const float2 st = *(const float2*)(stats + 2 * (size_t)row); mu = st.x * (1.0f / 1024.0f); const float var = st.y * (1.0f / 1024.0f) - mu * mu; rs = rsqrtf(fmaxf(var, 0.f) + LN_EPS); }
;     else { mu = 0.f; rs = 1.f; }
;     DEVI void operator()(const f32x4 (&acc)[2][2][4][2], const pg8::Unit& u, int wr, int wc, int fr, int fq) const {
;     ...
;                 const int row = row0 + ai * 128 + m * 16; float mu, rs; row_stats(stin, row, mu, rs);
;                 float sum = 0.f, sq = 0.f;
; #pragma unroll
;                 for (int bj = 0; bj < 2; ++bj) {
;                     f32x4 z[2];
; #pragma unroll
;                     for (int n = 0; n < 2; ++n) {
;                         const int col = colb + bj * 128 + 4 * n;
;                         f32x4 xv = *(const f32x4*)(zsrc + (size_t)row * DM + col);
;                         if (stin) { const f32x4 gv = *(const f32x4*)(gin + col), bv = *(const f32x4*)(bin + col); xv = (xv - mu) * rs * gv + bv; }
;                         f32x4 zz = ALPHA * xv + acc[ai][bj][m][n];
;                         if (bias) zz += *(const f32x4*)(bias + col);
;                         *(f32x4*)(zdst + (size_t)row * DM + col) = zz;
;                         sum += zz[0] + zz[1] + zz[2] + zz[3]; sq += zz[0] * zz[0] + zz[1] * zz[1] + zz[2] * zz[2] + zz[3] * zz[3];
;                         z[n] = zz;
;                     }
;                     u32x4 o; o.x = pk2(z[0][0], z[0][1]); o.y = pk2(z[0][2], z[0][3]); o.z = pk2(z[1][0], z[1][1]); o.w = pk2(z[1][2], z[1][3]);
;                     if (zb) *(u32x4*)(zb + (size_t)row * DM + colb + bj * 128) = o;
;                 }
;                 sum += __shfl_xor(sum, 16); sq += __shfl_xor(sq, 16);
;                 sum += __shfl_xor(sum, 32); sq += __shfl_xor(sq, 32);
;                 if (fq == 0) { atomicAdd(stout + 2 * (size_t)row, sum); atomicAdd(stout + 2 * (size_t)row + 1, sq); }
.LBB0_1548:
	s_or_b64 exec, exec, s[30:31]
	v_add_u32_e32 v68, 0x90, v154
	v_ashrrev_i32_e32 v69, 31, v68
	v_lshlrev_b64 v[48:49], 3, v[68:69]
	s_waitcnt lgkmcnt(0)
	v_lshl_add_u64 v[50:51], s[12:13], 0, v[48:49]
	flat_load_dwordx2 v[70:71], v[50:51]
	v_lshlrev_b64 v[50:51], 12, v[68:69]
	v_lshl_add_u64 v[50:51], s[46:47], 0, v[50:51]
	v_lshl_add_u64 v[50:51], v[144:145], 2, v[50:51]
	global_load_dwordx4 v[52:55], v[50:51], off
	global_load_dwordx4 v[56:59], v[150:151], off
	global_load_dwordx4 v[60:63], v[152:153], off
	global_load_dwordx4 v[64:67], v[50:51], off offset:16
	global_load_dwordx4 v[196:199], v[146:147], off
	global_load_dwordx4 v[200:203], v[148:149], off
	global_load_dwordx4 v[204:207], v[50:51], off offset:512
	global_load_dwordx4 v[208:211], v[50:51], off offset:528
	s_waitcnt vmcnt(0) lgkmcnt(0)
	v_pk_mul_f32 v[70:71], v[70:71], s[24:25] op_sel:[1,0] op_sel_hi:[0,0]
	v_fma_f32 v70, -v71, v71, v70
	v_max_f32_e32 v70, 0, v70
	v_add_f32_e32 v70, 0x3727c5ac, v70
	v_mul_f32_e32 v72, 0x4b800000, v70
	v_cmp_gt_f32_e32 vcc, s61, v70
	v_sub_f32_e32 v53, v53, v71
	v_sub_f32_e32 v52, v52, v71
	v_cndmask_b32_e32 v70, v70, v72, vcc
	v_rsq_f32_e32 v70, v70
	v_sub_f32_e32 v55, v55, v71
	v_sub_f32_e32 v54, v54, v71
	v_mul_f32_e32 v72, 0x45800000, v70
	v_cndmask_b32_e32 v70, v70, v72, vcc
	v_pk_mul_f32 v[54:55], v[54:55], v[70:71] op_sel_hi:[1,0]
	v_pk_mul_f32 v[52:53], v[52:53], v[70:71] op_sel_hi:[1,0]
	v_pk_fma_f32 v[54:55], v[58:59], v[54:55], v[62:63]
	v_pk_fma_f32 v[52:53], v[56:57], v[52:53], v[60:61]
	v_pk_fma_f32 v[46:47], v[54:55], s[26:27], v[46:47] op_sel_hi:[1,0,1]
	v_pk_fma_f32 v[44:45], v[52:53], s[26:27], v[44:45] op_sel_hi:[1,0,1]
	global_store_dwordx4 v[50:51], v[44:47], off
	v_lshlrev_b64 v[60:61], 11, v[68:69]
	v_lshl_add_u64 v[60:61], s[14:15], 0, v[60:61]
	v_lshl_add_u64 v[68:69], v[144:145], 1, v[60:61]
	v_sub_f32_e32 v61, v65, v71
	v_sub_f32_e32 v60, v64, v71
	v_sub_f32_e32 v63, v67, v71
	v_sub_f32_e32 v62, v66, v71
	v_pk_mul_f32 v[62:63], v[62:63], v[70:71] op_sel_hi:[1,0]
	v_pk_mul_f32 v[64:65], v[60:61], v[70:71] op_sel_hi:[1,0]
	v_cvt_pk_bf16_f32 v60, v44, v45
	v_cvt_pk_bf16_f32 v61, v46, v47
	v_pk_fma_f32 v[54:55], v[198:199], v[62:63], v[202:203]
	v_pk_fma_f32 v[52:53], v[196:197], v[64:65], v[200:201]
	v_pk_fma_f32 v[42:43], v[54:55], s[26:27], v[42:43] op_sel_hi:[1,0,1]
	v_pk_fma_f32 v[40:41], v[52:53], s[26:27], v[40:41] op_sel_hi:[1,0,1]
	global_store_dwordx4 v[50:51], v[40:43], off offset:16
	v_cvt_pk_bf16_f32 v62, v40, v41
	v_cvt_pk_bf16_f32 v63, v42, v43
	flat_store_dwordx4 v[68:69], v[60:63]
	global_load_dwordx4 v[56:59], v[120:121], off
	s_nop 0
	global_load_dwordx4 v[60:63], v[122:123], off
	global_load_dwordx4 v[196:199], v[124:125], off
	global_load_dwordx4 v[200:203], v[126:127], off
	s_waitcnt vmcnt(0)
	v_sub_f32_e32 v53, v205, v71
	v_sub_f32_e32 v52, v204, v71
	v_sub_f32_e32 v55, v207, v71
	v_sub_f32_e32 v54, v206, v71
	v_pk_mul_f32 v[54:55], v[70:71], v[54:55] op_sel_hi:[0,1]
	v_pk_mul_f32 v[52:53], v[70:71], v[52:53] op_sel_hi:[0,1]
	v_pk_fma_f32 v[52:53], v[56:57], v[52:53], v[60:61]
	v_pk_fma_f32 v[54:55], v[58:59], v[54:55], v[62:63]
	v_pk_fma_f32 v[36:37], v[52:53], s[26:27], v[36:37] op_sel_hi:[1,0,1]
	v_pk_fma_f32 v[38:39], v[54:55], s[26:27], v[38:39] op_sel_hi:[1,0,1]
	global_store_dwordx4 v[50:51], v[36:39], off offset:512
	v_add_f32_e32 v60, v44, v45
	v_mul_f32_e32 v45, v45, v45
	v_fmac_f32_e32 v45, v44, v44
	v_add_f32_e32 v60, v46, v60
	v_fmac_f32_e32 v45, v46, v46
	v_add_f32_e32 v46, v40, v41
	v_mul_f32_e32 v41, v41, v41
	v_fmac_f32_e32 v41, v40, v40
	v_add_f32_e32 v44, v47, v60
	v_add_f32_e32 v46, v42, v46
	v_fmac_f32_e32 v41, v42, v42
	v_add_f32_e32 v44, 0, v44
	v_fmac_f32_e32 v45, v47, v47
	v_add_f32_e32 v40, v43, v46
	v_fmac_f32_e32 v41, v43, v43
	v_add_f32_e32 v44, v40, v44
	v_add_f32_e32 v45, v45, v41
	v_sub_f32_e32 v41, v209, v71
	v_sub_f32_e32 v40, v208, v71
	v_pk_mul_f32 v[40:41], v[70:71], v[40:41] op_sel_hi:[0,1]
	v_sub_f32_e32 v43, v211, v71
	v_sub_f32_e32 v42, v210, v71
	v_pk_mul_f32 v[42:43], v[70:71], v[42:43] op_sel_hi:[0,1]
	v_mul_f32_e32 v47, v37, v37
	v_add_f32_e32 v46, v36, v37
	v_fmac_f32_e32 v47, v36, v36
	v_add_f32_e32 v46, v38, v46
	v_fmac_f32_e32 v47, v38, v38
	v_add_f32_e32 v46, v39, v46
	v_fmac_f32_e32 v47, v39, v39
	v_add_f32_e32 v44, v44, v46
	v_add_f32_e32 v45, v45, v47
	v_cvt_pk_bf16_f32 v36, v36, v37
	v_cvt_pk_bf16_f32 v37, v38, v39
	v_pk_fma_f32 v[40:41], v[196:197], v[40:41], v[200:201]
	s_nop 0
	v_pk_fma_f32 v[40:41], v[40:41], s[26:27], v[32:33] op_sel_hi:[1,0,1]
	v_pk_fma_f32 v[42:43], v[198:199], v[42:43], v[202:203]
	v_mul_f32_e32 v33, v41, v41
	v_pk_fma_f32 v[42:43], v[42:43], s[26:27], v[34:35] op_sel_hi:[1,0,1]
	v_add_f32_e32 v32, v40, v41
	v_fmac_f32_e32 v33, v40, v40
	v_add_f32_e32 v32, v42, v32
	v_fmac_f32_e32 v33, v42, v42
	v_add_f32_e32 v32, v43, v32
	v_fmac_f32_e32 v33, v43, v43
	v_add_f32_e32 v32, v44, v32
	v_add_f32_e32 v33, v45, v33
	ds_bpermute_b32 v34, v116, v32
	ds_bpermute_b32 v35, v116, v33
	global_store_dwordx4 v[50:51], v[40:43], off offset:528
	v_cvt_pk_bf16_f32 v38, v40, v41
	v_cvt_pk_bf16_f32 v39, v42, v43
	s_waitcnt lgkmcnt(0)
	v_add_f32_e32 v32, v32, v34
	v_add_f32_e32 v33, v33, v35
	ds_bpermute_b32 v34, v117, v32
	ds_bpermute_b32 v35, v117, v33
	flat_store_dwordx4 v[68:69], v[36:39] offset:256
	s_and_saveexec_b64 s[30:31], s[2:3]
	s_cbranch_execz .LBB0_1550
	v_lshl_add_u64 v[36:37], s[10:11], 0, v[48:49]
	s_waitcnt lgkmcnt(0)
	v_add_f32_e32 v32, v32, v34
	v_add_f32_e32 v33, v33, v35
	flat_atomic_add_f32 v[36:37], v32
	flat_atomic_add_f32 v[36:37], v33 offset:4
; DEVI unsigned pk2(float lo, float hi) { unsigned r; asm("v_cvt_pk_bf16_f32 %0, %1, %2" : "=v"(r) : "v"(lo), "v"(hi)); return r; }
; DEVI void row_stats(const float* stats, int row, float& mu, float& rs) {
;     if (stats) { const float2 st = *(const float2*)(stats + 2 * (size_t)row); mu = st.x * (1.0f / 1024.0f); const float var = st.y * (1.0f / 1024.0f) - mu * mu; rs = rsqrtf(fmaxf(var, 0.f) + LN_EPS); }
;     else { mu = 0.f; rs = 1.f; }
;     DEVI void operator()(const f32x4 (&acc)[2][2][4][2], const pg8::Unit& u, int wr, int wc, int fr, int fq) const {
;     ...
;                 const int row = row0 + ai * 128 + m * 16; float mu, rs; row_stats(stin, row, mu, rs);
;                 float sum = 0.f, sq = 0.f;
; #pragma unroll
;                 for (int bj = 0; bj < 2; ++bj) {
;                     f32x4 z[2];
; #pragma unroll
;                     for (int n = 0; n < 2; ++n) {
;                         const int col = colb + bj * 128 + 4 * n;
;                         f32x4 xv = *(const f32x4*)(zsrc + (size_t)row * DM + col);
;                         if (stin) { const f32x4 gv = *(const f32x4*)(gin + col), bv = *(const f32x4*)(bin + col); xv = (xv - mu) * rs * gv + bv; }
;                         f32x4 zz = ALPHA * xv + acc[ai][bj][m][n];
;                         if (bias) zz += *(const f32x4*)(bias + col);
;                         *(f32x4*)(zdst + (size_t)row * DM + col) = zz;
;                         sum += zz[0] + zz[1] + zz[2] + zz[3]; sq += zz[0] * zz[0] + zz[1] * zz[1] + zz[2] * zz[2] + zz[3] * zz[3];
;                         z[n] = zz;
;                     }
;                     u32x4 o; o.x = pk2(z[0][0], z[0][1]); o.y = pk2(z[0][2], z[0][3]); o.z = pk2(z[1][0], z[1][1]); o.w = pk2(z[1][2], z[1][3]);
;                     if (zb) *(u32x4*)(zb + (size_t)row * DM + colb + bj * 128) = o;
;                 }
;                 sum += __shfl_xor(sum, 16); sq += __shfl_xor(sq, 16);
;                 sum += __shfl_xor(sum, 32); sq += __shfl_xor(sq, 32);
;                 if (fq == 0) { atomicAdd(stout + 2 * (size_t)row, sum); atomicAdd(stout + 2 * (size_t)row + 1, sq); }
.LBB0_1550:
	s_or_b64 exec, exec, s[30:31]
	v_add_u32_e32 v52, 0xa0, v154
	v_ashrrev_i32_e32 v53, 31, v52
	v_lshlrev_b64 v[32:33], 3, v[52:53]
	s_waitcnt lgkmcnt(0)
	v_lshl_add_u64 v[34:35], s[12:13], 0, v[32:33]
	flat_load_dwordx2 v[54:55], v[34:35]
	v_lshlrev_b64 v[34:35], 12, v[52:53]
	v_lshl_add_u64 v[34:35], s[46:47], 0, v[34:35]
	v_lshl_add_u64 v[34:35], v[144:145], 2, v[34:35]
	global_load_dwordx4 v[36:39], v[34:35], off
	global_load_dwordx4 v[40:43], v[150:151], off
	global_load_dwordx4 v[44:47], v[152:153], off
	global_load_dwordx4 v[48:51], v[34:35], off offset:16
	global_load_dwordx4 v[196:199], v[146:147], off
	global_load_dwordx4 v[200:203], v[148:149], off
	global_load_dwordx4 v[204:207], v[34:35], off offset:512
	global_load_dwordx4 v[208:211], v[34:35], off offset:528
	s_waitcnt vmcnt(0) lgkmcnt(0)
	v_pk_mul_f32 v[54:55], v[54:55], s[24:25] op_sel:[1,0] op_sel_hi:[0,0]
	v_fma_f32 v54, -v55, v55, v54
	v_max_f32_e32 v54, 0, v54
	v_add_f32_e32 v54, 0x3727c5ac, v54
	v_mul_f32_e32 v56, 0x4b800000, v54
	v_cmp_gt_f32_e32 vcc, s61, v54
	v_sub_f32_e32 v37, v37, v55
	v_sub_f32_e32 v36, v36, v55
	v_cndmask_b32_e32 v54, v54, v56, vcc
	v_rsq_f32_e32 v54, v54
	v_sub_f32_e32 v39, v39, v55
	v_sub_f32_e32 v38, v38, v55
	v_mul_f32_e32 v56, 0x45800000, v54
	v_cndmask_b32_e32 v54, v54, v56, vcc
	v_pk_mul_f32 v[38:39], v[38:39], v[54:55] op_sel_hi:[1,0]
	v_pk_mul_f32 v[36:37], v[36:37], v[54:55] op_sel_hi:[1,0]
	v_pk_fma_f32 v[38:39], v[42:43], v[38:39], v[46:47]
	v_pk_fma_f32 v[36:37], v[40:41], v[36:37], v[44:45]
	v_pk_fma_f32 v[30:31], v[38:39], s[26:27], v[30:31] op_sel_hi:[1,0,1]
	v_pk_fma_f32 v[28:29], v[36:37], s[26:27], v[28:29] op_sel_hi:[1,0,1]
	global_store_dwordx4 v[34:35], v[28:31], off
	v_lshlrev_b64 v[44:45], 11, v[52:53]
	v_lshl_add_u64 v[44:45], s[14:15], 0, v[44:45]
	v_lshl_add_u64 v[52:53], v[144:145], 1, v[44:45]
	v_sub_f32_e32 v45, v49, v55
	v_sub_f32_e32 v44, v48, v55
	v_sub_f32_e32 v47, v51, v55
	v_sub_f32_e32 v46, v50, v55
	v_pk_mul_f32 v[46:47], v[46:47], v[54:55] op_sel_hi:[1,0]
	v_pk_mul_f32 v[48:49], v[44:45], v[54:55] op_sel_hi:[1,0]
	v_cvt_pk_bf16_f32 v44, v28, v29
	v_cvt_pk_bf16_f32 v45, v30, v31
	v_pk_fma_f32 v[38:39], v[198:199], v[46:47], v[202:203]
	v_pk_fma_f32 v[36:37], v[196:197], v[48:49], v[200:201]
	v_pk_fma_f32 v[26:27], v[38:39], s[26:27], v[26:27] op_sel_hi:[1,0,1]
	v_pk_fma_f32 v[24:25], v[36:37], s[26:27], v[24:25] op_sel_hi:[1,0,1]
	global_store_dwordx4 v[34:35], v[24:27], off offset:16
	v_cvt_pk_bf16_f32 v46, v24, v25
	v_cvt_pk_bf16_f32 v47, v26, v27
	flat_store_dwordx4 v[52:53], v[44:47]
	global_load_dwordx4 v[40:43], v[120:121], off
	s_nop 0
	global_load_dwordx4 v[44:47], v[122:123], off
	global_load_dwordx4 v[196:199], v[124:125], off
	global_load_dwordx4 v[200:203], v[126:127], off
	s_waitcnt vmcnt(0)
	v_sub_f32_e32 v37, v205, v55
	v_sub_f32_e32 v36, v204, v55
	v_sub_f32_e32 v39, v207, v55
	v_sub_f32_e32 v38, v206, v55
	v_pk_mul_f32 v[38:39], v[54:55], v[38:39] op_sel_hi:[0,1]
	v_pk_mul_f32 v[36:37], v[54:55], v[36:37] op_sel_hi:[0,1]
	v_pk_fma_f32 v[36:37], v[40:41], v[36:37], v[44:45]
	v_pk_fma_f32 v[38:39], v[42:43], v[38:39], v[46:47]
	v_pk_fma_f32 v[20:21], v[36:37], s[26:27], v[20:21] op_sel_hi:[1,0,1]
	v_pk_fma_f32 v[22:23], v[38:39], s[26:27], v[22:23] op_sel_hi:[1,0,1]
	global_store_dwordx4 v[34:35], v[20:23], off offset:512
	v_add_f32_e32 v44, v28, v29
	v_mul_f32_e32 v29, v29, v29
	v_fmac_f32_e32 v29, v28, v28
	v_add_f32_e32 v44, v30, v44
	v_fmac_f32_e32 v29, v30, v30
	v_add_f32_e32 v30, v24, v25
	v_mul_f32_e32 v25, v25, v25
	v_fmac_f32_e32 v25, v24, v24
	v_add_f32_e32 v28, v31, v44
	v_add_f32_e32 v30, v26, v30
	v_fmac_f32_e32 v25, v26, v26
	v_add_f32_e32 v28, 0, v28
	v_fmac_f32_e32 v29, v31, v31
	v_add_f32_e32 v24, v27, v30
	v_fmac_f32_e32 v25, v27, v27
	v_add_f32_e32 v28, v24, v28
	v_add_f32_e32 v29, v29, v25
	v_sub_f32_e32 v25, v209, v55
	v_sub_f32_e32 v24, v208, v55
	v_pk_mul_f32 v[24:25], v[54:55], v[24:25] op_sel_hi:[0,1]
	v_sub_f32_e32 v27, v211, v55
	v_sub_f32_e32 v26, v210, v55
	v_pk_mul_f32 v[26:27], v[54:55], v[26:27] op_sel_hi:[0,1]
	v_mul_f32_e32 v31, v21, v21
	v_add_f32_e32 v30, v20, v21
	v_fmac_f32_e32 v31, v20, v20
	v_add_f32_e32 v30, v22, v30
	v_fmac_f32_e32 v31, v22, v22
	v_add_f32_e32 v30, v23, v30
	v_fmac_f32_e32 v31, v23, v23
	v_add_f32_e32 v28, v28, v30
	v_add_f32_e32 v29, v29, v31
	v_cvt_pk_bf16_f32 v20, v20, v21
	v_cvt_pk_bf16_f32 v21, v22, v23
	v_pk_fma_f32 v[24:25], v[196:197], v[24:25], v[200:201]
	s_nop 0
	v_pk_fma_f32 v[24:25], v[24:25], s[26:27], v[16:17] op_sel_hi:[1,0,1]
	v_pk_fma_f32 v[26:27], v[198:199], v[26:27], v[202:203]
	v_mul_f32_e32 v17, v25, v25
	v_pk_fma_f32 v[26:27], v[26:27], s[26:27], v[18:19] op_sel_hi:[1,0,1]
	v_add_f32_e32 v16, v24, v25
	v_fmac_f32_e32 v17, v24, v24
	v_add_f32_e32 v16, v26, v16
	v_fmac_f32_e32 v17, v26, v26
	v_add_f32_e32 v16, v27, v16
	v_fmac_f32_e32 v17, v27, v27
	v_add_f32_e32 v16, v28, v16
	v_add_f32_e32 v17, v29, v17
	ds_bpermute_b32 v18, v116, v16
	ds_bpermute_b32 v19, v116, v17
	global_store_dwordx4 v[34:35], v[24:27], off offset:528
	v_cvt_pk_bf16_f32 v22, v24, v25
	v_cvt_pk_bf16_f32 v23, v26, v27
	s_waitcnt lgkmcnt(0)
	v_add_f32_e32 v16, v16, v18
	v_add_f32_e32 v17, v17, v19
	ds_bpermute_b32 v18, v117, v16
	ds_bpermute_b32 v19, v117, v17
	flat_store_dwordx4 v[52:53], v[20:23] offset:256
	s_and_saveexec_b64 s[30:31], s[2:3]
	s_cbranch_execz .LBB0_1552
	v_lshl_add_u64 v[20:21], s[10:11], 0, v[32:33]
	s_waitcnt lgkmcnt(0)
	v_add_f32_e32 v16, v16, v18
	v_add_f32_e32 v17, v17, v19
	flat_atomic_add_f32 v[20:21], v16
	flat_atomic_add_f32 v[20:21], v17 offset:4
; DEVI unsigned pk2(float lo, float hi) { unsigned r; asm("v_cvt_pk_bf16_f32 %0, %1, %2" : "=v"(r) : "v"(lo), "v"(hi)); return r; }
; DEVI void row_stats(const float* stats, int row, float& mu, float& rs) {
;     if (stats) { const float2 st = *(const float2*)(stats + 2 * (size_t)row); mu = st.x * (1.0f / 1024.0f); const float var = st.y * (1.0f / 1024.0f) - mu * mu; rs = rsqrtf(fmaxf(var, 0.f) + LN_EPS); }
;     else { mu = 0.f; rs = 1.f; }
;     DEVI void operator()(const f32x4 (&acc)[2][2][4][2], const pg8::Unit& u, int wr, int wc, int fr, int fq) const {
;     ...
;                 const int row = row0 + ai * 128 + m * 16; float mu, rs; row_stats(stin, row, mu, rs);
;                 float sum = 0.f, sq = 0.f;
; #pragma unroll
;                 for (int bj = 0; bj < 2; ++bj) {
;                     f32x4 z[2];
; #pragma unroll
;                     for (int n = 0; n < 2; ++n) {
;                         const int col = colb + bj * 128 + 4 * n;
;                         f32x4 xv = *(const f32x4*)(zsrc + (size_t)row * DM + col);
;                         if (stin) { const f32x4 gv = *(const f32x4*)(gin + col), bv = *(const f32x4*)(bin + col); xv = (xv - mu) * rs * gv + bv; }
;                         f32x4 zz = ALPHA * xv + acc[ai][bj][m][n];
;                         if (bias) zz += *(const f32x4*)(bias + col);
;                         *(f32x4*)(zdst + (size_t)row * DM + col) = zz;
;                         sum += zz[0] + zz[1] + zz[2] + zz[3]; sq += zz[0] * zz[0] + zz[1] * zz[1] + zz[2] * zz[2] + zz[3] * zz[3];
;                         z[n] = zz;
;                     }
;                     u32x4 o; o.x = pk2(z[0][0], z[0][1]); o.y = pk2(z[0][2], z[0][3]); o.z = pk2(z[1][0], z[1][1]); o.w = pk2(z[1][2], z[1][3]);
;                     if (zb) *(u32x4*)(zb + (size_t)row * DM + colb + bj * 128) = o;
;                 }
;                 sum += __shfl_xor(sum, 16); sq += __shfl_xor(sq, 16);
;                 sum += __shfl_xor(sum, 32); sq += __shfl_xor(sq, 32);
;                 if (fq == 0) { atomicAdd(stout + 2 * (size_t)row, sum); atomicAdd(stout + 2 * (size_t)row + 1, sq); }
.LBB0_1552:
	s_or_b64 exec, exec, s[30:31]
	v_add_u32_e32 v36, 0xb0, v154
	v_ashrrev_i32_e32 v37, 31, v36
	v_lshlrev_b64 v[16:17], 3, v[36:37]
	s_waitcnt lgkmcnt(0)
	v_lshl_add_u64 v[18:19], s[12:13], 0, v[16:17]
	flat_load_dwordx2 v[38:39], v[18:19]
	v_lshlrev_b64 v[18:19], 12, v[36:37]
	v_lshl_add_u64 v[18:19], s[46:47], 0, v[18:19]
	v_lshl_add_u64 v[18:19], v[144:145], 2, v[18:19]
	global_load_dwordx4 v[20:23], v[18:19], off
	global_load_dwordx4 v[24:27], v[150:151], off
	global_load_dwordx4 v[28:31], v[152:153], off
	global_load_dwordx4 v[32:35], v[18:19], off offset:16
	global_load_dwordx4 v[196:199], v[146:147], off
	global_load_dwordx4 v[200:203], v[148:149], off
	global_load_dwordx4 v[204:207], v[18:19], off offset:512
	global_load_dwordx4 v[208:211], v[18:19], off offset:528
	s_waitcnt vmcnt(0) lgkmcnt(0)
	v_pk_mul_f32 v[38:39], v[38:39], s[24:25] op_sel:[1,0] op_sel_hi:[0,0]
	v_fma_f32 v38, -v39, v39, v38
	v_max_f32_e32 v38, 0, v38
	v_add_f32_e32 v38, 0x3727c5ac, v38
	v_mul_f32_e32 v40, 0x4b800000, v38
	v_cmp_gt_f32_e32 vcc, s61, v38
	v_sub_f32_e32 v21, v21, v39
	v_sub_f32_e32 v20, v20, v39
	v_cndmask_b32_e32 v38, v38, v40, vcc
	v_rsq_f32_e32 v38, v38
	v_sub_f32_e32 v23, v23, v39
	v_sub_f32_e32 v22, v22, v39
	v_mul_f32_e32 v40, 0x45800000, v38
	v_cndmask_b32_e32 v38, v38, v40, vcc
	v_pk_mul_f32 v[22:23], v[22:23], v[38:39] op_sel_hi:[1,0]
	v_pk_mul_f32 v[20:21], v[20:21], v[38:39] op_sel_hi:[1,0]
	v_pk_fma_f32 v[22:23], v[26:27], v[22:23], v[30:31]
	v_pk_fma_f32 v[20:21], v[24:25], v[20:21], v[28:29]
	v_pk_fma_f32 v[14:15], v[22:23], s[26:27], v[14:15] op_sel_hi:[1,0,1]
	v_pk_fma_f32 v[12:13], v[20:21], s[26:27], v[12:13] op_sel_hi:[1,0,1]
	global_store_dwordx4 v[18:19], v[12:15], off
	v_lshlrev_b64 v[28:29], 11, v[36:37]
	v_lshl_add_u64 v[28:29], s[14:15], 0, v[28:29]
	v_lshl_add_u64 v[36:37], v[144:145], 1, v[28:29]
	v_sub_f32_e32 v29, v33, v39
	v_sub_f32_e32 v28, v32, v39
	v_sub_f32_e32 v31, v35, v39
	v_sub_f32_e32 v30, v34, v39
	v_pk_mul_f32 v[30:31], v[30:31], v[38:39] op_sel_hi:[1,0]
	v_pk_mul_f32 v[32:33], v[28:29], v[38:39] op_sel_hi:[1,0]
	v_cvt_pk_bf16_f32 v28, v12, v13
	v_cvt_pk_bf16_f32 v29, v14, v15
	v_pk_fma_f32 v[22:23], v[198:199], v[30:31], v[202:203]
	v_pk_fma_f32 v[20:21], v[196:197], v[32:33], v[200:201]
	v_pk_fma_f32 v[10:11], v[22:23], s[26:27], v[10:11] op_sel_hi:[1,0,1]
	v_pk_fma_f32 v[8:9], v[20:21], s[26:27], v[8:9] op_sel_hi:[1,0,1]
	global_store_dwordx4 v[18:19], v[8:11], off offset:16
	v_cvt_pk_bf16_f32 v30, v8, v9
	v_cvt_pk_bf16_f32 v31, v10, v11
	flat_store_dwordx4 v[36:37], v[28:31]
	global_load_dwordx4 v[24:27], v[120:121], off
	s_nop 0
	global_load_dwordx4 v[28:31], v[122:123], off
	global_load_dwordx4 v[196:199], v[124:125], off
	global_load_dwordx4 v[200:203], v[126:127], off
	s_waitcnt vmcnt(0)
	v_sub_f32_e32 v21, v205, v39
	v_sub_f32_e32 v20, v204, v39
	v_sub_f32_e32 v23, v207, v39
	v_sub_f32_e32 v22, v206, v39
	v_pk_mul_f32 v[22:23], v[38:39], v[22:23] op_sel_hi:[0,1]
	v_pk_mul_f32 v[20:21], v[38:39], v[20:21] op_sel_hi:[0,1]
	v_pk_fma_f32 v[20:21], v[24:25], v[20:21], v[28:29]
	v_pk_fma_f32 v[22:23], v[26:27], v[22:23], v[30:31]
	v_pk_fma_f32 v[4:5], v[20:21], s[26:27], v[4:5] op_sel_hi:[1,0,1]
	v_pk_fma_f32 v[6:7], v[22:23], s[26:27], v[6:7] op_sel_hi:[1,0,1]
	global_store_dwordx4 v[18:19], v[4:7], off offset:512
	v_add_f32_e32 v28, v12, v13
	v_mul_f32_e32 v13, v13, v13
	v_fmac_f32_e32 v13, v12, v12
	v_add_f32_e32 v28, v14, v28
	v_fmac_f32_e32 v13, v14, v14
	v_add_f32_e32 v14, v8, v9
	v_mul_f32_e32 v9, v9, v9
	v_fmac_f32_e32 v9, v8, v8
	v_add_f32_e32 v12, v15, v28
	v_add_f32_e32 v14, v10, v14
	v_fmac_f32_e32 v9, v10, v10
	v_add_f32_e32 v12, 0, v12
	v_fmac_f32_e32 v13, v15, v15
	v_add_f32_e32 v8, v11, v14
	v_fmac_f32_e32 v9, v11, v11
	v_add_f32_e32 v12, v8, v12
	v_add_f32_e32 v13, v13, v9
	v_sub_f32_e32 v9, v209, v39
	v_sub_f32_e32 v8, v208, v39
	v_pk_mul_f32 v[8:9], v[38:39], v[8:9] op_sel_hi:[0,1]
	v_sub_f32_e32 v11, v211, v39
	v_sub_f32_e32 v10, v210, v39
	v_pk_mul_f32 v[10:11], v[38:39], v[10:11] op_sel_hi:[0,1]
	v_mul_f32_e32 v15, v5, v5
	v_add_f32_e32 v14, v4, v5
	v_fmac_f32_e32 v15, v4, v4
	v_add_f32_e32 v14, v6, v14
	v_fmac_f32_e32 v15, v6, v6
	v_add_f32_e32 v14, v7, v14
	v_fmac_f32_e32 v15, v7, v7
	v_add_f32_e32 v12, v12, v14
	v_add_f32_e32 v13, v13, v15
	v_cvt_pk_bf16_f32 v4, v4, v5
	v_cvt_pk_bf16_f32 v5, v6, v7
	v_pk_fma_f32 v[8:9], v[196:197], v[8:9], v[200:201]
	s_nop 0
	v_pk_fma_f32 v[8:9], v[8:9], s[26:27], v[0:1] op_sel_hi:[1,0,1]
	v_pk_fma_f32 v[10:11], v[198:199], v[10:11], v[202:203]
	v_mul_f32_e32 v1, v9, v9
	v_pk_fma_f32 v[10:11], v[10:11], s[26:27], v[2:3] op_sel_hi:[1,0,1]
	v_add_f32_e32 v0, v8, v9
	v_fmac_f32_e32 v1, v8, v8
	v_add_f32_e32 v0, v10, v0
	v_fmac_f32_e32 v1, v10, v10
	v_add_f32_e32 v0, v11, v0
	v_fmac_f32_e32 v1, v11, v11
	v_add_f32_e32 v0, v12, v0
	v_add_f32_e32 v1, v13, v1
	ds_bpermute_b32 v2, v116, v0
	ds_bpermute_b32 v3, v116, v1
	global_store_dwordx4 v[18:19], v[8:11], off offset:528
	v_cvt_pk_bf16_f32 v6, v8, v9
	v_cvt_pk_bf16_f32 v7, v10, v11
	s_waitcnt lgkmcnt(0)
	v_add_f32_e32 v0, v0, v2
	v_add_f32_e32 v1, v1, v3
	ds_bpermute_b32 v2, v117, v0
	ds_bpermute_b32 v3, v117, v1
	flat_store_dwordx4 v[36:37], v[4:7] offset:256
	s_and_saveexec_b64 s[30:31], s[2:3]
	s_cbranch_execz .LBB0_1554
	v_lshl_add_u64 v[4:5], s[10:11], 0, v[16:17]
	s_waitcnt lgkmcnt(0)
	v_add_f32_e32 v0, v0, v2
	v_add_f32_e32 v1, v1, v3
	flat_atomic_add_f32 v[4:5], v0
	flat_atomic_add_f32 v[4:5], v1 offset:4

; DEVI unsigned pk2(float lo, float hi) { unsigned r; asm("v_cvt_pk_bf16_f32 %0, %1, %2" : "=v"(r) : "v"(lo), "v"(hi)); return r; }
; DEVI void row_stats(const float* stats, int row, float& mu, float& rs) {
;     if (stats) { const float2 st = *(const float2*)(stats + 2 * (size_t)row); mu = st.x * (1.0f / 1024.0f); const float var = st.y * (1.0f / 1024.0f) - mu * mu; rs = rsqrtf(fmaxf(var, 0.f) + LN_EPS); }
;     else { mu = 0.f; rs = 1.f; }
;     DEVI void operator()(const f32x4 (&acc)[2][2][4][2], const pg8::Unit& u, int wr, int wc, int fr, int fq) const {
;     ...
;                 const int row = row0 + ai * 128 + m * 16; float mu, rs; row_stats(stin, row, mu, rs);
;                 float sum = 0.f, sq = 0.f;
; #pragma unroll
;                 for (int bj = 0; bj < 2; ++bj) {
;                     f32x4 z[2];
; #pragma unroll
;                     for (int n = 0; n < 2; ++n) {
;                         const int col = colb + bj * 128 + 4 * n;
;                         f32x4 xv = *(const f32x4*)(zsrc + (size_t)row * DM + col);
;                         if (stin) { const f32x4 gv = *(const f32x4*)(gin + col), bv = *(const f32x4*)(bin + col); xv = (xv - mu) * rs * gv + bv; }
;                         f32x4 zz = ALPHA * xv + acc[ai][bj][m][n];
;                         if (bias) zz += *(const f32x4*)(bias + col);
;                         *(f32x4*)(zdst + (size_t)row * DM + col) = zz;
;                         sum += zz[0] + zz[1] + zz[2] + zz[3]; sq += zz[0] * zz[0] + zz[1] * zz[1] + zz[2] * zz[2] + zz[3] * zz[3];
;                         z[n] = zz;
;                     }
;                     u32x4 o; o.x = pk2(z[0][0], z[0][1]); o.y = pk2(z[0][2], z[0][3]); o.z = pk2(z[1][0], z[1][1]); o.w = pk2(z[1][2], z[1][3]);
;                     if (zb) *(u32x4*)(zb + (size_t)row * DM + colb + bj * 128) = o;
;                 }
;                 sum += __shfl_xor(sum, 16); sq += __shfl_xor(sq, 16);
;                 sum += __shfl_xor(sum, 32); sq += __shfl_xor(sq, 32);
;                 if (fq == 0) { atomicAdd(stout + 2 * (size_t)row, sum); atomicAdd(stout + 2 * (size_t)row + 1, sq); }
.LBB0_2194:
	s_or_b64 exec, exec, s[30:31]
	v_or_b32_e32 v118, 16, v154
	v_ashrrev_i32_e32 v119, 31, v118
	v_lshlrev_b64 v[112:113], 3, v[118:119]
	s_waitcnt lgkmcnt(0)
	v_lshl_add_u64 v[114:115], s[12:13], 0, v[112:113]
	flat_load_dwordx2 v[160:161], v[114:115]
	v_lshlrev_b64 v[114:115], 12, v[118:119]
	v_lshl_add_u64 v[114:115], s[46:47], 0, v[114:115]
	v_lshl_add_u64 v[114:115], v[144:145], 2, v[114:115]
	global_load_dwordx4 v[156:159], v[114:115], off
	global_load_dwordx4 v[170:173], v[150:151], off
	global_load_dwordx4 v[174:177], v[152:153], off
	global_load_dwordx4 v[178:181], v[114:115], off offset:16
	v_lshlrev_b64 v[118:119], 11, v[118:119]
	v_lshl_add_u64 v[118:119], s[14:15], 0, v[118:119]
	v_lshl_add_u64 v[118:119], v[144:145], 1, v[118:119]
	global_load_dwordx4 v[196:199], v[146:147], off
	global_load_dwordx4 v[200:203], v[148:149], off
	global_load_dwordx4 v[204:207], v[114:115], off offset:512
	global_load_dwordx4 v[208:211], v[114:115], off offset:528
	s_waitcnt vmcnt(0) lgkmcnt(0)
	v_pk_mul_f32 v[160:161], v[160:161], s[24:25] op_sel:[1,0] op_sel_hi:[0,0]
	v_fma_f32 v155, -v161, v161, v160
	v_max_f32_e32 v155, 0, v155
	v_add_f32_e32 v155, 0x3727c5ac, v155
	v_mul_f32_e32 v160, 0x4b800000, v155
	v_cmp_gt_f32_e32 vcc, s61, v155
	v_sub_f32_e32 v157, v157, v161
	v_sub_f32_e32 v156, v156, v161
	v_cndmask_b32_e32 v155, v155, v160, vcc
	v_rsq_f32_e32 v155, v155
	v_sub_f32_e32 v159, v159, v161
	v_sub_f32_e32 v158, v158, v161
	v_mul_f32_e32 v160, 0x45800000, v155
	v_cndmask_b32_e32 v160, v155, v160, vcc
	v_pk_mul_f32 v[158:159], v[158:159], v[160:161] op_sel_hi:[1,0]
	v_pk_mul_f32 v[156:157], v[156:157], v[160:161] op_sel_hi:[1,0]
	v_pk_fma_f32 v[158:159], v[172:173], v[158:159], v[176:177]
	v_pk_fma_f32 v[156:157], v[170:171], v[156:157], v[174:175]
	v_pk_fma_f32 v[110:111], v[158:159], s[26:27], v[110:111] op_sel_hi:[1,0,1]
	v_pk_fma_f32 v[108:109], v[156:157], s[26:27], v[108:109] op_sel_hi:[1,0,1]
	global_store_dwordx4 v[114:115], v[108:111], off
	v_sub_f32_e32 v175, v179, v161
	v_sub_f32_e32 v174, v178, v161
	v_sub_f32_e32 v177, v181, v161
	v_sub_f32_e32 v176, v180, v161
	v_pk_mul_f32 v[176:177], v[176:177], v[160:161] op_sel_hi:[1,0]
	v_pk_mul_f32 v[178:179], v[174:175], v[160:161] op_sel_hi:[1,0]
	v_cvt_pk_bf16_f32 v174, v108, v109
	v_cvt_pk_bf16_f32 v175, v110, v111
	v_add_f32_e32 v155, v108, v109
	v_mul_f32_e32 v109, v109, v109
	v_fmac_f32_e32 v109, v108, v108
	v_add_f32_e32 v155, v110, v155
	v_fmac_f32_e32 v109, v110, v110
	v_add_f32_e32 v108, v111, v155
	v_add_f32_e32 v108, 0, v108
	v_fmac_f32_e32 v109, v111, v111
	v_pk_fma_f32 v[156:157], v[196:197], v[178:179], v[200:201]
	v_pk_fma_f32 v[158:159], v[198:199], v[176:177], v[202:203]
	v_pk_fma_f32 v[104:105], v[156:157], s[26:27], v[104:105] op_sel_hi:[1,0,1]
	v_pk_fma_f32 v[106:107], v[158:159], s[26:27], v[106:107] op_sel_hi:[1,0,1]
	global_store_dwordx4 v[114:115], v[104:107], off offset:16
	v_cvt_pk_bf16_f32 v176, v104, v105
	v_cvt_pk_bf16_f32 v177, v106, v107
	flat_store_dwordx4 v[118:119], v[174:177]
	global_load_dwordx4 v[170:173], v[120:121], off
	s_nop 0
	global_load_dwordx4 v[174:177], v[122:123], off
	v_add_f32_e32 v110, v104, v105
	v_mul_f32_e32 v105, v105, v105
	v_fmac_f32_e32 v105, v104, v104
	v_add_f32_e32 v110, v106, v110
	v_fmac_f32_e32 v105, v106, v106
	v_add_f32_e32 v104, v107, v110
	v_fmac_f32_e32 v105, v107, v107
	v_add_f32_e32 v108, v104, v108
	v_add_f32_e32 v109, v109, v105
	global_load_dwordx4 v[196:199], v[124:125], off
	global_load_dwordx4 v[200:203], v[126:127], off
	s_waitcnt vmcnt(0)
	v_sub_f32_e32 v157, v205, v161
	v_sub_f32_e32 v156, v204, v161
	v_sub_f32_e32 v159, v207, v161
	v_sub_f32_e32 v158, v206, v161
	v_pk_mul_f32 v[158:159], v[160:161], v[158:159] op_sel_hi:[0,1]
	v_pk_mul_f32 v[156:157], v[160:161], v[156:157] op_sel_hi:[0,1]
	v_pk_fma_f32 v[156:157], v[170:171], v[156:157], v[174:175]
	v_pk_fma_f32 v[158:159], v[172:173], v[158:159], v[176:177]
	v_pk_fma_f32 v[100:101], v[156:157], s[26:27], v[100:101] op_sel_hi:[1,0,1]
	v_pk_fma_f32 v[102:103], v[158:159], s[26:27], v[102:103] op_sel_hi:[1,0,1]
	global_store_dwordx4 v[114:115], v[100:103], off offset:512
	v_sub_f32_e32 v105, v209, v161
	v_sub_f32_e32 v104, v208, v161
	v_pk_mul_f32 v[104:105], v[160:161], v[104:105] op_sel_hi:[0,1]
	v_sub_f32_e32 v107, v211, v161
	v_sub_f32_e32 v106, v210, v161
	v_pk_mul_f32 v[106:107], v[160:161], v[106:107] op_sel_hi:[0,1]
	v_mul_f32_e32 v111, v101, v101
	v_add_f32_e32 v110, v100, v101
	v_fmac_f32_e32 v111, v100, v100
	v_add_f32_e32 v110, v102, v110
	v_fmac_f32_e32 v111, v102, v102
	v_add_f32_e32 v110, v103, v110
	v_fmac_f32_e32 v111, v103, v103
	v_add_f32_e32 v108, v108, v110
	v_add_f32_e32 v109, v109, v111
	v_cvt_pk_bf16_f32 v100, v100, v101
	v_cvt_pk_bf16_f32 v101, v102, v103
	v_pk_fma_f32 v[104:105], v[196:197], v[104:105], v[200:201]
	s_nop 0
	v_pk_fma_f32 v[104:105], v[104:105], s[26:27], v[96:97] op_sel_hi:[1,0,1]
	v_pk_fma_f32 v[106:107], v[198:199], v[106:107], v[202:203]
	v_mul_f32_e32 v97, v105, v105
	v_pk_fma_f32 v[106:107], v[106:107], s[26:27], v[98:99] op_sel_hi:[1,0,1]
	v_add_f32_e32 v96, v104, v105
	v_fmac_f32_e32 v97, v104, v104
	v_add_f32_e32 v96, v106, v96
	v_fmac_f32_e32 v97, v106, v106
	v_add_f32_e32 v96, v107, v96
	v_fmac_f32_e32 v97, v107, v107
	v_add_f32_e32 v96, v108, v96
	v_add_f32_e32 v97, v109, v97
	ds_bpermute_b32 v98, v116, v96
	ds_bpermute_b32 v99, v116, v97
	global_store_dwordx4 v[114:115], v[104:107], off offset:528
	v_cvt_pk_bf16_f32 v102, v104, v105
	v_cvt_pk_bf16_f32 v103, v106, v107
	s_waitcnt lgkmcnt(0)
	v_add_f32_e32 v96, v96, v98
	v_add_f32_e32 v97, v97, v99
	ds_bpermute_b32 v98, v117, v96
	ds_bpermute_b32 v99, v117, v97
	flat_store_dwordx4 v[118:119], v[100:103] offset:256
	s_and_saveexec_b64 s[30:31], s[2:3]
	s_cbranch_execz .LBB0_2196
	s_waitcnt lgkmcnt(0)
	v_add_f32_e32 v99, v97, v99
	v_add_f32_e32 v98, v96, v98
	v_lshl_add_u64 v[96:97], s[10:11], 0, v[112:113]
	flat_atomic_add_f32 v[96:97], v98
	flat_atomic_add_f32 v[96:97], v99 offset:4
; DEVI unsigned pk2(float lo, float hi) { unsigned r; asm("v_cvt_pk_bf16_f32 %0, %1, %2" : "=v"(r) : "v"(lo), "v"(hi)); return r; }
; DEVI void row_stats(const float* stats, int row, float& mu, float& rs) {
;     if (stats) { const float2 st = *(const float2*)(stats + 2 * (size_t)row); mu = st.x * (1.0f / 1024.0f); const float var = st.y * (1.0f / 1024.0f) - mu * mu; rs = rsqrtf(fmaxf(var, 0.f) + LN_EPS); }
;     else { mu = 0.f; rs = 1.f; }
;     DEVI void operator()(const f32x4 (&acc)[2][2][4][2], const pg8::Unit& u, int wr, int wc, int fr, int fq) const {
;     ...
;                 const int row = row0 + ai * 128 + m * 16; float mu, rs; row_stats(stin, row, mu, rs);
;                 float sum = 0.f, sq = 0.f;
; #pragma unroll
;                 for (int bj = 0; bj < 2; ++bj) {
;                     f32x4 z[2];
; #pragma unroll
;                     for (int n = 0; n < 2; ++n) {
;                         const int col = colb + bj * 128 + 4 * n;
;                         f32x4 xv = *(const f32x4*)(zsrc + (size_t)row * DM + col);
;                         if (stin) { const f32x4 gv = *(const f32x4*)(gin + col), bv = *(const f32x4*)(bin + col); xv = (xv - mu) * rs * gv + bv; }
;                         f32x4 zz = ALPHA * xv + acc[ai][bj][m][n];
;                         if (bias) zz += *(const f32x4*)(bias + col);
;                         *(f32x4*)(zdst + (size_t)row * DM + col) = zz;
;                         sum += zz[0] + zz[1] + zz[2] + zz[3]; sq += zz[0] * zz[0] + zz[1] * zz[1] + zz[2] * zz[2] + zz[3] * zz[3];
;                         z[n] = zz;
;                     }
;                     u32x4 o; o.x = pk2(z[0][0], z[0][1]); o.y = pk2(z[0][2], z[0][3]); o.z = pk2(z[1][0], z[1][1]); o.w = pk2(z[1][2], z[1][3]);
;                     if (zb) *(u32x4*)(zb + (size_t)row * DM + colb + bj * 128) = o;
;                 }
;                 sum += __shfl_xor(sum, 16); sq += __shfl_xor(sq, 16);
;                 sum += __shfl_xor(sum, 32); sq += __shfl_xor(sq, 32);
;                 if (fq == 0) { atomicAdd(stout + 2 * (size_t)row, sum); atomicAdd(stout + 2 * (size_t)row + 1, sq); }
.LBB0_2196:
	s_or_b64 exec, exec, s[30:31]
	v_or_b32_e32 v118, 32, v154
	v_ashrrev_i32_e32 v119, 31, v118
	v_lshlrev_b64 v[96:97], 3, v[118:119]
	s_waitcnt lgkmcnt(0)
	v_lshl_add_u64 v[98:99], s[12:13], 0, v[96:97]
	flat_load_dwordx2 v[156:157], v[98:99]
	v_lshlrev_b64 v[98:99], 12, v[118:119]
	v_lshl_add_u64 v[98:99], s[46:47], 0, v[98:99]
	v_lshl_add_u64 v[98:99], v[144:145], 2, v[98:99]
	global_load_dwordx4 v[100:103], v[98:99], off
	global_load_dwordx4 v[104:107], v[150:151], off
	global_load_dwordx4 v[108:111], v[152:153], off
	global_load_dwordx4 v[112:115], v[98:99], off offset:16
	global_load_dwordx4 v[196:199], v[146:147], off
	global_load_dwordx4 v[200:203], v[148:149], off
	global_load_dwordx4 v[204:207], v[98:99], off offset:512
	global_load_dwordx4 v[208:211], v[98:99], off offset:528
	s_waitcnt vmcnt(0) lgkmcnt(0)
	v_pk_mul_f32 v[156:157], v[156:157], s[24:25] op_sel:[1,0] op_sel_hi:[0,0]
	v_fma_f32 v155, -v157, v157, v156
	v_max_f32_e32 v155, 0, v155
	v_add_f32_e32 v155, 0x3727c5ac, v155
	v_mul_f32_e32 v156, 0x4b800000, v155
	v_cmp_gt_f32_e32 vcc, s61, v155
	v_sub_f32_e32 v101, v101, v157
	v_sub_f32_e32 v100, v100, v157
	v_cndmask_b32_e32 v155, v155, v156, vcc
	v_rsq_f32_e32 v155, v155
	v_sub_f32_e32 v103, v103, v157
	v_sub_f32_e32 v102, v102, v157
	v_mul_f32_e32 v156, 0x45800000, v155
	v_cndmask_b32_e32 v156, v155, v156, vcc
	v_pk_mul_f32 v[102:103], v[102:103], v[156:157] op_sel_hi:[1,0]
	v_pk_mul_f32 v[100:101], v[100:101], v[156:157] op_sel_hi:[1,0]
	v_pk_fma_f32 v[102:103], v[106:107], v[102:103], v[110:111]
	v_pk_fma_f32 v[100:101], v[104:105], v[100:101], v[108:109]
	v_pk_fma_f32 v[94:95], v[102:103], s[26:27], v[94:95] op_sel_hi:[1,0,1]
	v_pk_fma_f32 v[92:93], v[100:101], s[26:27], v[92:93] op_sel_hi:[1,0,1]
	global_store_dwordx4 v[98:99], v[92:95], off
	v_lshlrev_b64 v[108:109], 11, v[118:119]
	v_lshl_add_u64 v[108:109], s[14:15], 0, v[108:109]
	v_lshl_add_u64 v[118:119], v[144:145], 1, v[108:109]
	v_sub_f32_e32 v109, v113, v157
	v_sub_f32_e32 v108, v112, v157
	v_sub_f32_e32 v111, v115, v157
	v_sub_f32_e32 v110, v114, v157
	v_pk_mul_f32 v[110:111], v[110:111], v[156:157] op_sel_hi:[1,0]
	v_pk_mul_f32 v[112:113], v[108:109], v[156:157] op_sel_hi:[1,0]
	v_cvt_pk_bf16_f32 v108, v92, v93
	v_cvt_pk_bf16_f32 v109, v94, v95
	v_pk_fma_f32 v[102:103], v[198:199], v[110:111], v[202:203]
	v_pk_fma_f32 v[100:101], v[196:197], v[112:113], v[200:201]
	v_pk_fma_f32 v[90:91], v[102:103], s[26:27], v[90:91] op_sel_hi:[1,0,1]
	v_pk_fma_f32 v[88:89], v[100:101], s[26:27], v[88:89] op_sel_hi:[1,0,1]
	global_store_dwordx4 v[98:99], v[88:91], off offset:16
	v_cvt_pk_bf16_f32 v110, v88, v89
	v_cvt_pk_bf16_f32 v111, v90, v91
	flat_store_dwordx4 v[118:119], v[108:111]
	global_load_dwordx4 v[104:107], v[120:121], off
	s_nop 0
	global_load_dwordx4 v[108:111], v[122:123], off
	global_load_dwordx4 v[196:199], v[124:125], off
	global_load_dwordx4 v[200:203], v[126:127], off
	s_waitcnt vmcnt(0)
	v_sub_f32_e32 v101, v205, v157
	v_sub_f32_e32 v100, v204, v157
	v_sub_f32_e32 v103, v207, v157
	v_sub_f32_e32 v102, v206, v157
	v_pk_mul_f32 v[102:103], v[156:157], v[102:103] op_sel_hi:[0,1]
	v_pk_mul_f32 v[100:101], v[156:157], v[100:101] op_sel_hi:[0,1]
	v_pk_fma_f32 v[100:101], v[104:105], v[100:101], v[108:109]
	v_pk_fma_f32 v[102:103], v[106:107], v[102:103], v[110:111]
	v_pk_fma_f32 v[84:85], v[100:101], s[26:27], v[84:85] op_sel_hi:[1,0,1]
	v_pk_fma_f32 v[86:87], v[102:103], s[26:27], v[86:87] op_sel_hi:[1,0,1]
	global_store_dwordx4 v[98:99], v[84:87], off offset:512
	v_add_f32_e32 v108, v92, v93
	v_mul_f32_e32 v93, v93, v93
	v_fmac_f32_e32 v93, v92, v92
	v_add_f32_e32 v108, v94, v108
	v_fmac_f32_e32 v93, v94, v94
	v_add_f32_e32 v94, v88, v89
	v_mul_f32_e32 v89, v89, v89
	v_fmac_f32_e32 v89, v88, v88
	v_add_f32_e32 v92, v95, v108
	v_add_f32_e32 v94, v90, v94
	v_fmac_f32_e32 v89, v90, v90
	v_add_f32_e32 v92, 0, v92
	v_fmac_f32_e32 v93, v95, v95
	v_add_f32_e32 v88, v91, v94
	v_fmac_f32_e32 v89, v91, v91
	v_add_f32_e32 v92, v88, v92
	v_add_f32_e32 v93, v93, v89
	v_sub_f32_e32 v89, v209, v157
	v_sub_f32_e32 v88, v208, v157
	v_pk_mul_f32 v[88:89], v[156:157], v[88:89] op_sel_hi:[0,1]
	v_sub_f32_e32 v91, v211, v157
	v_sub_f32_e32 v90, v210, v157
	v_pk_mul_f32 v[90:91], v[156:157], v[90:91] op_sel_hi:[0,1]
	v_mul_f32_e32 v95, v85, v85
	v_add_f32_e32 v94, v84, v85
	v_fmac_f32_e32 v95, v84, v84
	v_add_f32_e32 v94, v86, v94
	v_fmac_f32_e32 v95, v86, v86
	v_add_f32_e32 v94, v87, v94
	v_fmac_f32_e32 v95, v87, v87
	v_add_f32_e32 v92, v92, v94
	v_add_f32_e32 v93, v93, v95
	v_cvt_pk_bf16_f32 v84, v84, v85
	v_cvt_pk_bf16_f32 v85, v86, v87
	v_pk_fma_f32 v[88:89], v[196:197], v[88:89], v[200:201]
	s_nop 0
	v_pk_fma_f32 v[88:89], v[88:89], s[26:27], v[80:81] op_sel_hi:[1,0,1]
	v_pk_fma_f32 v[90:91], v[198:199], v[90:91], v[202:203]
	v_mul_f32_e32 v81, v89, v89
	v_pk_fma_f32 v[90:91], v[90:91], s[26:27], v[82:83] op_sel_hi:[1,0,1]
	v_add_f32_e32 v80, v88, v89
	v_fmac_f32_e32 v81, v88, v88
	v_add_f32_e32 v80, v90, v80
	v_fmac_f32_e32 v81, v90, v90
	v_add_f32_e32 v80, v91, v80
	v_fmac_f32_e32 v81, v91, v91
	v_add_f32_e32 v80, v92, v80
	v_add_f32_e32 v81, v93, v81
	ds_bpermute_b32 v82, v116, v80
	ds_bpermute_b32 v83, v116, v81
	global_store_dwordx4 v[98:99], v[88:91], off offset:528
	v_cvt_pk_bf16_f32 v86, v88, v89
	v_cvt_pk_bf16_f32 v87, v90, v91
	s_waitcnt lgkmcnt(0)
	v_add_f32_e32 v80, v80, v82
	v_add_f32_e32 v81, v81, v83
	ds_bpermute_b32 v82, v117, v80
	ds_bpermute_b32 v83, v117, v81
	flat_store_dwordx4 v[118:119], v[84:87] offset:256
	s_and_saveexec_b64 s[30:31], s[2:3]
	s_cbranch_execz .LBB0_2198
	s_waitcnt lgkmcnt(0)
	v_add_f32_e32 v83, v81, v83
	v_add_f32_e32 v82, v80, v82
	v_lshl_add_u64 v[80:81], s[10:11], 0, v[96:97]
	flat_atomic_add_f32 v[80:81], v82
	flat_atomic_add_f32 v[80:81], v83 offset:4
; DEVI unsigned pk2(float lo, float hi) { unsigned r; asm("v_cvt_pk_bf16_f32 %0, %1, %2" : "=v"(r) : "v"(lo), "v"(hi)); return r; }
; DEVI void row_stats(const float* stats, int row, float& mu, float& rs) {
;     if (stats) { const float2 st = *(const float2*)(stats + 2 * (size_t)row); mu = st.x * (1.0f / 1024.0f); const float var = st.y * (1.0f / 1024.0f) - mu * mu; rs = rsqrtf(fmaxf(var, 0.f) + LN_EPS); }
;     else { mu = 0.f; rs = 1.f; }
;     DEVI void operator()(const f32x4 (&acc)[2][2][4][2], const pg8::Unit& u, int wr, int wc, int fr, int fq) const {
;     ...
;                 const int row = row0 + ai * 128 + m * 16; float mu, rs; row_stats(stin, row, mu, rs);
;                 float sum = 0.f, sq = 0.f;
; #pragma unroll
;                 for (int bj = 0; bj < 2; ++bj) {
;                     f32x4 z[2];
; #pragma unroll
;                     for (int n = 0; n < 2; ++n) {
;                         const int col = colb + bj * 128 + 4 * n;
;                         f32x4 xv = *(const f32x4*)(zsrc + (size_t)row * DM + col);
;                         if (stin) { const f32x4 gv = *(const f32x4*)(gin + col), bv = *(const f32x4*)(bin + col); xv = (xv - mu) * rs * gv + bv; }
;                         f32x4 zz = ALPHA * xv + acc[ai][bj][m][n];
;                         if (bias) zz += *(const f32x4*)(bias + col);
;                         *(f32x4*)(zdst + (size_t)row * DM + col) = zz;
;                         sum += zz[0] + zz[1] + zz[2] + zz[3]; sq += zz[0] * zz[0] + zz[1] * zz[1] + zz[2] * zz[2] + zz[3] * zz[3];
;                         z[n] = zz;
;                     }
;                     u32x4 o; o.x = pk2(z[0][0], z[0][1]); o.y = pk2(z[0][2], z[0][3]); o.z = pk2(z[1][0], z[1][1]); o.w = pk2(z[1][2], z[1][3]);
;                     if (zb) *(u32x4*)(zb + (size_t)row * DM + colb + bj * 128) = o;
;                 }
;                 sum += __shfl_xor(sum, 16); sq += __shfl_xor(sq, 16);
;                 sum += __shfl_xor(sum, 32); sq += __shfl_xor(sq, 32);
;                 if (fq == 0) { atomicAdd(stout + 2 * (size_t)row, sum); atomicAdd(stout + 2 * (size_t)row + 1, sq); }
.LBB0_2198:
	s_or_b64 exec, exec, s[30:31]
	v_or_b32_e32 v100, 48, v154
	v_ashrrev_i32_e32 v101, 31, v100
	v_lshlrev_b64 v[80:81], 3, v[100:101]
	s_waitcnt lgkmcnt(0)
	v_lshl_add_u64 v[82:83], s[12:13], 0, v[80:81]
	flat_load_dwordx2 v[102:103], v[82:83]
	v_lshlrev_b64 v[82:83], 12, v[100:101]
	v_lshl_add_u64 v[82:83], s[46:47], 0, v[82:83]
	v_lshl_add_u64 v[82:83], v[144:145], 2, v[82:83]
	global_load_dwordx4 v[84:87], v[82:83], off
	global_load_dwordx4 v[88:91], v[150:151], off
	global_load_dwordx4 v[92:95], v[152:153], off
	global_load_dwordx4 v[96:99], v[82:83], off offset:16
	global_load_dwordx4 v[196:199], v[146:147], off
	global_load_dwordx4 v[200:203], v[148:149], off
	global_load_dwordx4 v[204:207], v[82:83], off offset:512
	global_load_dwordx4 v[208:211], v[82:83], off offset:528
	s_waitcnt vmcnt(0) lgkmcnt(0)
	v_pk_mul_f32 v[102:103], v[102:103], s[24:25] op_sel:[1,0] op_sel_hi:[0,0]
	v_fma_f32 v102, -v103, v103, v102
	v_max_f32_e32 v102, 0, v102
	v_add_f32_e32 v102, 0x3727c5ac, v102
	v_mul_f32_e32 v104, 0x4b800000, v102
	v_cmp_gt_f32_e32 vcc, s61, v102
	v_sub_f32_e32 v85, v85, v103
	v_sub_f32_e32 v84, v84, v103
	v_cndmask_b32_e32 v102, v102, v104, vcc
	v_rsq_f32_e32 v102, v102
	v_sub_f32_e32 v87, v87, v103
	v_sub_f32_e32 v86, v86, v103
	v_mul_f32_e32 v104, 0x45800000, v102
	v_cndmask_b32_e32 v102, v102, v104, vcc
	v_pk_mul_f32 v[86:87], v[86:87], v[102:103] op_sel_hi:[1,0]
	v_pk_mul_f32 v[84:85], v[84:85], v[102:103] op_sel_hi:[1,0]
	v_pk_fma_f32 v[86:87], v[90:91], v[86:87], v[94:95]
	v_pk_fma_f32 v[84:85], v[88:89], v[84:85], v[92:93]
	v_pk_fma_f32 v[78:79], v[86:87], s[26:27], v[78:79] op_sel_hi:[1,0,1]
	v_pk_fma_f32 v[76:77], v[84:85], s[26:27], v[76:77] op_sel_hi:[1,0,1]
	global_store_dwordx4 v[82:83], v[76:79], off
	v_lshlrev_b64 v[92:93], 11, v[100:101]
	v_lshl_add_u64 v[92:93], s[14:15], 0, v[92:93]
	v_lshl_add_u64 v[100:101], v[144:145], 1, v[92:93]
	v_sub_f32_e32 v93, v97, v103
	v_sub_f32_e32 v92, v96, v103
	v_sub_f32_e32 v95, v99, v103
	v_sub_f32_e32 v94, v98, v103
	v_pk_mul_f32 v[94:95], v[94:95], v[102:103] op_sel_hi:[1,0]
	v_pk_mul_f32 v[96:97], v[92:93], v[102:103] op_sel_hi:[1,0]
	v_cvt_pk_bf16_f32 v92, v76, v77
	v_cvt_pk_bf16_f32 v93, v78, v79
	v_pk_fma_f32 v[86:87], v[198:199], v[94:95], v[202:203]
	v_pk_fma_f32 v[84:85], v[196:197], v[96:97], v[200:201]
	v_pk_fma_f32 v[74:75], v[86:87], s[26:27], v[74:75] op_sel_hi:[1,0,1]
	v_pk_fma_f32 v[72:73], v[84:85], s[26:27], v[72:73] op_sel_hi:[1,0,1]
	global_store_dwordx4 v[82:83], v[72:75], off offset:16
	v_cvt_pk_bf16_f32 v94, v72, v73
	v_cvt_pk_bf16_f32 v95, v74, v75
	flat_store_dwordx4 v[100:101], v[92:95]
	global_load_dwordx4 v[88:91], v[120:121], off
	s_nop 0
	global_load_dwordx4 v[92:95], v[122:123], off
	global_load_dwordx4 v[196:199], v[124:125], off
	global_load_dwordx4 v[200:203], v[126:127], off
	s_waitcnt vmcnt(0)
	v_sub_f32_e32 v85, v205, v103
	v_sub_f32_e32 v84, v204, v103
	v_sub_f32_e32 v87, v207, v103
	v_sub_f32_e32 v86, v206, v103
	v_pk_mul_f32 v[86:87], v[102:103], v[86:87] op_sel_hi:[0,1]
	v_pk_mul_f32 v[84:85], v[102:103], v[84:85] op_sel_hi:[0,1]
	v_pk_fma_f32 v[84:85], v[88:89], v[84:85], v[92:93]
	v_pk_fma_f32 v[86:87], v[90:91], v[86:87], v[94:95]
	v_pk_fma_f32 v[68:69], v[84:85], s[26:27], v[68:69] op_sel_hi:[1,0,1]
	v_pk_fma_f32 v[70:71], v[86:87], s[26:27], v[70:71] op_sel_hi:[1,0,1]
	global_store_dwordx4 v[82:83], v[68:71], off offset:512
	v_add_f32_e32 v92, v76, v77
	v_mul_f32_e32 v77, v77, v77
	v_fmac_f32_e32 v77, v76, v76
	v_add_f32_e32 v92, v78, v92
	v_fmac_f32_e32 v77, v78, v78
	v_add_f32_e32 v78, v72, v73
	v_mul_f32_e32 v73, v73, v73
	v_fmac_f32_e32 v73, v72, v72
	v_add_f32_e32 v76, v79, v92
	v_add_f32_e32 v78, v74, v78
	v_fmac_f32_e32 v73, v74, v74
	v_add_f32_e32 v76, 0, v76
	v_fmac_f32_e32 v77, v79, v79
	v_add_f32_e32 v72, v75, v78
	v_fmac_f32_e32 v73, v75, v75
	v_add_f32_e32 v76, v72, v76
	v_add_f32_e32 v77, v77, v73
	v_sub_f32_e32 v73, v209, v103
	v_sub_f32_e32 v72, v208, v103
	v_pk_mul_f32 v[72:73], v[102:103], v[72:73] op_sel_hi:[0,1]
	v_sub_f32_e32 v75, v211, v103
	v_sub_f32_e32 v74, v210, v103
	v_pk_mul_f32 v[74:75], v[102:103], v[74:75] op_sel_hi:[0,1]
	v_mul_f32_e32 v79, v69, v69
	v_add_f32_e32 v78, v68, v69
	v_fmac_f32_e32 v79, v68, v68
	v_add_f32_e32 v78, v70, v78
	v_fmac_f32_e32 v79, v70, v70
	v_add_f32_e32 v78, v71, v78
	v_fmac_f32_e32 v79, v71, v71
	v_add_f32_e32 v76, v76, v78
	v_add_f32_e32 v77, v77, v79
	v_cvt_pk_bf16_f32 v68, v68, v69
	v_cvt_pk_bf16_f32 v69, v70, v71
	v_pk_fma_f32 v[72:73], v[196:197], v[72:73], v[200:201]
	s_nop 0
	v_pk_fma_f32 v[72:73], v[72:73], s[26:27], v[64:65] op_sel_hi:[1,0,1]
	v_pk_fma_f32 v[74:75], v[198:199], v[74:75], v[202:203]
	v_mul_f32_e32 v65, v73, v73
	v_pk_fma_f32 v[74:75], v[74:75], s[26:27], v[66:67] op_sel_hi:[1,0,1]
	v_add_f32_e32 v64, v72, v73
	v_fmac_f32_e32 v65, v72, v72
	v_add_f32_e32 v64, v74, v64
	v_fmac_f32_e32 v65, v74, v74
	v_add_f32_e32 v64, v75, v64
	v_fmac_f32_e32 v65, v75, v75
	v_add_f32_e32 v64, v76, v64
	v_add_f32_e32 v65, v77, v65
	ds_bpermute_b32 v66, v116, v64
	ds_bpermute_b32 v67, v116, v65
	global_store_dwordx4 v[82:83], v[72:75], off offset:528
	v_cvt_pk_bf16_f32 v70, v72, v73
	v_cvt_pk_bf16_f32 v71, v74, v75
	s_waitcnt lgkmcnt(0)
	v_add_f32_e32 v64, v64, v66
	v_add_f32_e32 v65, v65, v67
	ds_bpermute_b32 v66, v117, v64
	ds_bpermute_b32 v67, v117, v65
	flat_store_dwordx4 v[100:101], v[68:71] offset:256
	s_and_saveexec_b64 s[30:31], s[2:3]
	s_cbranch_execz .LBB0_2200
	s_waitcnt lgkmcnt(0)
	v_add_f32_e32 v67, v65, v67
	v_add_f32_e32 v66, v64, v66
	v_lshl_add_u64 v[64:65], s[10:11], 0, v[80:81]
	flat_atomic_add_f32 v[64:65], v66
	flat_atomic_add_f32 v[64:65], v67 offset:4
; DEVI unsigned pk2(float lo, float hi) { unsigned r; asm("v_cvt_pk_bf16_f32 %0, %1, %2" : "=v"(r) : "v"(lo), "v"(hi)); return r; }
; DEVI void row_stats(const float* stats, int row, float& mu, float& rs) {
;     if (stats) { const float2 st = *(const float2*)(stats + 2 * (size_t)row); mu = st.x * (1.0f / 1024.0f); const float var = st.y * (1.0f / 1024.0f) - mu * mu; rs = rsqrtf(fmaxf(var, 0.f) + LN_EPS); }
;     else { mu = 0.f; rs = 1.f; }
;     DEVI void operator()(const f32x4 (&acc)[2][2][4][2], const pg8::Unit& u, int wr, int wc, int fr, int fq) const {
;     ...
;                 const int row = row0 + ai * 128 + m * 16; float mu, rs; row_stats(stin, row, mu, rs);
;                 float sum = 0.f, sq = 0.f;
; #pragma unroll
;                 for (int bj = 0; bj < 2; ++bj) {
;                     f32x4 z[2];
; #pragma unroll
;                     for (int n = 0; n < 2; ++n) {
;                         const int col = colb + bj * 128 + 4 * n;
;                         f32x4 xv = *(const f32x4*)(zsrc + (size_t)row * DM + col);
;                         if (stin) { const f32x4 gv = *(const f32x4*)(gin + col), bv = *(const f32x4*)(bin + col); xv = (xv - mu) * rs * gv + bv; }
;                         f32x4 zz = ALPHA * xv + acc[ai][bj][m][n];
;                         if (bias) zz += *(const f32x4*)(bias + col);
;                         *(f32x4*)(zdst + (size_t)row * DM + col) = zz;
;                         sum += zz[0] + zz[1] + zz[2] + zz[3]; sq += zz[0] * zz[0] + zz[1] * zz[1] + zz[2] * zz[2] + zz[3] * zz[3];
;                         z[n] = zz;
;                     }
;                     u32x4 o; o.x = pk2(z[0][0], z[0][1]); o.y = pk2(z[0][2], z[0][3]); o.z = pk2(z[1][0], z[1][1]); o.w = pk2(z[1][2], z[1][3]);
;                     if (zb) *(u32x4*)(zb + (size_t)row * DM + colb + bj * 128) = o;
;                 }
;                 sum += __shfl_xor(sum, 16); sq += __shfl_xor(sq, 16);
;                 sum += __shfl_xor(sum, 32); sq += __shfl_xor(sq, 32);
;                 if (fq == 0) { atomicAdd(stout + 2 * (size_t)row, sum); atomicAdd(stout + 2 * (size_t)row + 1, sq); }
.LBB0_2200:
	s_or_b64 exec, exec, s[30:31]
	v_add_u32_e32 v84, 0x80, v154
	v_ashrrev_i32_e32 v85, 31, v84
	v_lshlrev_b64 v[64:65], 3, v[84:85]
	s_waitcnt lgkmcnt(0)
	v_lshl_add_u64 v[66:67], s[12:13], 0, v[64:65]
	flat_load_dwordx2 v[86:87], v[66:67]
	v_lshlrev_b64 v[66:67], 12, v[84:85]
	v_lshl_add_u64 v[66:67], s[46:47], 0, v[66:67]
	v_lshl_add_u64 v[66:67], v[144:145], 2, v[66:67]
	global_load_dwordx4 v[68:71], v[66:67], off
	global_load_dwordx4 v[72:75], v[150:151], off
	global_load_dwordx4 v[76:79], v[152:153], off
	global_load_dwordx4 v[80:83], v[66:67], off offset:16
	global_load_dwordx4 v[196:199], v[146:147], off
	global_load_dwordx4 v[200:203], v[148:149], off
	global_load_dwordx4 v[204:207], v[66:67], off offset:512
	global_load_dwordx4 v[208:211], v[66:67], off offset:528
	s_waitcnt vmcnt(0) lgkmcnt(0)
	v_pk_mul_f32 v[86:87], v[86:87], s[24:25] op_sel:[1,0] op_sel_hi:[0,0]
	v_fma_f32 v86, -v87, v87, v86
	v_max_f32_e32 v86, 0, v86
	v_add_f32_e32 v86, 0x3727c5ac, v86
	v_mul_f32_e32 v88, 0x4b800000, v86
	v_cmp_gt_f32_e32 vcc, s61, v86
	v_sub_f32_e32 v69, v69, v87
	v_sub_f32_e32 v68, v68, v87
	v_cndmask_b32_e32 v86, v86, v88, vcc
	v_rsq_f32_e32 v86, v86
	v_sub_f32_e32 v71, v71, v87
	v_sub_f32_e32 v70, v70, v87
	v_mul_f32_e32 v88, 0x45800000, v86
	v_cndmask_b32_e32 v86, v86, v88, vcc
	v_pk_mul_f32 v[70:71], v[70:71], v[86:87] op_sel_hi:[1,0]
	v_pk_mul_f32 v[68:69], v[68:69], v[86:87] op_sel_hi:[1,0]
	v_pk_fma_f32 v[70:71], v[74:75], v[70:71], v[78:79]
	v_pk_fma_f32 v[68:69], v[72:73], v[68:69], v[76:77]
	v_pk_fma_f32 v[62:63], v[70:71], s[26:27], v[62:63] op_sel_hi:[1,0,1]
	v_pk_fma_f32 v[60:61], v[68:69], s[26:27], v[60:61] op_sel_hi:[1,0,1]
	global_store_dwordx4 v[66:67], v[60:63], off
	v_lshlrev_b64 v[76:77], 11, v[84:85]
	v_lshl_add_u64 v[76:77], s[14:15], 0, v[76:77]
	v_lshl_add_u64 v[84:85], v[144:145], 1, v[76:77]
	v_sub_f32_e32 v77, v81, v87
	v_sub_f32_e32 v76, v80, v87
	v_sub_f32_e32 v79, v83, v87
	v_sub_f32_e32 v78, v82, v87
	v_pk_mul_f32 v[78:79], v[78:79], v[86:87] op_sel_hi:[1,0]
	v_pk_mul_f32 v[80:81], v[76:77], v[86:87] op_sel_hi:[1,0]
	v_cvt_pk_bf16_f32 v76, v60, v61
	v_cvt_pk_bf16_f32 v77, v62, v63
	v_pk_fma_f32 v[70:71], v[198:199], v[78:79], v[202:203]
	v_pk_fma_f32 v[68:69], v[196:197], v[80:81], v[200:201]
	v_pk_fma_f32 v[58:59], v[70:71], s[26:27], v[58:59] op_sel_hi:[1,0,1]
	v_pk_fma_f32 v[56:57], v[68:69], s[26:27], v[56:57] op_sel_hi:[1,0,1]
	global_store_dwordx4 v[66:67], v[56:59], off offset:16
	v_cvt_pk_bf16_f32 v78, v56, v57
	v_cvt_pk_bf16_f32 v79, v58, v59
	flat_store_dwordx4 v[84:85], v[76:79]
	global_load_dwordx4 v[72:75], v[120:121], off
	s_nop 0
	global_load_dwordx4 v[76:79], v[122:123], off
	global_load_dwordx4 v[196:199], v[124:125], off
	global_load_dwordx4 v[200:203], v[126:127], off
	s_waitcnt vmcnt(0)
	v_sub_f32_e32 v69, v205, v87
	v_sub_f32_e32 v68, v204, v87
	v_sub_f32_e32 v71, v207, v87
	v_sub_f32_e32 v70, v206, v87
	v_pk_mul_f32 v[70:71], v[86:87], v[70:71] op_sel_hi:[0,1]
	v_pk_mul_f32 v[68:69], v[86:87], v[68:69] op_sel_hi:[0,1]
	v_pk_fma_f32 v[68:69], v[72:73], v[68:69], v[76:77]
	v_pk_fma_f32 v[70:71], v[74:75], v[70:71], v[78:79]
	v_pk_fma_f32 v[52:53], v[68:69], s[26:27], v[52:53] op_sel_hi:[1,0,1]
	v_pk_fma_f32 v[54:55], v[70:71], s[26:27], v[54:55] op_sel_hi:[1,0,1]
	global_store_dwordx4 v[66:67], v[52:55], off offset:512
	v_add_f32_e32 v76, v60, v61
	v_mul_f32_e32 v61, v61, v61
	v_fmac_f32_e32 v61, v60, v60
	v_add_f32_e32 v76, v62, v76
	v_fmac_f32_e32 v61, v62, v62
	v_add_f32_e32 v62, v56, v57
	v_mul_f32_e32 v57, v57, v57
	v_fmac_f32_e32 v57, v56, v56
	v_add_f32_e32 v60, v63, v76
	v_add_f32_e32 v62, v58, v62
	v_fmac_f32_e32 v57, v58, v58
	v_add_f32_e32 v60, 0, v60
	v_fmac_f32_e32 v61, v63, v63
	v_add_f32_e32 v56, v59, v62
	v_fmac_f32_e32 v57, v59, v59
	v_add_f32_e32 v60, v56, v60
	v_add_f32_e32 v61, v61, v57
	v_sub_f32_e32 v57, v209, v87
	v_sub_f32_e32 v56, v208, v87
	v_pk_mul_f32 v[56:57], v[86:87], v[56:57] op_sel_hi:[0,1]
	v_sub_f32_e32 v59, v211, v87
	v_sub_f32_e32 v58, v210, v87
	v_pk_mul_f32 v[58:59], v[86:87], v[58:59] op_sel_hi:[0,1]
	v_mul_f32_e32 v63, v53, v53
	v_add_f32_e32 v62, v52, v53
	v_fmac_f32_e32 v63, v52, v52
	v_add_f32_e32 v62, v54, v62
	v_fmac_f32_e32 v63, v54, v54
	v_add_f32_e32 v62, v55, v62
	v_fmac_f32_e32 v63, v55, v55
	v_add_f32_e32 v60, v60, v62
	v_add_f32_e32 v61, v61, v63
	v_cvt_pk_bf16_f32 v52, v52, v53
	v_cvt_pk_bf16_f32 v53, v54, v55
	v_pk_fma_f32 v[56:57], v[196:197], v[56:57], v[200:201]
	s_nop 0
	v_pk_fma_f32 v[56:57], v[56:57], s[26:27], v[48:49] op_sel_hi:[1,0,1]
	v_pk_fma_f32 v[58:59], v[198:199], v[58:59], v[202:203]
	v_mul_f32_e32 v49, v57, v57
	v_pk_fma_f32 v[58:59], v[58:59], s[26:27], v[50:51] op_sel_hi:[1,0,1]
	v_add_f32_e32 v48, v56, v57
	v_fmac_f32_e32 v49, v56, v56
	v_add_f32_e32 v48, v58, v48
	v_fmac_f32_e32 v49, v58, v58
	v_add_f32_e32 v48, v59, v48
	v_fmac_f32_e32 v49, v59, v59
	v_add_f32_e32 v48, v60, v48
	v_add_f32_e32 v49, v61, v49
	ds_bpermute_b32 v50, v116, v48
	ds_bpermute_b32 v51, v116, v49
	global_store_dwordx4 v[66:67], v[56:59], off offset:528
	v_cvt_pk_bf16_f32 v54, v56, v57
	v_cvt_pk_bf16_f32 v55, v58, v59
	s_waitcnt lgkmcnt(0)
	v_add_f32_e32 v48, v48, v50
	v_add_f32_e32 v49, v49, v51
	ds_bpermute_b32 v50, v117, v48
	ds_bpermute_b32 v51, v117, v49
	flat_store_dwordx4 v[84:85], v[52:55] offset:256
	s_and_saveexec_b64 s[30:31], s[2:3]
	s_cbranch_execz .LBB0_2202
	s_waitcnt lgkmcnt(0)
	v_add_f32_e32 v51, v49, v51
	v_add_f32_e32 v50, v48, v50
	v_lshl_add_u64 v[48:49], s[10:11], 0, v[64:65]
	flat_atomic_add_f32 v[48:49], v50
	flat_atomic_add_f32 v[48:49], v51 offset:4
; DEVI unsigned pk2(float lo, float hi) { unsigned r; asm("v_cvt_pk_bf16_f32 %0, %1, %2" : "=v"(r) : "v"(lo), "v"(hi)); return r; }
; DEVI void row_stats(const float* stats, int row, float& mu, float& rs) {
;     if (stats) { const float2 st = *(const float2*)(stats + 2 * (size_t)row); mu = st.x * (1.0f / 1024.0f); const float var = st.y * (1.0f / 1024.0f) - mu * mu; rs = rsqrtf(fmaxf(var, 0.f) + LN_EPS); }
;     else { mu = 0.f; rs = 1.f; }
;     DEVI void operator()(const f32x4 (&acc)[2][2][4][2], const pg8::Unit& u, int wr, int wc, int fr, int fq) const {
;     ...
;                 const int row = row0 + ai * 128 + m * 16; float mu, rs; row_stats(stin, row, mu, rs);
;                 float sum = 0.f, sq = 0.f;
; #pragma unroll
;                 for (int bj = 0; bj < 2; ++bj) {
;                     f32x4 z[2];
; #pragma unroll
;                     for (int n = 0; n < 2; ++n) {
;                         const int col = colb + bj * 128 + 4 * n;
;                         f32x4 xv = *(const f32x4*)(zsrc + (size_t)row * DM + col);
;                         if (stin) { const f32x4 gv = *(const f32x4*)(gin + col), bv = *(const f32x4*)(bin + col); xv = (xv - mu) * rs * gv + bv; }
;                         f32x4 zz = ALPHA * xv + acc[ai][bj][m][n];
;                         if (bias) zz += *(const f32x4*)(bias + col);
;                         *(f32x4*)(zdst + (size_t)row * DM + col) = zz;
;                         sum += zz[0] + zz[1] + zz[2] + zz[3]; sq += zz[0] * zz[0] + zz[1] * zz[1] + zz[2] * zz[2] + zz[3] * zz[3];
;                         z[n] = zz;
;                     }
;                     u32x4 o; o.x = pk2(z[0][0], z[0][1]); o.y = pk2(z[0][2], z[0][3]); o.z = pk2(z[1][0], z[1][1]); o.w = pk2(z[1][2], z[1][3]);
;                     if (zb) *(u32x4*)(zb + (size_t)row * DM + colb + bj * 128) = o;
;                 }
;                 sum += __shfl_xor(sum, 16); sq += __shfl_xor(sq, 16);
;                 sum += __shfl_xor(sum, 32); sq += __shfl_xor(sq, 32);
;                 if (fq == 0) { atomicAdd(stout + 2 * (size_t)row, sum); atomicAdd(stout + 2 * (size_t)row + 1, sq); }
.LBB0_2202:
	s_or_b64 exec, exec, s[30:31]
	v_add_u32_e32 v68, 0x90, v154
	v_ashrrev_i32_e32 v69, 31, v68
	v_lshlrev_b64 v[48:49], 3, v[68:69]
	s_waitcnt lgkmcnt(0)
	v_lshl_add_u64 v[50:51], s[12:13], 0, v[48:49]
	flat_load_dwordx2 v[70:71], v[50:51]
	v_lshlrev_b64 v[50:51], 12, v[68:69]
	v_lshl_add_u64 v[50:51], s[46:47], 0, v[50:51]
	v_lshl_add_u64 v[50:51], v[144:145], 2, v[50:51]
	global_load_dwordx4 v[52:55], v[50:51], off
	global_load_dwordx4 v[56:59], v[150:151], off
	global_load_dwordx4 v[60:63], v[152:153], off
	global_load_dwordx4 v[64:67], v[50:51], off offset:16
	global_load_dwordx4 v[196:199], v[146:147], off
	global_load_dwordx4 v[200:203], v[148:149], off
	global_load_dwordx4 v[204:207], v[50:51], off offset:512
	global_load_dwordx4 v[208:211], v[50:51], off offset:528
	s_waitcnt vmcnt(0) lgkmcnt(0)
	v_pk_mul_f32 v[70:71], v[70:71], s[24:25] op_sel:[1,0] op_sel_hi:[0,0]
	v_fma_f32 v70, -v71, v71, v70
	v_max_f32_e32 v70, 0, v70
	v_add_f32_e32 v70, 0x3727c5ac, v70
	v_mul_f32_e32 v72, 0x4b800000, v70
	v_cmp_gt_f32_e32 vcc, s61, v70
	v_sub_f32_e32 v53, v53, v71
	v_sub_f32_e32 v52, v52, v71
	v_cndmask_b32_e32 v70, v70, v72, vcc
	v_rsq_f32_e32 v70, v70
	v_sub_f32_e32 v55, v55, v71
	v_sub_f32_e32 v54, v54, v71
	v_mul_f32_e32 v72, 0x45800000, v70
	v_cndmask_b32_e32 v70, v70, v72, vcc
	v_pk_mul_f32 v[54:55], v[54:55], v[70:71] op_sel_hi:[1,0]
	v_pk_mul_f32 v[52:53], v[52:53], v[70:71] op_sel_hi:[1,0]
	v_pk_fma_f32 v[54:55], v[58:59], v[54:55], v[62:63]
	v_pk_fma_f32 v[52:53], v[56:57], v[52:53], v[60:61]
	v_pk_fma_f32 v[46:47], v[54:55], s[26:27], v[46:47] op_sel_hi:[1,0,1]
	v_pk_fma_f32 v[44:45], v[52:53], s[26:27], v[44:45] op_sel_hi:[1,0,1]
	global_store_dwordx4 v[50:51], v[44:47], off
	v_lshlrev_b64 v[60:61], 11, v[68:69]
	v_lshl_add_u64 v[60:61], s[14:15], 0, v[60:61]
	v_lshl_add_u64 v[68:69], v[144:145], 1, v[60:61]
	v_sub_f32_e32 v61, v65, v71
	v_sub_f32_e32 v60, v64, v71
	v_sub_f32_e32 v63, v67, v71
	v_sub_f32_e32 v62, v66, v71
	v_pk_mul_f32 v[62:63], v[62:63], v[70:71] op_sel_hi:[1,0]
	v_pk_mul_f32 v[64:65], v[60:61], v[70:71] op_sel_hi:[1,0]
	v_cvt_pk_bf16_f32 v60, v44, v45
	v_cvt_pk_bf16_f32 v61, v46, v47
	v_pk_fma_f32 v[54:55], v[198:199], v[62:63], v[202:203]
	v_pk_fma_f32 v[52:53], v[196:197], v[64:65], v[200:201]
	v_pk_fma_f32 v[42:43], v[54:55], s[26:27], v[42:43] op_sel_hi:[1,0,1]
	v_pk_fma_f32 v[40:41], v[52:53], s[26:27], v[40:41] op_sel_hi:[1,0,1]
	global_store_dwordx4 v[50:51], v[40:43], off offset:16
	v_cvt_pk_bf16_f32 v62, v40, v41
	v_cvt_pk_bf16_f32 v63, v42, v43
	flat_store_dwordx4 v[68:69], v[60:63]
	global_load_dwordx4 v[56:59], v[120:121], off
	s_nop 0
	global_load_dwordx4 v[60:63], v[122:123], off
	global_load_dwordx4 v[196:199], v[124:125], off
	global_load_dwordx4 v[200:203], v[126:127], off
	s_waitcnt vmcnt(0)
	v_sub_f32_e32 v53, v205, v71
	v_sub_f32_e32 v52, v204, v71
	v_sub_f32_e32 v55, v207, v71
	v_sub_f32_e32 v54, v206, v71
	v_pk_mul_f32 v[54:55], v[70:71], v[54:55] op_sel_hi:[0,1]
	v_pk_mul_f32 v[52:53], v[70:71], v[52:53] op_sel_hi:[0,1]
	v_pk_fma_f32 v[52:53], v[56:57], v[52:53], v[60:61]
	v_pk_fma_f32 v[54:55], v[58:59], v[54:55], v[62:63]
	v_pk_fma_f32 v[36:37], v[52:53], s[26:27], v[36:37] op_sel_hi:[1,0,1]
	v_pk_fma_f32 v[38:39], v[54:55], s[26:27], v[38:39] op_sel_hi:[1,0,1]
	global_store_dwordx4 v[50:51], v[36:39], off offset:512
	v_add_f32_e32 v60, v44, v45
	v_mul_f32_e32 v45, v45, v45
	v_fmac_f32_e32 v45, v44, v44
	v_add_f32_e32 v60, v46, v60
	v_fmac_f32_e32 v45, v46, v46
	v_add_f32_e32 v46, v40, v41
	v_mul_f32_e32 v41, v41, v41
	v_fmac_f32_e32 v41, v40, v40
	v_add_f32_e32 v44, v47, v60
	v_add_f32_e32 v46, v42, v46
	v_fmac_f32_e32 v41, v42, v42
	v_add_f32_e32 v44, 0, v44
	v_fmac_f32_e32 v45, v47, v47
	v_add_f32_e32 v40, v43, v46
	v_fmac_f32_e32 v41, v43, v43
	v_add_f32_e32 v44, v40, v44
	v_add_f32_e32 v45, v45, v41
	v_sub_f32_e32 v41, v209, v71
	v_sub_f32_e32 v40, v208, v71
	v_pk_mul_f32 v[40:41], v[70:71], v[40:41] op_sel_hi:[0,1]
	v_sub_f32_e32 v43, v211, v71
	v_sub_f32_e32 v42, v210, v71
	v_pk_mul_f32 v[42:43], v[70:71], v[42:43] op_sel_hi:[0,1]
	v_mul_f32_e32 v47, v37, v37
	v_add_f32_e32 v46, v36, v37
	v_fmac_f32_e32 v47, v36, v36
	v_add_f32_e32 v46, v38, v46
	v_fmac_f32_e32 v47, v38, v38
	v_add_f32_e32 v46, v39, v46
	v_fmac_f32_e32 v47, v39, v39
	v_add_f32_e32 v44, v44, v46
	v_add_f32_e32 v45, v45, v47
	v_cvt_pk_bf16_f32 v36, v36, v37
	v_cvt_pk_bf16_f32 v37, v38, v39
	v_pk_fma_f32 v[40:41], v[196:197], v[40:41], v[200:201]
	s_nop 0
	v_pk_fma_f32 v[40:41], v[40:41], s[26:27], v[32:33] op_sel_hi:[1,0,1]
	v_pk_fma_f32 v[42:43], v[198:199], v[42:43], v[202:203]
	v_mul_f32_e32 v33, v41, v41
	v_pk_fma_f32 v[42:43], v[42:43], s[26:27], v[34:35] op_sel_hi:[1,0,1]
	v_add_f32_e32 v32, v40, v41
	v_fmac_f32_e32 v33, v40, v40
	v_add_f32_e32 v32, v42, v32
	v_fmac_f32_e32 v33, v42, v42
	v_add_f32_e32 v32, v43, v32
	v_fmac_f32_e32 v33, v43, v43
	v_add_f32_e32 v32, v44, v32
	v_add_f32_e32 v33, v45, v33
	ds_bpermute_b32 v34, v116, v32
	ds_bpermute_b32 v35, v116, v33
	global_store_dwordx4 v[50:51], v[40:43], off offset:528
	v_cvt_pk_bf16_f32 v38, v40, v41
	v_cvt_pk_bf16_f32 v39, v42, v43
	s_waitcnt lgkmcnt(0)
	v_add_f32_e32 v32, v32, v34
	v_add_f32_e32 v33, v33, v35
	ds_bpermute_b32 v34, v117, v32
	ds_bpermute_b32 v35, v117, v33
	flat_store_dwordx4 v[68:69], v[36:39] offset:256
	s_and_saveexec_b64 s[30:31], s[2:3]
	s_cbranch_execz .LBB0_2204
	s_waitcnt lgkmcnt(0)
	v_add_f32_e32 v35, v33, v35
	v_add_f32_e32 v34, v32, v34
	v_lshl_add_u64 v[32:33], s[10:11], 0, v[48:49]
	flat_atomic_add_f32 v[32:33], v34
	flat_atomic_add_f32 v[32:33], v35 offset:4
; DEVI unsigned pk2(float lo, float hi) { unsigned r; asm("v_cvt_pk_bf16_f32 %0, %1, %2" : "=v"(r) : "v"(lo), "v"(hi)); return r; }
; DEVI void row_stats(const float* stats, int row, float& mu, float& rs) {
;     if (stats) { const float2 st = *(const float2*)(stats + 2 * (size_t)row); mu = st.x * (1.0f / 1024.0f); const float var = st.y * (1.0f / 1024.0f) - mu * mu; rs = rsqrtf(fmaxf(var, 0.f) + LN_EPS); }
;     else { mu = 0.f; rs = 1.f; }
;     DEVI void operator()(const f32x4 (&acc)[2][2][4][2], const pg8::Unit& u, int wr, int wc, int fr, int fq) const {
;     ...
;                 const int row = row0 + ai * 128 + m * 16; float mu, rs; row_stats(stin, row, mu, rs);
;                 float sum = 0.f, sq = 0.f;
; #pragma unroll
;                 for (int bj = 0; bj < 2; ++bj) {
;                     f32x4 z[2];
; #pragma unroll
;                     for (int n = 0; n < 2; ++n) {
;                         const int col = colb + bj * 128 + 4 * n;
;                         f32x4 xv = *(const f32x4*)(zsrc + (size_t)row * DM + col);
;                         if (stin) { const f32x4 gv = *(const f32x4*)(gin + col), bv = *(const f32x4*)(bin + col); xv = (xv - mu) * rs * gv + bv; }
;                         f32x4 zz = ALPHA * xv + acc[ai][bj][m][n];
;                         if (bias) zz += *(const f32x4*)(bias + col);
;                         *(f32x4*)(zdst + (size_t)row * DM + col) = zz;
;                         sum += zz[0] + zz[1] + zz[2] + zz[3]; sq += zz[0] * zz[0] + zz[1] * zz[1] + zz[2] * zz[2] + zz[3] * zz[3];
;                         z[n] = zz;
;                     }
;                     u32x4 o; o.x = pk2(z[0][0], z[0][1]); o.y = pk2(z[0][2], z[0][3]); o.z = pk2(z[1][0], z[1][1]); o.w = pk2(z[1][2], z[1][3]);
;                     if (zb) *(u32x4*)(zb + (size_t)row * DM + colb + bj * 128) = o;
;                 }
;                 sum += __shfl_xor(sum, 16); sq += __shfl_xor(sq, 16);
;                 sum += __shfl_xor(sum, 32); sq += __shfl_xor(sq, 32);
;                 if (fq == 0) { atomicAdd(stout + 2 * (size_t)row, sum); atomicAdd(stout + 2 * (size_t)row + 1, sq); }
.LBB0_2204:
	s_or_b64 exec, exec, s[30:31]
	v_add_u32_e32 v52, 0xa0, v154
	v_ashrrev_i32_e32 v53, 31, v52
	v_lshlrev_b64 v[32:33], 3, v[52:53]
	s_waitcnt lgkmcnt(0)
	v_lshl_add_u64 v[34:35], s[12:13], 0, v[32:33]
	flat_load_dwordx2 v[54:55], v[34:35]
	v_lshlrev_b64 v[34:35], 12, v[52:53]
	v_lshl_add_u64 v[34:35], s[46:47], 0, v[34:35]
	v_lshl_add_u64 v[34:35], v[144:145], 2, v[34:35]
	global_load_dwordx4 v[36:39], v[34:35], off
	global_load_dwordx4 v[40:43], v[150:151], off
	global_load_dwordx4 v[44:47], v[152:153], off
	global_load_dwordx4 v[48:51], v[34:35], off offset:16
	global_load_dwordx4 v[196:199], v[146:147], off
	global_load_dwordx4 v[200:203], v[148:149], off
	global_load_dwordx4 v[204:207], v[34:35], off offset:512
	global_load_dwordx4 v[208:211], v[34:35], off offset:528
	s_waitcnt vmcnt(0) lgkmcnt(0)
	v_pk_mul_f32 v[54:55], v[54:55], s[24:25] op_sel:[1,0] op_sel_hi:[0,0]
	v_fma_f32 v54, -v55, v55, v54
	v_max_f32_e32 v54, 0, v54
	v_add_f32_e32 v54, 0x3727c5ac, v54
	v_mul_f32_e32 v56, 0x4b800000, v54
	v_cmp_gt_f32_e32 vcc, s61, v54
	v_sub_f32_e32 v37, v37, v55
	v_sub_f32_e32 v36, v36, v55
	v_cndmask_b32_e32 v54, v54, v56, vcc
	v_rsq_f32_e32 v54, v54
	v_sub_f32_e32 v39, v39, v55
	v_sub_f32_e32 v38, v38, v55
	v_mul_f32_e32 v56, 0x45800000, v54
	v_cndmask_b32_e32 v54, v54, v56, vcc
	v_pk_mul_f32 v[38:39], v[38:39], v[54:55] op_sel_hi:[1,0]
	v_pk_mul_f32 v[36:37], v[36:37], v[54:55] op_sel_hi:[1,0]
	v_pk_fma_f32 v[38:39], v[42:43], v[38:39], v[46:47]
	v_pk_fma_f32 v[36:37], v[40:41], v[36:37], v[44:45]
	v_pk_fma_f32 v[30:31], v[38:39], s[26:27], v[30:31] op_sel_hi:[1,0,1]
	v_pk_fma_f32 v[28:29], v[36:37], s[26:27], v[28:29] op_sel_hi:[1,0,1]
	global_store_dwordx4 v[34:35], v[28:31], off
	v_lshlrev_b64 v[44:45], 11, v[52:53]
	v_lshl_add_u64 v[44:45], s[14:15], 0, v[44:45]
	v_lshl_add_u64 v[52:53], v[144:145], 1, v[44:45]
	v_sub_f32_e32 v45, v49, v55
	v_sub_f32_e32 v44, v48, v55
	v_sub_f32_e32 v47, v51, v55
	v_sub_f32_e32 v46, v50, v55
	v_pk_mul_f32 v[46:47], v[46:47], v[54:55] op_sel_hi:[1,0]
	v_pk_mul_f32 v[48:49], v[44:45], v[54:55] op_sel_hi:[1,0]
	v_cvt_pk_bf16_f32 v44, v28, v29
	v_cvt_pk_bf16_f32 v45, v30, v31
	v_pk_fma_f32 v[38:39], v[198:199], v[46:47], v[202:203]
	v_pk_fma_f32 v[36:37], v[196:197], v[48:49], v[200:201]
	v_pk_fma_f32 v[26:27], v[38:39], s[26:27], v[26:27] op_sel_hi:[1,0,1]
	v_pk_fma_f32 v[24:25], v[36:37], s[26:27], v[24:25] op_sel_hi:[1,0,1]
	global_store_dwordx4 v[34:35], v[24:27], off offset:16
	v_cvt_pk_bf16_f32 v46, v24, v25
	v_cvt_pk_bf16_f32 v47, v26, v27
	flat_store_dwordx4 v[52:53], v[44:47]
	global_load_dwordx4 v[40:43], v[120:121], off
	s_nop 0
	global_load_dwordx4 v[44:47], v[122:123], off
	global_load_dwordx4 v[196:199], v[124:125], off
	global_load_dwordx4 v[200:203], v[126:127], off
	s_waitcnt vmcnt(0)
	v_sub_f32_e32 v37, v205, v55
	v_sub_f32_e32 v36, v204, v55
	v_sub_f32_e32 v39, v207, v55
	v_sub_f32_e32 v38, v206, v55
	v_pk_mul_f32 v[38:39], v[54:55], v[38:39] op_sel_hi:[0,1]
	v_pk_mul_f32 v[36:37], v[54:55], v[36:37] op_sel_hi:[0,1]
	v_pk_fma_f32 v[36:37], v[40:41], v[36:37], v[44:45]
	v_pk_fma_f32 v[38:39], v[42:43], v[38:39], v[46:47]
	v_pk_fma_f32 v[20:21], v[36:37], s[26:27], v[20:21] op_sel_hi:[1,0,1]
	v_pk_fma_f32 v[22:23], v[38:39], s[26:27], v[22:23] op_sel_hi:[1,0,1]
	global_store_dwordx4 v[34:35], v[20:23], off offset:512
	v_add_f32_e32 v44, v28, v29
	v_mul_f32_e32 v29, v29, v29
	v_fmac_f32_e32 v29, v28, v28
	v_add_f32_e32 v44, v30, v44
	v_fmac_f32_e32 v29, v30, v30
	v_add_f32_e32 v30, v24, v25
	v_mul_f32_e32 v25, v25, v25
	v_fmac_f32_e32 v25, v24, v24
	v_add_f32_e32 v28, v31, v44
	v_add_f32_e32 v30, v26, v30
	v_fmac_f32_e32 v25, v26, v26
	v_add_f32_e32 v28, 0, v28
	v_fmac_f32_e32 v29, v31, v31
	v_add_f32_e32 v24, v27, v30
	v_fmac_f32_e32 v25, v27, v27
	v_add_f32_e32 v28, v24, v28
	v_add_f32_e32 v29, v29, v25
	v_sub_f32_e32 v25, v209, v55
	v_sub_f32_e32 v24, v208, v55
	v_pk_mul_f32 v[24:25], v[54:55], v[24:25] op_sel_hi:[0,1]
	v_sub_f32_e32 v27, v211, v55
	v_sub_f32_e32 v26, v210, v55
	v_pk_mul_f32 v[26:27], v[54:55], v[26:27] op_sel_hi:[0,1]
	v_mul_f32_e32 v31, v21, v21
	v_add_f32_e32 v30, v20, v21
	v_fmac_f32_e32 v31, v20, v20
	v_add_f32_e32 v30, v22, v30
	v_fmac_f32_e32 v31, v22, v22
	v_add_f32_e32 v30, v23, v30
	v_fmac_f32_e32 v31, v23, v23
	v_add_f32_e32 v28, v28, v30
	v_add_f32_e32 v29, v29, v31
	v_cvt_pk_bf16_f32 v20, v20, v21
	v_cvt_pk_bf16_f32 v21, v22, v23
	v_pk_fma_f32 v[24:25], v[196:197], v[24:25], v[200:201]
	s_nop 0
	v_pk_fma_f32 v[24:25], v[24:25], s[26:27], v[16:17] op_sel_hi:[1,0,1]
	v_pk_fma_f32 v[26:27], v[198:199], v[26:27], v[202:203]
	v_mul_f32_e32 v17, v25, v25
	v_pk_fma_f32 v[26:27], v[26:27], s[26:27], v[18:19] op_sel_hi:[1,0,1]
	v_add_f32_e32 v16, v24, v25
	v_fmac_f32_e32 v17, v24, v24
	v_add_f32_e32 v16, v26, v16
	v_fmac_f32_e32 v17, v26, v26
	v_add_f32_e32 v16, v27, v16
	v_fmac_f32_e32 v17, v27, v27
	v_add_f32_e32 v16, v28, v16
	v_add_f32_e32 v17, v29, v17
	ds_bpermute_b32 v18, v116, v16
	ds_bpermute_b32 v19, v116, v17
	global_store_dwordx4 v[34:35], v[24:27], off offset:528
	v_cvt_pk_bf16_f32 v22, v24, v25
	v_cvt_pk_bf16_f32 v23, v26, v27
	s_waitcnt lgkmcnt(0)
	v_add_f32_e32 v16, v16, v18
	v_add_f32_e32 v17, v17, v19
	ds_bpermute_b32 v18, v117, v16
	ds_bpermute_b32 v19, v117, v17
	flat_store_dwordx4 v[52:53], v[20:23] offset:256
	s_and_saveexec_b64 s[30:31], s[2:3]
	s_cbranch_execz .LBB0_2206
	s_waitcnt lgkmcnt(0)
	v_add_f32_e32 v19, v17, v19
	v_add_f32_e32 v18, v16, v18
	v_lshl_add_u64 v[16:17], s[10:11], 0, v[32:33]
	flat_atomic_add_f32 v[16:17], v18
	flat_atomic_add_f32 v[16:17], v19 offset:4
; DEVI unsigned pk2(float lo, float hi) { unsigned r; asm("v_cvt_pk_bf16_f32 %0, %1, %2" : "=v"(r) : "v"(lo), "v"(hi)); return r; }
; DEVI void row_stats(const float* stats, int row, float& mu, float& rs) {
;     if (stats) { const float2 st = *(const float2*)(stats + 2 * (size_t)row); mu = st.x * (1.0f / 1024.0f); const float var = st.y * (1.0f / 1024.0f) - mu * mu; rs = rsqrtf(fmaxf(var, 0.f) + LN_EPS); }
;     else { mu = 0.f; rs = 1.f; }
;     DEVI void operator()(const f32x4 (&acc)[2][2][4][2], const pg8::Unit& u, int wr, int wc, int fr, int fq) const {
;     ...
;                 const int row = row0 + ai * 128 + m * 16; float mu, rs; row_stats(stin, row, mu, rs);
;                 float sum = 0.f, sq = 0.f;
; #pragma unroll
;                 for (int bj = 0; bj < 2; ++bj) {
;                     f32x4 z[2];
; #pragma unroll
;                     for (int n = 0; n < 2; ++n) {
;                         const int col = colb + bj * 128 + 4 * n;
;                         f32x4 xv = *(const f32x4*)(zsrc + (size_t)row * DM + col);
;                         if (stin) { const f32x4 gv = *(const f32x4*)(gin + col), bv = *(const f32x4*)(bin + col); xv = (xv - mu) * rs * gv + bv; }
;                         f32x4 zz = ALPHA * xv + acc[ai][bj][m][n];
;                         if (bias) zz += *(const f32x4*)(bias + col);
;                         *(f32x4*)(zdst + (size_t)row * DM + col) = zz;
;                         sum += zz[0] + zz[1] + zz[2] + zz[3]; sq += zz[0] * zz[0] + zz[1] * zz[1] + zz[2] * zz[2] + zz[3] * zz[3];
;                         z[n] = zz;
;                     }
;                     u32x4 o; o.x = pk2(z[0][0], z[0][1]); o.y = pk2(z[0][2], z[0][3]); o.z = pk2(z[1][0], z[1][1]); o.w = pk2(z[1][2], z[1][3]);
;                     if (zb) *(u32x4*)(zb + (size_t)row * DM + colb + bj * 128) = o;
;                 }
;                 sum += __shfl_xor(sum, 16); sq += __shfl_xor(sq, 16);
;                 sum += __shfl_xor(sum, 32); sq += __shfl_xor(sq, 32);
;                 if (fq == 0) { atomicAdd(stout + 2 * (size_t)row, sum); atomicAdd(stout + 2 * (size_t)row + 1, sq); }
.LBB0_2206:
	s_or_b64 exec, exec, s[30:31]
	v_add_u32_e32 v36, 0xb0, v154
	v_ashrrev_i32_e32 v37, 31, v36
	v_lshlrev_b64 v[16:17], 3, v[36:37]
	s_waitcnt lgkmcnt(0)
	v_lshl_add_u64 v[18:19], s[12:13], 0, v[16:17]
	flat_load_dwordx2 v[38:39], v[18:19]
	v_lshlrev_b64 v[18:19], 12, v[36:37]
	v_lshl_add_u64 v[18:19], s[46:47], 0, v[18:19]
	v_lshl_add_u64 v[18:19], v[144:145], 2, v[18:19]
	global_load_dwordx4 v[20:23], v[18:19], off
	global_load_dwordx4 v[24:27], v[150:151], off
	global_load_dwordx4 v[28:31], v[152:153], off
	global_load_dwordx4 v[32:35], v[18:19], off offset:16
	global_load_dwordx4 v[196:199], v[146:147], off
	global_load_dwordx4 v[200:203], v[148:149], off
	global_load_dwordx4 v[204:207], v[18:19], off offset:512
	global_load_dwordx4 v[208:211], v[18:19], off offset:528
	s_waitcnt vmcnt(0) lgkmcnt(0)
	v_pk_mul_f32 v[38:39], v[38:39], s[24:25] op_sel:[1,0] op_sel_hi:[0,0]
	v_fma_f32 v38, -v39, v39, v38
	v_max_f32_e32 v38, 0, v38
	v_add_f32_e32 v38, 0x3727c5ac, v38
	v_mul_f32_e32 v40, 0x4b800000, v38
	v_cmp_gt_f32_e32 vcc, s61, v38
	v_sub_f32_e32 v21, v21, v39
	v_sub_f32_e32 v20, v20, v39
	v_cndmask_b32_e32 v38, v38, v40, vcc
	v_rsq_f32_e32 v38, v38
	v_sub_f32_e32 v23, v23, v39
	v_sub_f32_e32 v22, v22, v39
	v_mul_f32_e32 v40, 0x45800000, v38
	v_cndmask_b32_e32 v38, v38, v40, vcc
	v_pk_mul_f32 v[22:23], v[22:23], v[38:39] op_sel_hi:[1,0]
	v_pk_mul_f32 v[20:21], v[20:21], v[38:39] op_sel_hi:[1,0]
	v_pk_fma_f32 v[22:23], v[26:27], v[22:23], v[30:31]
	v_pk_fma_f32 v[20:21], v[24:25], v[20:21], v[28:29]
	v_pk_fma_f32 v[14:15], v[22:23], s[26:27], v[14:15] op_sel_hi:[1,0,1]
	v_pk_fma_f32 v[12:13], v[20:21], s[26:27], v[12:13] op_sel_hi:[1,0,1]
	global_store_dwordx4 v[18:19], v[12:15], off
	v_lshlrev_b64 v[28:29], 11, v[36:37]
	v_lshl_add_u64 v[28:29], s[14:15], 0, v[28:29]
	v_lshl_add_u64 v[36:37], v[144:145], 1, v[28:29]
	v_sub_f32_e32 v29, v33, v39
	v_sub_f32_e32 v28, v32, v39
	v_sub_f32_e32 v31, v35, v39
	v_sub_f32_e32 v30, v34, v39
	v_pk_mul_f32 v[30:31], v[30:31], v[38:39] op_sel_hi:[1,0]
	v_pk_mul_f32 v[32:33], v[28:29], v[38:39] op_sel_hi:[1,0]
	v_cvt_pk_bf16_f32 v28, v12, v13
	v_cvt_pk_bf16_f32 v29, v14, v15
	v_pk_fma_f32 v[22:23], v[198:199], v[30:31], v[202:203]
	v_pk_fma_f32 v[20:21], v[196:197], v[32:33], v[200:201]
	v_pk_fma_f32 v[10:11], v[22:23], s[26:27], v[10:11] op_sel_hi:[1,0,1]
	v_pk_fma_f32 v[8:9], v[20:21], s[26:27], v[8:9] op_sel_hi:[1,0,1]
	global_store_dwordx4 v[18:19], v[8:11], off offset:16
	v_cvt_pk_bf16_f32 v30, v8, v9
	v_cvt_pk_bf16_f32 v31, v10, v11
	flat_store_dwordx4 v[36:37], v[28:31]
	global_load_dwordx4 v[24:27], v[120:121], off
	s_nop 0
	global_load_dwordx4 v[28:31], v[122:123], off
	global_load_dwordx4 v[196:199], v[124:125], off
	global_load_dwordx4 v[200:203], v[126:127], off
	s_waitcnt vmcnt(0)
	v_sub_f32_e32 v21, v205, v39
	v_sub_f32_e32 v20, v204, v39
	v_sub_f32_e32 v23, v207, v39
	v_sub_f32_e32 v22, v206, v39
	v_pk_mul_f32 v[22:23], v[38:39], v[22:23] op_sel_hi:[0,1]
	v_pk_mul_f32 v[20:21], v[38:39], v[20:21] op_sel_hi:[0,1]
	v_pk_fma_f32 v[20:21], v[24:25], v[20:21], v[28:29]
	v_pk_fma_f32 v[22:23], v[26:27], v[22:23], v[30:31]
	v_pk_fma_f32 v[4:5], v[20:21], s[26:27], v[4:5] op_sel_hi:[1,0,1]
	v_pk_fma_f32 v[6:7], v[22:23], s[26:27], v[6:7] op_sel_hi:[1,0,1]
	global_store_dwordx4 v[18:19], v[4:7], off offset:512
	v_add_f32_e32 v28, v12, v13
	v_mul_f32_e32 v13, v13, v13
	v_fmac_f32_e32 v13, v12, v12
	v_add_f32_e32 v28, v14, v28
	v_fmac_f32_e32 v13, v14, v14
	v_add_f32_e32 v14, v8, v9
	v_mul_f32_e32 v9, v9, v9
	v_fmac_f32_e32 v9, v8, v8
	v_add_f32_e32 v12, v15, v28
	v_add_f32_e32 v14, v10, v14
	v_fmac_f32_e32 v9, v10, v10
	v_add_f32_e32 v12, 0, v12
	v_fmac_f32_e32 v13, v15, v15
	v_add_f32_e32 v8, v11, v14
	v_fmac_f32_e32 v9, v11, v11
	v_add_f32_e32 v12, v8, v12
	v_add_f32_e32 v13, v13, v9
	v_sub_f32_e32 v9, v209, v39
	v_sub_f32_e32 v8, v208, v39
	v_pk_mul_f32 v[8:9], v[38:39], v[8:9] op_sel_hi:[0,1]
	v_sub_f32_e32 v11, v211, v39
	v_sub_f32_e32 v10, v210, v39
	v_pk_mul_f32 v[10:11], v[38:39], v[10:11] op_sel_hi:[0,1]
	v_mul_f32_e32 v15, v5, v5
	v_add_f32_e32 v14, v4, v5
	v_fmac_f32_e32 v15, v4, v4
	v_add_f32_e32 v14, v6, v14
	v_fmac_f32_e32 v15, v6, v6
	v_add_f32_e32 v14, v7, v14
	v_fmac_f32_e32 v15, v7, v7
	v_add_f32_e32 v12, v12, v14
	v_add_f32_e32 v13, v13, v15
	v_cvt_pk_bf16_f32 v4, v4, v5
	v_cvt_pk_bf16_f32 v5, v6, v7
	v_pk_fma_f32 v[8:9], v[196:197], v[8:9], v[200:201]
	s_nop 0
	v_pk_fma_f32 v[8:9], v[8:9], s[26:27], v[0:1] op_sel_hi:[1,0,1]
	v_pk_fma_f32 v[10:11], v[198:199], v[10:11], v[202:203]
	v_mul_f32_e32 v1, v9, v9
	v_pk_fma_f32 v[10:11], v[10:11], s[26:27], v[2:3] op_sel_hi:[1,0,1]
	v_add_f32_e32 v0, v8, v9
	v_fmac_f32_e32 v1, v8, v8
	v_add_f32_e32 v0, v10, v0
	v_fmac_f32_e32 v1, v10, v10
	v_add_f32_e32 v0, v11, v0
	v_fmac_f32_e32 v1, v11, v11
	v_add_f32_e32 v0, v12, v0
	v_add_f32_e32 v1, v13, v1
	ds_bpermute_b32 v2, v116, v0
	ds_bpermute_b32 v3, v116, v1
	global_store_dwordx4 v[18:19], v[8:11], off offset:528
	v_cvt_pk_bf16_f32 v6, v8, v9
	v_cvt_pk_bf16_f32 v7, v10, v11
	s_waitcnt lgkmcnt(0)
	v_add_f32_e32 v0, v0, v2
	v_add_f32_e32 v1, v1, v3
	ds_bpermute_b32 v2, v117, v0
	ds_bpermute_b32 v3, v117, v1
	flat_store_dwordx4 v[36:37], v[4:7] offset:256
	s_and_saveexec_b64 s[30:31], s[2:3]
	s_cbranch_execz .LBB0_2208
	s_waitcnt lgkmcnt(0)
	v_add_f32_e32 v3, v1, v3
	v_add_f32_e32 v2, v0, v2
	v_lshl_add_u64 v[0:1], s[10:11], 0, v[16:17]
	flat_atomic_add_f32 v[0:1], v2
	flat_atomic_add_f32 v[0:1], v3 offset:4

; DEVI unsigned pk2(float lo, float hi) { unsigned r; asm("v_cvt_pk_bf16_f32 %0, %1, %2" : "=v"(r) : "v"(lo), "v"(hi)); return r; }
; DEVI void row_stats(const float* stats, int row, float& mu, float& rs) {
;     if (stats) { const float2 st = *(const float2*)(stats + 2 * (size_t)row); mu = st.x * (1.0f / 1024.0f); const float var = st.y * (1.0f / 1024.0f) - mu * mu; rs = rsqrtf(fmaxf(var, 0.f) + LN_EPS); }
;     else { mu = 0.f; rs = 1.f; }
;     DEVI void operator()(const f32x4 (&acc)[2][2][4][2], const pg8::Unit& u, int wr, int wc, int fr, int fq) const {
;     ...
;                 const int row = row0 + ai * 128 + m * 16; float mu, rs; row_stats(stin, row, mu, rs);
;                 float sum = 0.f, sq = 0.f;
; #pragma unroll
;                 for (int bj = 0; bj < 2; ++bj) {
;                     f32x4 z[2];
; #pragma unroll
;                     for (int n = 0; n < 2; ++n) {
;                         const int col = colb + bj * 128 + 4 * n;
;                         f32x4 xv = *(const f32x4*)(zsrc + (size_t)row * DM + col);
;                         if (stin) { const f32x4 gv = *(const f32x4*)(gin + col), bv = *(const f32x4*)(bin + col); xv = (xv - mu) * rs * gv + bv; }
;                         f32x4 zz = ALPHA * xv + acc[ai][bj][m][n];
;                         if (bias) zz += *(const f32x4*)(bias + col);
;                         *(f32x4*)(zdst + (size_t)row * DM + col) = zz;
;                         sum += zz[0] + zz[1] + zz[2] + zz[3]; sq += zz[0] * zz[0] + zz[1] * zz[1] + zz[2] * zz[2] + zz[3] * zz[3];
;                         z[n] = zz;
;                     }
;                     u32x4 o; o.x = pk2(z[0][0], z[0][1]); o.y = pk2(z[0][2], z[0][3]); o.z = pk2(z[1][0], z[1][1]); o.w = pk2(z[1][2], z[1][3]);
;                     if (zb) *(u32x4*)(zb + (size_t)row * DM + colb + bj * 128) = o;
;                 }
;                 sum += __shfl_xor(sum, 16); sq += __shfl_xor(sq, 16);
;                 sum += __shfl_xor(sum, 32); sq += __shfl_xor(sq, 32);
;                 if (fq == 0) { atomicAdd(stout + 2 * (size_t)row, sum); atomicAdd(stout + 2 * (size_t)row + 1, sq); }
.LBB0_2847:
	s_or_b64 exec, exec, s[28:29]
	v_or_b32_e32 v118, 16, v154
	v_ashrrev_i32_e32 v119, 31, v118
	v_lshlrev_b64 v[112:113], 3, v[118:119]
	v_lshl_add_u64 v[156:157], s[12:13], 0, v[112:113]
	flat_load_dwordx2 v[180:181], v[156:157]
	v_lshlrev_b64 v[118:119], 12, v[118:119]
	v_lshl_add_u64 v[118:119], s[46:47], 0, v[118:119]
	v_lshl_add_u64 v[118:119], v[144:145], 2, v[118:119]
	global_load_dwordx4 v[156:159], v[118:119], off
	global_load_dwordx4 v[168:171], v[150:151], off
	global_load_dwordx4 v[172:175], v[152:153], off
	global_load_dwordx4 v[176:179], v[118:119], off offset:16
	global_load_dwordx4 v[194:197], v[118:119], off offset:512
	global_load_dwordx4 v[198:201], v[118:119], off offset:528
	s_waitcnt vmcnt(0) lgkmcnt(0)
	v_pk_mul_f32 v[180:181], v[180:181], s[22:23] op_sel:[1,0] op_sel_hi:[0,0]
	v_fma_f32 v115, -v181, v181, v180
	v_max_f32_e32 v115, 0, v115
	v_add_f32_e32 v115, 0x3727c5ac, v115
	v_mul_f32_e32 v117, 0x4b800000, v115
	v_cmp_gt_f32_e32 vcc, s55, v115
	v_sub_f32_e32 v157, v157, v181
	v_sub_f32_e32 v156, v156, v181
	v_cndmask_b32_e32 v115, v115, v117, vcc
	v_rsq_f32_e32 v115, v115
	v_sub_f32_e32 v159, v159, v181
	v_sub_f32_e32 v158, v158, v181
	v_sub_f32_e32 v177, v177, v181
	v_mul_f32_e32 v117, 0x45800000, v115
	v_cndmask_b32_e32 v180, v115, v117, vcc
	v_pk_mul_f32 v[158:159], v[158:159], v[180:181] op_sel_hi:[1,0]
	v_pk_mul_f32 v[156:157], v[156:157], v[180:181] op_sel_hi:[1,0]
	v_pk_fma_f32 v[158:159], v[170:171], v[158:159], v[174:175]
	v_pk_fma_f32 v[156:157], v[168:169], v[156:157], v[172:173]
	v_pk_fma_f32 v[110:111], v[158:159], s[24:25], v[110:111] op_sel_hi:[1,0,1]
	v_pk_fma_f32 v[108:109], v[156:157], s[24:25], v[108:109] op_sel_hi:[1,0,1]
	global_store_dwordx4 v[118:119], v[108:111], off
	global_load_dwordx4 v[156:159], v[146:147], off
	global_load_dwordx4 v[168:171], v[148:149], off
	v_sub_f32_e32 v176, v176, v181
	v_sub_f32_e32 v179, v179, v181
	v_sub_f32_e32 v178, v178, v181
	v_pk_mul_f32 v[178:179], v[178:179], v[180:181] op_sel_hi:[1,0]
	v_pk_mul_f32 v[176:177], v[176:177], v[180:181] op_sel_hi:[1,0]
	v_add_f32_e32 v115, v108, v109
	v_mul_f32_e32 v109, v109, v109
	v_fmac_f32_e32 v109, v108, v108
	v_add_f32_e32 v115, v110, v115
	v_fmac_f32_e32 v109, v110, v110
	v_add_f32_e32 v108, v111, v115
	v_add_f32_e32 v108, 0, v108
	v_fmac_f32_e32 v109, v111, v111
	s_waitcnt vmcnt(0)
	v_pk_fma_f32 v[156:157], v[156:157], v[176:177], v[168:169]
	v_pk_fma_f32 v[158:159], v[158:159], v[178:179], v[170:171]
	v_pk_fma_f32 v[104:105], v[156:157], s[24:25], v[104:105] op_sel_hi:[1,0,1]
	v_pk_fma_f32 v[106:107], v[158:159], s[24:25], v[106:107] op_sel_hi:[1,0,1]
	global_store_dwordx4 v[118:119], v[104:107], off offset:16
	global_load_dwordx4 v[156:159], v[124:125], off
	global_load_dwordx4 v[168:171], v[126:127], off
	s_waitcnt vmcnt(2)
	v_sub_f32_e32 v173, v195, v181
	v_sub_f32_e32 v172, v194, v181
	v_sub_f32_e32 v175, v197, v181
	v_sub_f32_e32 v174, v196, v181
	v_pk_mul_f32 v[174:175], v[180:181], v[174:175] op_sel_hi:[0,1]
	v_pk_mul_f32 v[172:173], v[180:181], v[172:173] op_sel_hi:[0,1]
	v_add_f32_e32 v110, v104, v105
	v_mul_f32_e32 v105, v105, v105
	v_fmac_f32_e32 v105, v104, v104
	v_add_f32_e32 v110, v106, v110
	v_fmac_f32_e32 v105, v106, v106
	v_add_f32_e32 v104, v107, v110
	v_fmac_f32_e32 v105, v107, v107
	v_add_f32_e32 v104, v104, v108
	v_add_f32_e32 v105, v109, v105
	s_waitcnt vmcnt(0)
	v_pk_fma_f32 v[156:157], v[156:157], v[172:173], v[168:169]
	v_pk_fma_f32 v[158:159], v[158:159], v[174:175], v[170:171]
	v_pk_fma_f32 v[100:101], v[156:157], s[24:25], v[100:101] op_sel_hi:[1,0,1]
	v_pk_fma_f32 v[102:103], v[158:159], s[24:25], v[102:103] op_sel_hi:[1,0,1]
	global_store_dwordx4 v[118:119], v[100:103], off offset:512
	global_load_dwordx4 v[156:159], v[120:121], off
	global_load_dwordx4 v[168:171], v[122:123], off
	v_add_f32_e32 v106, v100, v101
	v_mul_f32_e32 v101, v101, v101
	v_fmac_f32_e32 v101, v100, v100
	s_waitcnt vmcnt(1)
	v_sub_f32_e32 v173, v199, v181
	v_sub_f32_e32 v172, v198, v181
	v_add_f32_e32 v106, v102, v106
	v_fmac_f32_e32 v101, v102, v102
	v_pk_mul_f32 v[172:173], v[180:181], v[172:173] op_sel_hi:[0,1]
	v_add_f32_e32 v100, v103, v106
	v_fmac_f32_e32 v101, v103, v103
	v_sub_f32_e32 v175, v201, v181
	v_sub_f32_e32 v174, v200, v181
	v_add_f32_e32 v104, v104, v100
	v_add_f32_e32 v105, v105, v101
	v_pk_mul_f32 v[174:175], v[180:181], v[174:175] op_sel_hi:[0,1]
	s_waitcnt vmcnt(0)
	v_pk_fma_f32 v[100:101], v[156:157], v[172:173], v[168:169]
	s_nop 0
	v_pk_fma_f32 v[100:101], v[100:101], s[24:25], v[96:97] op_sel_hi:[1,0,1]
	v_pk_fma_f32 v[102:103], v[158:159], v[174:175], v[170:171]
	v_mul_f32_e32 v97, v101, v101
	v_pk_fma_f32 v[102:103], v[102:103], s[24:25], v[98:99] op_sel_hi:[1,0,1]
	v_add_f32_e32 v96, v100, v101
	v_fmac_f32_e32 v97, v100, v100
	v_add_f32_e32 v96, v102, v96
	v_fmac_f32_e32 v97, v102, v102
	v_add_f32_e32 v96, v103, v96
	v_fmac_f32_e32 v97, v103, v103
	v_add_f32_e32 v96, v104, v96
	v_add_f32_e32 v97, v105, v97
	ds_bpermute_b32 v98, v116, v96
	ds_bpermute_b32 v99, v116, v97
	global_store_dwordx4 v[118:119], v[100:103], off offset:528
	s_waitcnt lgkmcnt(1)
	v_add_f32_e32 v96, v96, v98
	s_waitcnt lgkmcnt(0)
	v_add_f32_e32 v97, v97, v99
	ds_bpermute_b32 v98, v114, v96
	ds_bpermute_b32 v99, v114, v97
	s_and_saveexec_b64 s[28:29], s[2:3]
	s_cbranch_execz .LBB0_2849
	v_lshl_add_u64 v[100:101], s[10:11], 0, v[112:113]
	s_waitcnt lgkmcnt(1)
	v_add_f32_e32 v96, v96, v98
	s_waitcnt lgkmcnt(0)
	v_add_f32_e32 v97, v97, v99
	flat_atomic_add_f32 v[100:101], v96
	flat_atomic_add_f32 v[100:101], v97 offset:4
; DEVI unsigned pk2(float lo, float hi) { unsigned r; asm("v_cvt_pk_bf16_f32 %0, %1, %2" : "=v"(r) : "v"(lo), "v"(hi)); return r; }
; DEVI void row_stats(const float* stats, int row, float& mu, float& rs) {
;     if (stats) { const float2 st = *(const float2*)(stats + 2 * (size_t)row); mu = st.x * (1.0f / 1024.0f); const float var = st.y * (1.0f / 1024.0f) - mu * mu; rs = rsqrtf(fmaxf(var, 0.f) + LN_EPS); }
;     else { mu = 0.f; rs = 1.f; }
;     DEVI void operator()(const f32x4 (&acc)[2][2][4][2], const pg8::Unit& u, int wr, int wc, int fr, int fq) const {
;     ...
;                 const int row = row0 + ai * 128 + m * 16; float mu, rs; row_stats(stin, row, mu, rs);
;                 float sum = 0.f, sq = 0.f;
; #pragma unroll
;                 for (int bj = 0; bj < 2; ++bj) {
;                     f32x4 z[2];
; #pragma unroll
;                     for (int n = 0; n < 2; ++n) {
;                         const int col = colb + bj * 128 + 4 * n;
;                         f32x4 xv = *(const f32x4*)(zsrc + (size_t)row * DM + col);
;                         if (stin) { const f32x4 gv = *(const f32x4*)(gin + col), bv = *(const f32x4*)(bin + col); xv = (xv - mu) * rs * gv + bv; }
;                         f32x4 zz = ALPHA * xv + acc[ai][bj][m][n];
;                         if (bias) zz += *(const f32x4*)(bias + col);
;                         *(f32x4*)(zdst + (size_t)row * DM + col) = zz;
;                         sum += zz[0] + zz[1] + zz[2] + zz[3]; sq += zz[0] * zz[0] + zz[1] * zz[1] + zz[2] * zz[2] + zz[3] * zz[3];
;                         z[n] = zz;
;                     }
;                     u32x4 o; o.x = pk2(z[0][0], z[0][1]); o.y = pk2(z[0][2], z[0][3]); o.z = pk2(z[1][0], z[1][1]); o.w = pk2(z[1][2], z[1][3]);
;                     if (zb) *(u32x4*)(zb + (size_t)row * DM + colb + bj * 128) = o;
;                 }
;                 sum += __shfl_xor(sum, 16); sq += __shfl_xor(sq, 16);
;                 sum += __shfl_xor(sum, 32); sq += __shfl_xor(sq, 32);
;                 if (fq == 0) { atomicAdd(stout + 2 * (size_t)row, sum); atomicAdd(stout + 2 * (size_t)row + 1, sq); }
.LBB0_2849:
	s_or_b64 exec, exec, s[28:29]
	s_waitcnt lgkmcnt(0)
	v_or_b32_e32 v98, 32, v154
	v_ashrrev_i32_e32 v99, 31, v98
	v_lshlrev_b64 v[96:97], 3, v[98:99]
	v_lshl_add_u64 v[100:101], s[12:13], 0, v[96:97]
	flat_load_dwordx2 v[118:119], v[100:101]
	v_lshlrev_b64 v[98:99], 12, v[98:99]
	v_lshl_add_u64 v[98:99], s[46:47], 0, v[98:99]
	v_lshl_add_u64 v[156:157], v[144:145], 2, v[98:99]
	global_load_dwordx4 v[98:101], v[156:157], off
	global_load_dwordx4 v[102:105], v[150:151], off
	global_load_dwordx4 v[106:109], v[152:153], off
	global_load_dwordx4 v[110:113], v[156:157], off offset:16
	global_load_dwordx4 v[194:197], v[156:157], off offset:512
	global_load_dwordx4 v[198:201], v[156:157], off offset:528
	s_waitcnt vmcnt(0) lgkmcnt(0)
	v_pk_mul_f32 v[118:119], v[118:119], s[22:23] op_sel:[1,0] op_sel_hi:[0,0]
	v_fma_f32 v115, -v119, v119, v118
	v_max_f32_e32 v115, 0, v115
	v_add_f32_e32 v115, 0x3727c5ac, v115
	v_mul_f32_e32 v117, 0x4b800000, v115
	v_cmp_gt_f32_e32 vcc, s55, v115
	v_sub_f32_e32 v99, v99, v119
	v_sub_f32_e32 v98, v98, v119
	v_cndmask_b32_e32 v115, v115, v117, vcc
	v_rsq_f32_e32 v115, v115
	v_sub_f32_e32 v101, v101, v119
	v_sub_f32_e32 v100, v100, v119
	v_sub_f32_e32 v111, v111, v119
	v_mul_f32_e32 v117, 0x45800000, v115
	v_cndmask_b32_e32 v118, v115, v117, vcc
	v_pk_mul_f32 v[100:101], v[100:101], v[118:119] op_sel_hi:[1,0]
	v_pk_mul_f32 v[98:99], v[98:99], v[118:119] op_sel_hi:[1,0]
	v_pk_fma_f32 v[100:101], v[104:105], v[100:101], v[108:109]
	v_pk_fma_f32 v[98:99], v[102:103], v[98:99], v[106:107]
	v_pk_fma_f32 v[94:95], v[100:101], s[24:25], v[94:95] op_sel_hi:[1,0,1]
	v_pk_fma_f32 v[92:93], v[98:99], s[24:25], v[92:93] op_sel_hi:[1,0,1]
	global_store_dwordx4 v[156:157], v[92:95], off
	global_load_dwordx4 v[98:101], v[146:147], off
	global_load_dwordx4 v[102:105], v[148:149], off
	v_sub_f32_e32 v110, v110, v119
	v_sub_f32_e32 v113, v113, v119
	v_sub_f32_e32 v112, v112, v119
	v_pk_mul_f32 v[112:113], v[112:113], v[118:119] op_sel_hi:[1,0]
	v_pk_mul_f32 v[110:111], v[110:111], v[118:119] op_sel_hi:[1,0]
	s_waitcnt vmcnt(0)
	v_pk_fma_f32 v[100:101], v[100:101], v[112:113], v[104:105]
	v_pk_fma_f32 v[98:99], v[98:99], v[110:111], v[102:103]
	v_pk_fma_f32 v[90:91], v[100:101], s[24:25], v[90:91] op_sel_hi:[1,0,1]
	v_pk_fma_f32 v[88:89], v[98:99], s[24:25], v[88:89] op_sel_hi:[1,0,1]
	global_store_dwordx4 v[156:157], v[88:91], off offset:16
	global_load_dwordx4 v[98:101], v[124:125], off
	global_load_dwordx4 v[102:105], v[126:127], off
	s_waitcnt vmcnt(2)
	v_sub_f32_e32 v107, v195, v119
	v_sub_f32_e32 v106, v194, v119
	v_sub_f32_e32 v109, v197, v119
	v_sub_f32_e32 v108, v196, v119
	v_pk_mul_f32 v[108:109], v[118:119], v[108:109] op_sel_hi:[0,1]
	v_pk_mul_f32 v[106:107], v[118:119], v[106:107] op_sel_hi:[0,1]
	s_waitcnt vmcnt(0)
	v_pk_fma_f32 v[98:99], v[98:99], v[106:107], v[102:103]
	v_pk_fma_f32 v[100:101], v[100:101], v[108:109], v[104:105]
	v_pk_fma_f32 v[84:85], v[98:99], s[24:25], v[84:85] op_sel_hi:[1,0,1]
	v_pk_fma_f32 v[86:87], v[100:101], s[24:25], v[86:87] op_sel_hi:[1,0,1]
	global_store_dwordx4 v[156:157], v[84:87], off offset:512
	global_load_dwordx4 v[98:101], v[120:121], off
	global_load_dwordx4 v[102:105], v[122:123], off
	s_waitcnt vmcnt(1)
	v_sub_f32_e32 v106, v198, v119
	v_add_f32_e32 v110, v92, v93
	v_mul_f32_e32 v93, v93, v93
	v_fmac_f32_e32 v93, v92, v92
	v_add_f32_e32 v110, v94, v110
	v_fmac_f32_e32 v93, v94, v94
	v_add_f32_e32 v94, v88, v89
	v_mul_f32_e32 v89, v89, v89
	v_fmac_f32_e32 v89, v88, v88
	v_add_f32_e32 v94, v90, v94
	v_fmac_f32_e32 v89, v90, v90
	v_add_f32_e32 v90, v84, v85
	v_mul_f32_e32 v85, v85, v85
	v_add_f32_e32 v92, v95, v110
	v_fmac_f32_e32 v85, v84, v84
	v_sub_f32_e32 v107, v199, v119
	v_add_f32_e32 v92, 0, v92
	v_fmac_f32_e32 v93, v95, v95
	v_add_f32_e32 v88, v91, v94
	v_fmac_f32_e32 v89, v91, v91
	v_add_f32_e32 v90, v86, v90
	v_fmac_f32_e32 v85, v86, v86
	v_pk_mul_f32 v[106:107], v[118:119], v[106:107] op_sel_hi:[0,1]
	v_add_f32_e32 v88, v88, v92
	v_add_f32_e32 v89, v93, v89
	v_add_f32_e32 v84, v87, v90
	v_fmac_f32_e32 v85, v87, v87
	v_sub_f32_e32 v109, v201, v119
	v_sub_f32_e32 v108, v200, v119
	v_add_f32_e32 v88, v88, v84
	v_add_f32_e32 v89, v89, v85
	v_pk_mul_f32 v[108:109], v[118:119], v[108:109] op_sel_hi:[0,1]
	s_waitcnt vmcnt(0)
	v_pk_fma_f32 v[84:85], v[98:99], v[106:107], v[102:103]
	s_nop 0
	v_pk_fma_f32 v[84:85], v[84:85], s[24:25], v[80:81] op_sel_hi:[1,0,1]
	v_pk_fma_f32 v[86:87], v[100:101], v[108:109], v[104:105]
	v_mul_f32_e32 v81, v85, v85
	v_pk_fma_f32 v[86:87], v[86:87], s[24:25], v[82:83] op_sel_hi:[1,0,1]
	v_add_f32_e32 v80, v84, v85
	v_fmac_f32_e32 v81, v84, v84
	v_add_f32_e32 v80, v86, v80
	v_fmac_f32_e32 v81, v86, v86
	v_add_f32_e32 v80, v87, v80
	v_fmac_f32_e32 v81, v87, v87
	v_add_f32_e32 v80, v88, v80
	v_add_f32_e32 v81, v89, v81
	ds_bpermute_b32 v82, v116, v80
	ds_bpermute_b32 v83, v116, v81
	global_store_dwordx4 v[156:157], v[84:87], off offset:528
	s_waitcnt lgkmcnt(1)
	v_add_f32_e32 v80, v80, v82
	s_waitcnt lgkmcnt(0)
	v_add_f32_e32 v81, v81, v83
	ds_bpermute_b32 v82, v114, v80
	ds_bpermute_b32 v83, v114, v81
	s_and_saveexec_b64 s[28:29], s[2:3]
	s_cbranch_execz .LBB0_2851
	v_lshl_add_u64 v[84:85], s[10:11], 0, v[96:97]
	s_waitcnt lgkmcnt(1)
	v_add_f32_e32 v80, v80, v82
	s_waitcnt lgkmcnt(0)
	v_add_f32_e32 v81, v81, v83
	flat_atomic_add_f32 v[84:85], v80
	flat_atomic_add_f32 v[84:85], v81 offset:4
; DEVI unsigned pk2(float lo, float hi) { unsigned r; asm("v_cvt_pk_bf16_f32 %0, %1, %2" : "=v"(r) : "v"(lo), "v"(hi)); return r; }
; DEVI void row_stats(const float* stats, int row, float& mu, float& rs) {
;     if (stats) { const float2 st = *(const float2*)(stats + 2 * (size_t)row); mu = st.x * (1.0f / 1024.0f); const float var = st.y * (1.0f / 1024.0f) - mu * mu; rs = rsqrtf(fmaxf(var, 0.f) + LN_EPS); }
;     else { mu = 0.f; rs = 1.f; }
;     DEVI void operator()(const f32x4 (&acc)[2][2][4][2], const pg8::Unit& u, int wr, int wc, int fr, int fq) const {
;     ...
;                 const int row = row0 + ai * 128 + m * 16; float mu, rs; row_stats(stin, row, mu, rs);
;                 float sum = 0.f, sq = 0.f;
; #pragma unroll
;                 for (int bj = 0; bj < 2; ++bj) {
;                     f32x4 z[2];
; #pragma unroll
;                     for (int n = 0; n < 2; ++n) {
;                         const int col = colb + bj * 128 + 4 * n;
;                         f32x4 xv = *(const f32x4*)(zsrc + (size_t)row * DM + col);
;                         if (stin) { const f32x4 gv = *(const f32x4*)(gin + col), bv = *(const f32x4*)(bin + col); xv = (xv - mu) * rs * gv + bv; }
;                         f32x4 zz = ALPHA * xv + acc[ai][bj][m][n];
;                         if (bias) zz += *(const f32x4*)(bias + col);
;                         *(f32x4*)(zdst + (size_t)row * DM + col) = zz;
;                         sum += zz[0] + zz[1] + zz[2] + zz[3]; sq += zz[0] * zz[0] + zz[1] * zz[1] + zz[2] * zz[2] + zz[3] * zz[3];
;                         z[n] = zz;
;                     }
;                     u32x4 o; o.x = pk2(z[0][0], z[0][1]); o.y = pk2(z[0][2], z[0][3]); o.z = pk2(z[1][0], z[1][1]); o.w = pk2(z[1][2], z[1][3]);
;                     if (zb) *(u32x4*)(zb + (size_t)row * DM + colb + bj * 128) = o;
;                 }
;                 sum += __shfl_xor(sum, 16); sq += __shfl_xor(sq, 16);
;                 sum += __shfl_xor(sum, 32); sq += __shfl_xor(sq, 32);
;                 if (fq == 0) { atomicAdd(stout + 2 * (size_t)row, sum); atomicAdd(stout + 2 * (size_t)row + 1, sq); }
.LBB0_2851:
	s_or_b64 exec, exec, s[28:29]
	s_waitcnt lgkmcnt(0)
	v_or_b32_e32 v82, 48, v154
	v_ashrrev_i32_e32 v83, 31, v82
	v_lshlrev_b64 v[80:81], 3, v[82:83]
	v_lshl_add_u64 v[84:85], s[12:13], 0, v[80:81]
	flat_load_dwordx2 v[98:99], v[84:85]
	v_lshlrev_b64 v[82:83], 12, v[82:83]
	v_lshl_add_u64 v[82:83], s[46:47], 0, v[82:83]
	v_lshl_add_u64 v[100:101], v[144:145], 2, v[82:83]
	global_load_dwordx4 v[82:85], v[100:101], off
	global_load_dwordx4 v[86:89], v[150:151], off
	global_load_dwordx4 v[90:93], v[152:153], off
	global_load_dwordx4 v[94:97], v[100:101], off offset:16
	global_load_dwordx4 v[194:197], v[100:101], off offset:512
	global_load_dwordx4 v[198:201], v[100:101], off offset:528
	s_waitcnt vmcnt(0) lgkmcnt(0)
	v_pk_mul_f32 v[98:99], v[98:99], s[22:23] op_sel:[1,0] op_sel_hi:[0,0]
	v_fma_f32 v98, -v99, v99, v98
	v_max_f32_e32 v98, 0, v98
	v_add_f32_e32 v98, 0x3727c5ac, v98
	v_mul_f32_e32 v102, 0x4b800000, v98
	v_cmp_gt_f32_e32 vcc, s55, v98
	v_sub_f32_e32 v83, v83, v99
	v_sub_f32_e32 v82, v82, v99
	v_cndmask_b32_e32 v98, v98, v102, vcc
	v_rsq_f32_e32 v98, v98
	v_sub_f32_e32 v85, v85, v99
	v_sub_f32_e32 v84, v84, v99
	v_sub_f32_e32 v95, v95, v99
	v_mul_f32_e32 v102, 0x45800000, v98
	v_cndmask_b32_e32 v98, v98, v102, vcc
	v_pk_mul_f32 v[84:85], v[84:85], v[98:99] op_sel_hi:[1,0]
	v_pk_mul_f32 v[82:83], v[82:83], v[98:99] op_sel_hi:[1,0]
	v_pk_fma_f32 v[84:85], v[88:89], v[84:85], v[92:93]
	v_pk_fma_f32 v[82:83], v[86:87], v[82:83], v[90:91]
	v_pk_fma_f32 v[78:79], v[84:85], s[24:25], v[78:79] op_sel_hi:[1,0,1]
	v_pk_fma_f32 v[76:77], v[82:83], s[24:25], v[76:77] op_sel_hi:[1,0,1]
	global_store_dwordx4 v[100:101], v[76:79], off
	global_load_dwordx4 v[82:85], v[146:147], off
	global_load_dwordx4 v[86:89], v[148:149], off
	v_sub_f32_e32 v94, v94, v99
	v_sub_f32_e32 v97, v97, v99
	v_sub_f32_e32 v96, v96, v99
	v_pk_mul_f32 v[96:97], v[96:97], v[98:99] op_sel_hi:[1,0]
	v_pk_mul_f32 v[94:95], v[94:95], v[98:99] op_sel_hi:[1,0]
	s_waitcnt vmcnt(0)
	v_pk_fma_f32 v[84:85], v[84:85], v[96:97], v[88:89]
	v_pk_fma_f32 v[82:83], v[82:83], v[94:95], v[86:87]
	v_pk_fma_f32 v[74:75], v[84:85], s[24:25], v[74:75] op_sel_hi:[1,0,1]
	v_pk_fma_f32 v[72:73], v[82:83], s[24:25], v[72:73] op_sel_hi:[1,0,1]
	global_store_dwordx4 v[100:101], v[72:75], off offset:16
	global_load_dwordx4 v[82:85], v[124:125], off
	global_load_dwordx4 v[86:89], v[126:127], off
	s_waitcnt vmcnt(2)
	v_sub_f32_e32 v91, v195, v99
	v_sub_f32_e32 v90, v194, v99
	v_sub_f32_e32 v93, v197, v99
	v_sub_f32_e32 v92, v196, v99
	v_pk_mul_f32 v[92:93], v[98:99], v[92:93] op_sel_hi:[0,1]
	v_pk_mul_f32 v[90:91], v[98:99], v[90:91] op_sel_hi:[0,1]
	s_waitcnt vmcnt(0)
	v_pk_fma_f32 v[82:83], v[82:83], v[90:91], v[86:87]
	v_pk_fma_f32 v[84:85], v[84:85], v[92:93], v[88:89]
	v_pk_fma_f32 v[68:69], v[82:83], s[24:25], v[68:69] op_sel_hi:[1,0,1]
	v_pk_fma_f32 v[70:71], v[84:85], s[24:25], v[70:71] op_sel_hi:[1,0,1]
	global_store_dwordx4 v[100:101], v[68:71], off offset:512
	global_load_dwordx4 v[82:85], v[120:121], off
	global_load_dwordx4 v[86:89], v[122:123], off
	s_waitcnt vmcnt(1)
	v_sub_f32_e32 v90, v198, v99
	v_add_f32_e32 v94, v76, v77
	v_mul_f32_e32 v77, v77, v77
	v_fmac_f32_e32 v77, v76, v76
	v_add_f32_e32 v94, v78, v94
	v_fmac_f32_e32 v77, v78, v78
	v_add_f32_e32 v78, v72, v73
	v_mul_f32_e32 v73, v73, v73
	v_fmac_f32_e32 v73, v72, v72
	v_add_f32_e32 v78, v74, v78
	v_fmac_f32_e32 v73, v74, v74
	v_add_f32_e32 v74, v68, v69
	v_mul_f32_e32 v69, v69, v69
	v_add_f32_e32 v76, v79, v94
	v_fmac_f32_e32 v69, v68, v68
	v_sub_f32_e32 v91, v199, v99
	v_add_f32_e32 v76, 0, v76
	v_fmac_f32_e32 v77, v79, v79
	v_add_f32_e32 v72, v75, v78
	v_fmac_f32_e32 v73, v75, v75
	v_add_f32_e32 v74, v70, v74
	v_fmac_f32_e32 v69, v70, v70
	v_pk_mul_f32 v[90:91], v[98:99], v[90:91] op_sel_hi:[0,1]
	v_add_f32_e32 v72, v72, v76
	v_add_f32_e32 v73, v77, v73
	v_add_f32_e32 v68, v71, v74
	v_fmac_f32_e32 v69, v71, v71
	v_sub_f32_e32 v93, v201, v99
	v_sub_f32_e32 v92, v200, v99
	v_add_f32_e32 v72, v72, v68
	v_add_f32_e32 v73, v73, v69
	v_pk_mul_f32 v[92:93], v[98:99], v[92:93] op_sel_hi:[0,1]
	s_waitcnt vmcnt(0)
	v_pk_fma_f32 v[68:69], v[82:83], v[90:91], v[86:87]
	s_nop 0
	v_pk_fma_f32 v[68:69], v[68:69], s[24:25], v[64:65] op_sel_hi:[1,0,1]
	v_pk_fma_f32 v[70:71], v[84:85], v[92:93], v[88:89]
	v_mul_f32_e32 v65, v69, v69
	v_pk_fma_f32 v[70:71], v[70:71], s[24:25], v[66:67] op_sel_hi:[1,0,1]
	v_add_f32_e32 v64, v68, v69
	v_fmac_f32_e32 v65, v68, v68
	v_add_f32_e32 v64, v70, v64
	v_fmac_f32_e32 v65, v70, v70
	v_add_f32_e32 v64, v71, v64
	v_fmac_f32_e32 v65, v71, v71
	v_add_f32_e32 v64, v72, v64
	v_add_f32_e32 v65, v73, v65
	ds_bpermute_b32 v66, v116, v64
	ds_bpermute_b32 v67, v116, v65
	global_store_dwordx4 v[100:101], v[68:71], off offset:528
	s_waitcnt lgkmcnt(1)
	v_add_f32_e32 v64, v64, v66
	s_waitcnt lgkmcnt(0)
	v_add_f32_e32 v65, v65, v67
	ds_bpermute_b32 v66, v114, v64
	ds_bpermute_b32 v67, v114, v65
	s_and_saveexec_b64 s[28:29], s[2:3]
	s_cbranch_execz .LBB0_2853
	v_lshl_add_u64 v[68:69], s[10:11], 0, v[80:81]
	s_waitcnt lgkmcnt(1)
	v_add_f32_e32 v64, v64, v66
	s_waitcnt lgkmcnt(0)
	v_add_f32_e32 v65, v65, v67
	flat_atomic_add_f32 v[68:69], v64
	flat_atomic_add_f32 v[68:69], v65 offset:4
; DEVI unsigned pk2(float lo, float hi) { unsigned r; asm("v_cvt_pk_bf16_f32 %0, %1, %2" : "=v"(r) : "v"(lo), "v"(hi)); return r; }
;     DEVI void operator()(const f32x4 (&acc)[2][2][4][2], const pg8::Unit& u, int wr, int wc, int fr, int fq) const {
;     ...
;                 const int row = row0 + ai * 128 + m * 16; float mu, rs; row_stats(stin, row, mu, rs);
;                 float sum = 0.f, sq = 0.f;
; #pragma unroll
;                 for (int bj = 0; bj < 2; ++bj) {
;                     f32x4 z[2];
; #pragma unroll
;                     for (int n = 0; n < 2; ++n) {
;                         const int col = colb + bj * 128 + 4 * n;
;                         f32x4 xv = *(const f32x4*)(zsrc + (size_t)row * DM + col);
;                         if (stin) { const f32x4 gv = *(const f32x4*)(gin + col), bv = *(const f32x4*)(bin + col); xv = (xv - mu) * rs * gv + bv; }
;                         f32x4 zz = ALPHA * xv + acc[ai][bj][m][n];
;                         if (bias) zz += *(const f32x4*)(bias + col);
;                         *(f32x4*)(zdst + (size_t)row * DM + col) = zz;
;                         sum += zz[0] + zz[1] + zz[2] + zz[3]; sq += zz[0] * zz[0] + zz[1] * zz[1] + zz[2] * zz[2] + zz[3] * zz[3];
;                         z[n] = zz;
;                     }
;                     u32x4 o; o.x = pk2(z[0][0], z[0][1]); o.y = pk2(z[0][2], z[0][3]); o.z = pk2(z[1][0], z[1][1]); o.w = pk2(z[1][2], z[1][3]);
;                     if (zb) *(u32x4*)(zb + (size_t)row * DM + colb + bj * 128) = o;
;                 }
;                 sum += __shfl_xor(sum, 16); sq += __shfl_xor(sq, 16);
;                 sum += __shfl_xor(sum, 32); sq += __shfl_xor(sq, 32);
;                 if (fq == 0) { atomicAdd(stout + 2 * (size_t)row, sum); atomicAdd(stout + 2 * (size_t)row + 1, sq); }
.LBB0_2853:
	s_or_b64 exec, exec, s[28:29]
	s_waitcnt lgkmcnt(0)
	v_add_u32_e32 v66, 0x80, v154
	v_ashrrev_i32_e32 v67, 31, v66
	v_lshlrev_b64 v[64:65], 3, v[66:67]
	v_lshl_add_u64 v[68:69], s[12:13], 0, v[64:65]
	flat_load_dwordx2 v[82:83], v[68:69]
	v_lshlrev_b64 v[66:67], 12, v[66:67]
	v_lshl_add_u64 v[66:67], s[46:47], 0, v[66:67]
	v_lshl_add_u64 v[84:85], v[144:145], 2, v[66:67]
	global_load_dwordx4 v[66:69], v[84:85], off
	global_load_dwordx4 v[70:73], v[150:151], off
	global_load_dwordx4 v[74:77], v[152:153], off
	global_load_dwordx4 v[78:81], v[84:85], off offset:16
	global_load_dwordx4 v[194:197], v[84:85], off offset:512
	global_load_dwordx4 v[198:201], v[84:85], off offset:528
	s_waitcnt vmcnt(0) lgkmcnt(0)
	v_pk_mul_f32 v[82:83], v[82:83], s[22:23] op_sel:[1,0] op_sel_hi:[0,0]
	v_fma_f32 v82, -v83, v83, v82
	v_max_f32_e32 v82, 0, v82
	v_add_f32_e32 v82, 0x3727c5ac, v82
	v_mul_f32_e32 v86, 0x4b800000, v82
	v_cmp_gt_f32_e32 vcc, s55, v82
	v_sub_f32_e32 v67, v67, v83
	v_sub_f32_e32 v66, v66, v83
	v_cndmask_b32_e32 v82, v82, v86, vcc
	v_rsq_f32_e32 v82, v82
	v_sub_f32_e32 v69, v69, v83
	v_sub_f32_e32 v68, v68, v83
	v_sub_f32_e32 v79, v79, v83
	v_mul_f32_e32 v86, 0x45800000, v82
	v_cndmask_b32_e32 v82, v82, v86, vcc
	v_pk_mul_f32 v[68:69], v[68:69], v[82:83] op_sel_hi:[1,0]
	v_pk_mul_f32 v[66:67], v[66:67], v[82:83] op_sel_hi:[1,0]
	v_pk_fma_f32 v[68:69], v[72:73], v[68:69], v[76:77]
	v_pk_fma_f32 v[66:67], v[70:71], v[66:67], v[74:75]
	v_pk_fma_f32 v[62:63], v[68:69], s[24:25], v[62:63] op_sel_hi:[1,0,1]
	v_pk_fma_f32 v[60:61], v[66:67], s[24:25], v[60:61] op_sel_hi:[1,0,1]
	global_store_dwordx4 v[84:85], v[60:63], off
	global_load_dwordx4 v[66:69], v[146:147], off
	global_load_dwordx4 v[70:73], v[148:149], off
	v_sub_f32_e32 v78, v78, v83
	v_sub_f32_e32 v81, v81, v83
	v_sub_f32_e32 v80, v80, v83
	v_pk_mul_f32 v[80:81], v[80:81], v[82:83] op_sel_hi:[1,0]
	v_pk_mul_f32 v[78:79], v[78:79], v[82:83] op_sel_hi:[1,0]
	s_waitcnt vmcnt(0)
	v_pk_fma_f32 v[68:69], v[68:69], v[80:81], v[72:73]
	v_pk_fma_f32 v[66:67], v[66:67], v[78:79], v[70:71]
	v_pk_fma_f32 v[58:59], v[68:69], s[24:25], v[58:59] op_sel_hi:[1,0,1]
	v_pk_fma_f32 v[56:57], v[66:67], s[24:25], v[56:57] op_sel_hi:[1,0,1]
	global_store_dwordx4 v[84:85], v[56:59], off offset:16
	global_load_dwordx4 v[66:69], v[124:125], off
	global_load_dwordx4 v[70:73], v[126:127], off
	s_waitcnt vmcnt(2)
	v_sub_f32_e32 v75, v195, v83
	v_sub_f32_e32 v74, v194, v83
	v_sub_f32_e32 v77, v197, v83
	v_sub_f32_e32 v76, v196, v83
	v_pk_mul_f32 v[76:77], v[82:83], v[76:77] op_sel_hi:[0,1]
	v_pk_mul_f32 v[74:75], v[82:83], v[74:75] op_sel_hi:[0,1]
	s_waitcnt vmcnt(0)
	v_pk_fma_f32 v[66:67], v[66:67], v[74:75], v[70:71]
	v_pk_fma_f32 v[68:69], v[68:69], v[76:77], v[72:73]
	v_pk_fma_f32 v[52:53], v[66:67], s[24:25], v[52:53] op_sel_hi:[1,0,1]
	v_pk_fma_f32 v[54:55], v[68:69], s[24:25], v[54:55] op_sel_hi:[1,0,1]
	global_store_dwordx4 v[84:85], v[52:55], off offset:512
	global_load_dwordx4 v[66:69], v[120:121], off
	global_load_dwordx4 v[70:73], v[122:123], off
	s_waitcnt vmcnt(1)
	v_sub_f32_e32 v74, v198, v83
	v_add_f32_e32 v78, v60, v61
	v_mul_f32_e32 v61, v61, v61
	v_fmac_f32_e32 v61, v60, v60
	v_add_f32_e32 v78, v62, v78
	v_fmac_f32_e32 v61, v62, v62
	v_add_f32_e32 v62, v56, v57
	v_mul_f32_e32 v57, v57, v57
	v_fmac_f32_e32 v57, v56, v56
	v_add_f32_e32 v62, v58, v62
	v_fmac_f32_e32 v57, v58, v58
	v_add_f32_e32 v58, v52, v53
	v_mul_f32_e32 v53, v53, v53
	v_add_f32_e32 v60, v63, v78
	v_fmac_f32_e32 v53, v52, v52
	v_sub_f32_e32 v75, v199, v83
	v_add_f32_e32 v60, 0, v60
	v_fmac_f32_e32 v61, v63, v63
	v_add_f32_e32 v56, v59, v62
	v_fmac_f32_e32 v57, v59, v59
	v_add_f32_e32 v58, v54, v58
	v_fmac_f32_e32 v53, v54, v54
	v_pk_mul_f32 v[74:75], v[82:83], v[74:75] op_sel_hi:[0,1]
	v_add_f32_e32 v56, v56, v60
	v_add_f32_e32 v57, v61, v57
	v_add_f32_e32 v52, v55, v58
	v_fmac_f32_e32 v53, v55, v55
	v_sub_f32_e32 v77, v201, v83
	v_sub_f32_e32 v76, v200, v83
	v_add_f32_e32 v56, v56, v52
	v_add_f32_e32 v57, v57, v53
	v_pk_mul_f32 v[76:77], v[82:83], v[76:77] op_sel_hi:[0,1]
	s_waitcnt vmcnt(0)
	v_pk_fma_f32 v[52:53], v[66:67], v[74:75], v[70:71]
	s_nop 0
	v_pk_fma_f32 v[52:53], v[52:53], s[24:25], v[48:49] op_sel_hi:[1,0,1]
	v_pk_fma_f32 v[54:55], v[68:69], v[76:77], v[72:73]
	v_mul_f32_e32 v49, v53, v53
	v_pk_fma_f32 v[54:55], v[54:55], s[24:25], v[50:51] op_sel_hi:[1,0,1]
	v_add_f32_e32 v48, v52, v53
	v_fmac_f32_e32 v49, v52, v52
	v_add_f32_e32 v48, v54, v48
	v_fmac_f32_e32 v49, v54, v54
	v_add_f32_e32 v48, v55, v48
	v_fmac_f32_e32 v49, v55, v55
	v_add_f32_e32 v48, v56, v48
	v_add_f32_e32 v49, v57, v49
	ds_bpermute_b32 v50, v116, v48
	ds_bpermute_b32 v51, v116, v49
	global_store_dwordx4 v[84:85], v[52:55], off offset:528
	s_waitcnt lgkmcnt(1)
	v_add_f32_e32 v48, v48, v50
	s_waitcnt lgkmcnt(0)
	v_add_f32_e32 v49, v49, v51
	ds_bpermute_b32 v50, v114, v48
	ds_bpermute_b32 v51, v114, v49
	s_and_saveexec_b64 s[28:29], s[2:3]
	s_cbranch_execz .LBB0_2855
	v_lshl_add_u64 v[52:53], s[10:11], 0, v[64:65]
	s_waitcnt lgkmcnt(1)
	v_add_f32_e32 v48, v48, v50
	s_waitcnt lgkmcnt(0)
	v_add_f32_e32 v49, v49, v51
	flat_atomic_add_f32 v[52:53], v48
	flat_atomic_add_f32 v[52:53], v49 offset:4
; DEVI unsigned pk2(float lo, float hi) { unsigned r; asm("v_cvt_pk_bf16_f32 %0, %1, %2" : "=v"(r) : "v"(lo), "v"(hi)); return r; }
;     DEVI void operator()(const f32x4 (&acc)[2][2][4][2], const pg8::Unit& u, int wr, int wc, int fr, int fq) const {
;     ...
;                 const int row = row0 + ai * 128 + m * 16; float mu, rs; row_stats(stin, row, mu, rs);
;                 float sum = 0.f, sq = 0.f;
; #pragma unroll
;                 for (int bj = 0; bj < 2; ++bj) {
;                     f32x4 z[2];
; #pragma unroll
;                     for (int n = 0; n < 2; ++n) {
;                         const int col = colb + bj * 128 + 4 * n;
;                         f32x4 xv = *(const f32x4*)(zsrc + (size_t)row * DM + col);
;                         if (stin) { const f32x4 gv = *(const f32x4*)(gin + col), bv = *(const f32x4*)(bin + col); xv = (xv - mu) * rs * gv + bv; }
;                         f32x4 zz = ALPHA * xv + acc[ai][bj][m][n];
;                         if (bias) zz += *(const f32x4*)(bias + col);
;                         *(f32x4*)(zdst + (size_t)row * DM + col) = zz;
;                         sum += zz[0] + zz[1] + zz[2] + zz[3]; sq += zz[0] * zz[0] + zz[1] * zz[1] + zz[2] * zz[2] + zz[3] * zz[3];
;                         z[n] = zz;
;                     }
;                     u32x4 o; o.x = pk2(z[0][0], z[0][1]); o.y = pk2(z[0][2], z[0][3]); o.z = pk2(z[1][0], z[1][1]); o.w = pk2(z[1][2], z[1][3]);
;                     if (zb) *(u32x4*)(zb + (size_t)row * DM + colb + bj * 128) = o;
;                 }
;                 sum += __shfl_xor(sum, 16); sq += __shfl_xor(sq, 16);
;                 sum += __shfl_xor(sum, 32); sq += __shfl_xor(sq, 32);
;                 if (fq == 0) { atomicAdd(stout + 2 * (size_t)row, sum); atomicAdd(stout + 2 * (size_t)row + 1, sq); }
.LBB0_2855:
	s_or_b64 exec, exec, s[28:29]
	s_waitcnt lgkmcnt(0)
	v_add_u32_e32 v50, 0x90, v154
	v_ashrrev_i32_e32 v51, 31, v50
	v_lshlrev_b64 v[48:49], 3, v[50:51]
	v_lshl_add_u64 v[52:53], s[12:13], 0, v[48:49]
	flat_load_dwordx2 v[66:67], v[52:53]
	v_lshlrev_b64 v[50:51], 12, v[50:51]
	v_lshl_add_u64 v[50:51], s[46:47], 0, v[50:51]
	v_lshl_add_u64 v[68:69], v[144:145], 2, v[50:51]
	global_load_dwordx4 v[50:53], v[68:69], off
	global_load_dwordx4 v[54:57], v[150:151], off
	global_load_dwordx4 v[58:61], v[152:153], off
	global_load_dwordx4 v[62:65], v[68:69], off offset:16
	global_load_dwordx4 v[194:197], v[68:69], off offset:512
	global_load_dwordx4 v[198:201], v[68:69], off offset:528
	s_waitcnt vmcnt(0) lgkmcnt(0)
	v_pk_mul_f32 v[66:67], v[66:67], s[22:23] op_sel:[1,0] op_sel_hi:[0,0]
	v_fma_f32 v66, -v67, v67, v66
	v_max_f32_e32 v66, 0, v66
	v_add_f32_e32 v66, 0x3727c5ac, v66
	v_mul_f32_e32 v70, 0x4b800000, v66
	v_cmp_gt_f32_e32 vcc, s55, v66
	v_sub_f32_e32 v51, v51, v67
	v_sub_f32_e32 v50, v50, v67
	v_cndmask_b32_e32 v66, v66, v70, vcc
	v_rsq_f32_e32 v66, v66
	v_sub_f32_e32 v53, v53, v67
	v_sub_f32_e32 v52, v52, v67
	v_sub_f32_e32 v63, v63, v67
	v_mul_f32_e32 v70, 0x45800000, v66
	v_cndmask_b32_e32 v66, v66, v70, vcc
	v_pk_mul_f32 v[52:53], v[52:53], v[66:67] op_sel_hi:[1,0]
	v_pk_mul_f32 v[50:51], v[50:51], v[66:67] op_sel_hi:[1,0]
	v_pk_fma_f32 v[52:53], v[56:57], v[52:53], v[60:61]
	v_pk_fma_f32 v[50:51], v[54:55], v[50:51], v[58:59]
	v_pk_fma_f32 v[46:47], v[52:53], s[24:25], v[46:47] op_sel_hi:[1,0,1]
	v_pk_fma_f32 v[44:45], v[50:51], s[24:25], v[44:45] op_sel_hi:[1,0,1]
	global_store_dwordx4 v[68:69], v[44:47], off
	global_load_dwordx4 v[50:53], v[146:147], off
	global_load_dwordx4 v[54:57], v[148:149], off
	v_sub_f32_e32 v62, v62, v67
	v_sub_f32_e32 v65, v65, v67
	v_sub_f32_e32 v64, v64, v67
	v_pk_mul_f32 v[64:65], v[64:65], v[66:67] op_sel_hi:[1,0]
	v_pk_mul_f32 v[62:63], v[62:63], v[66:67] op_sel_hi:[1,0]
	s_waitcnt vmcnt(0)
	v_pk_fma_f32 v[52:53], v[52:53], v[64:65], v[56:57]
	v_pk_fma_f32 v[50:51], v[50:51], v[62:63], v[54:55]
	v_pk_fma_f32 v[42:43], v[52:53], s[24:25], v[42:43] op_sel_hi:[1,0,1]
	v_pk_fma_f32 v[40:41], v[50:51], s[24:25], v[40:41] op_sel_hi:[1,0,1]
	global_store_dwordx4 v[68:69], v[40:43], off offset:16
	global_load_dwordx4 v[50:53], v[124:125], off
	global_load_dwordx4 v[54:57], v[126:127], off
	s_waitcnt vmcnt(2)
	v_sub_f32_e32 v59, v195, v67
	v_sub_f32_e32 v58, v194, v67
	v_sub_f32_e32 v61, v197, v67
	v_sub_f32_e32 v60, v196, v67
	v_pk_mul_f32 v[60:61], v[66:67], v[60:61] op_sel_hi:[0,1]
	v_pk_mul_f32 v[58:59], v[66:67], v[58:59] op_sel_hi:[0,1]
	s_waitcnt vmcnt(0)
	v_pk_fma_f32 v[50:51], v[50:51], v[58:59], v[54:55]
	v_pk_fma_f32 v[52:53], v[52:53], v[60:61], v[56:57]
	v_pk_fma_f32 v[36:37], v[50:51], s[24:25], v[36:37] op_sel_hi:[1,0,1]
	v_pk_fma_f32 v[38:39], v[52:53], s[24:25], v[38:39] op_sel_hi:[1,0,1]
	global_store_dwordx4 v[68:69], v[36:39], off offset:512
	global_load_dwordx4 v[50:53], v[120:121], off
	global_load_dwordx4 v[54:57], v[122:123], off
	s_waitcnt vmcnt(1)
	v_sub_f32_e32 v58, v198, v67
	v_add_f32_e32 v62, v44, v45
	v_mul_f32_e32 v45, v45, v45
	v_fmac_f32_e32 v45, v44, v44
	v_add_f32_e32 v62, v46, v62
	v_fmac_f32_e32 v45, v46, v46
	v_add_f32_e32 v46, v40, v41
	v_mul_f32_e32 v41, v41, v41
	v_fmac_f32_e32 v41, v40, v40
	v_add_f32_e32 v46, v42, v46
	v_fmac_f32_e32 v41, v42, v42
	v_add_f32_e32 v42, v36, v37
	v_mul_f32_e32 v37, v37, v37
	v_add_f32_e32 v44, v47, v62
	v_fmac_f32_e32 v37, v36, v36
	v_sub_f32_e32 v59, v199, v67
	v_add_f32_e32 v44, 0, v44
	v_fmac_f32_e32 v45, v47, v47
	v_add_f32_e32 v40, v43, v46
	v_fmac_f32_e32 v41, v43, v43
	v_add_f32_e32 v42, v38, v42
	v_fmac_f32_e32 v37, v38, v38
	v_pk_mul_f32 v[58:59], v[66:67], v[58:59] op_sel_hi:[0,1]
	v_add_f32_e32 v40, v40, v44
	v_add_f32_e32 v41, v45, v41
	v_add_f32_e32 v36, v39, v42
	v_fmac_f32_e32 v37, v39, v39
	v_sub_f32_e32 v61, v201, v67
	v_sub_f32_e32 v60, v200, v67
	v_add_f32_e32 v40, v40, v36
	v_add_f32_e32 v41, v41, v37
	v_pk_mul_f32 v[60:61], v[66:67], v[60:61] op_sel_hi:[0,1]
	s_waitcnt vmcnt(0)
	v_pk_fma_f32 v[36:37], v[50:51], v[58:59], v[54:55]
	s_nop 0
	v_pk_fma_f32 v[36:37], v[36:37], s[24:25], v[32:33] op_sel_hi:[1,0,1]
	v_pk_fma_f32 v[38:39], v[52:53], v[60:61], v[56:57]
	v_mul_f32_e32 v33, v37, v37
	v_pk_fma_f32 v[38:39], v[38:39], s[24:25], v[34:35] op_sel_hi:[1,0,1]
	v_add_f32_e32 v32, v36, v37
	v_fmac_f32_e32 v33, v36, v36
	v_add_f32_e32 v32, v38, v32
	v_fmac_f32_e32 v33, v38, v38
	v_add_f32_e32 v32, v39, v32
	v_fmac_f32_e32 v33, v39, v39
	v_add_f32_e32 v32, v40, v32
	v_add_f32_e32 v33, v41, v33
	ds_bpermute_b32 v34, v116, v32
	ds_bpermute_b32 v35, v116, v33
	global_store_dwordx4 v[68:69], v[36:39], off offset:528
	s_waitcnt lgkmcnt(1)
	v_add_f32_e32 v32, v32, v34
	s_waitcnt lgkmcnt(0)
	v_add_f32_e32 v33, v33, v35
	ds_bpermute_b32 v34, v114, v32
	ds_bpermute_b32 v35, v114, v33
	s_and_saveexec_b64 s[28:29], s[2:3]
	s_cbranch_execz .LBB0_2857
	v_lshl_add_u64 v[36:37], s[10:11], 0, v[48:49]
	s_waitcnt lgkmcnt(1)
	v_add_f32_e32 v32, v32, v34
	s_waitcnt lgkmcnt(0)
	v_add_f32_e32 v33, v33, v35
	flat_atomic_add_f32 v[36:37], v32
	flat_atomic_add_f32 v[36:37], v33 offset:4
; DEVI unsigned pk2(float lo, float hi) { unsigned r; asm("v_cvt_pk_bf16_f32 %0, %1, %2" : "=v"(r) : "v"(lo), "v"(hi)); return r; }
;     DEVI void operator()(const f32x4 (&acc)[2][2][4][2], const pg8::Unit& u, int wr, int wc, int fr, int fq) const {
;     ...
;                 const int row = row0 + ai * 128 + m * 16; float mu, rs; row_stats(stin, row, mu, rs);
;                 float sum = 0.f, sq = 0.f;
; #pragma unroll
;                 for (int bj = 0; bj < 2; ++bj) {
;                     f32x4 z[2];
; #pragma unroll
;                     for (int n = 0; n < 2; ++n) {
;                         const int col = colb + bj * 128 + 4 * n;
;                         f32x4 xv = *(const f32x4*)(zsrc + (size_t)row * DM + col);
;                         if (stin) { const f32x4 gv = *(const f32x4*)(gin + col), bv = *(const f32x4*)(bin + col); xv = (xv - mu) * rs * gv + bv; }
;                         f32x4 zz = ALPHA * xv + acc[ai][bj][m][n];
;                         if (bias) zz += *(const f32x4*)(bias + col);
;                         *(f32x4*)(zdst + (size_t)row * DM + col) = zz;
;                         sum += zz[0] + zz[1] + zz[2] + zz[3]; sq += zz[0] * zz[0] + zz[1] * zz[1] + zz[2] * zz[2] + zz[3] * zz[3];
;                         z[n] = zz;
;                     }
;                     u32x4 o; o.x = pk2(z[0][0], z[0][1]); o.y = pk2(z[0][2], z[0][3]); o.z = pk2(z[1][0], z[1][1]); o.w = pk2(z[1][2], z[1][3]);
;                     if (zb) *(u32x4*)(zb + (size_t)row * DM + colb + bj * 128) = o;
;                 }
;                 sum += __shfl_xor(sum, 16); sq += __shfl_xor(sq, 16);
;                 sum += __shfl_xor(sum, 32); sq += __shfl_xor(sq, 32);
;                 if (fq == 0) { atomicAdd(stout + 2 * (size_t)row, sum); atomicAdd(stout + 2 * (size_t)row + 1, sq); }
.LBB0_2857:
	s_or_b64 exec, exec, s[28:29]
	s_waitcnt lgkmcnt(0)
	v_add_u32_e32 v34, 0xa0, v154
	v_ashrrev_i32_e32 v35, 31, v34
	v_lshlrev_b64 v[32:33], 3, v[34:35]
	v_lshl_add_u64 v[36:37], s[12:13], 0, v[32:33]
	flat_load_dwordx2 v[50:51], v[36:37]
	v_lshlrev_b64 v[34:35], 12, v[34:35]
	v_lshl_add_u64 v[34:35], s[46:47], 0, v[34:35]
	v_lshl_add_u64 v[52:53], v[144:145], 2, v[34:35]
	global_load_dwordx4 v[34:37], v[52:53], off
	global_load_dwordx4 v[38:41], v[150:151], off
	global_load_dwordx4 v[42:45], v[152:153], off
	global_load_dwordx4 v[46:49], v[52:53], off offset:16
	global_load_dwordx4 v[194:197], v[52:53], off offset:512
	global_load_dwordx4 v[198:201], v[52:53], off offset:528
	s_waitcnt vmcnt(0) lgkmcnt(0)
	v_pk_mul_f32 v[50:51], v[50:51], s[22:23] op_sel:[1,0] op_sel_hi:[0,0]
	v_fma_f32 v50, -v51, v51, v50
	v_max_f32_e32 v50, 0, v50
	v_add_f32_e32 v50, 0x3727c5ac, v50
	v_mul_f32_e32 v54, 0x4b800000, v50
	v_cmp_gt_f32_e32 vcc, s55, v50
	v_sub_f32_e32 v35, v35, v51
	v_sub_f32_e32 v34, v34, v51
	v_cndmask_b32_e32 v50, v50, v54, vcc
	v_rsq_f32_e32 v50, v50
	v_sub_f32_e32 v37, v37, v51
	v_sub_f32_e32 v36, v36, v51
	v_sub_f32_e32 v47, v47, v51
	v_mul_f32_e32 v54, 0x45800000, v50
	v_cndmask_b32_e32 v50, v50, v54, vcc
	v_pk_mul_f32 v[36:37], v[36:37], v[50:51] op_sel_hi:[1,0]
	v_pk_mul_f32 v[34:35], v[34:35], v[50:51] op_sel_hi:[1,0]
	v_pk_fma_f32 v[36:37], v[40:41], v[36:37], v[44:45]
	v_pk_fma_f32 v[34:35], v[38:39], v[34:35], v[42:43]
	v_pk_fma_f32 v[30:31], v[36:37], s[24:25], v[30:31] op_sel_hi:[1,0,1]
	v_pk_fma_f32 v[28:29], v[34:35], s[24:25], v[28:29] op_sel_hi:[1,0,1]
	global_store_dwordx4 v[52:53], v[28:31], off
	global_load_dwordx4 v[34:37], v[146:147], off
	global_load_dwordx4 v[38:41], v[148:149], off
	v_sub_f32_e32 v46, v46, v51
	v_sub_f32_e32 v49, v49, v51
	v_sub_f32_e32 v48, v48, v51
	v_pk_mul_f32 v[48:49], v[48:49], v[50:51] op_sel_hi:[1,0]
	v_pk_mul_f32 v[46:47], v[46:47], v[50:51] op_sel_hi:[1,0]
	s_waitcnt vmcnt(0)
	v_pk_fma_f32 v[36:37], v[36:37], v[48:49], v[40:41]
	v_pk_fma_f32 v[34:35], v[34:35], v[46:47], v[38:39]
	v_pk_fma_f32 v[26:27], v[36:37], s[24:25], v[26:27] op_sel_hi:[1,0,1]
	v_pk_fma_f32 v[24:25], v[34:35], s[24:25], v[24:25] op_sel_hi:[1,0,1]
	global_store_dwordx4 v[52:53], v[24:27], off offset:16
	global_load_dwordx4 v[34:37], v[124:125], off
	global_load_dwordx4 v[38:41], v[126:127], off
	s_waitcnt vmcnt(2)
	v_sub_f32_e32 v43, v195, v51
	v_sub_f32_e32 v42, v194, v51
	v_sub_f32_e32 v45, v197, v51
	v_sub_f32_e32 v44, v196, v51
	v_pk_mul_f32 v[44:45], v[50:51], v[44:45] op_sel_hi:[0,1]
	v_pk_mul_f32 v[42:43], v[50:51], v[42:43] op_sel_hi:[0,1]
	s_waitcnt vmcnt(0)
	v_pk_fma_f32 v[34:35], v[34:35], v[42:43], v[38:39]
	v_pk_fma_f32 v[36:37], v[36:37], v[44:45], v[40:41]
	v_pk_fma_f32 v[20:21], v[34:35], s[24:25], v[20:21] op_sel_hi:[1,0,1]
	v_pk_fma_f32 v[22:23], v[36:37], s[24:25], v[22:23] op_sel_hi:[1,0,1]
	global_store_dwordx4 v[52:53], v[20:23], off offset:512
	global_load_dwordx4 v[34:37], v[120:121], off
	global_load_dwordx4 v[38:41], v[122:123], off
	s_waitcnt vmcnt(1)
	v_sub_f32_e32 v42, v198, v51
	v_add_f32_e32 v46, v28, v29
	v_mul_f32_e32 v29, v29, v29
	v_fmac_f32_e32 v29, v28, v28
	v_add_f32_e32 v46, v30, v46
	v_fmac_f32_e32 v29, v30, v30
	v_add_f32_e32 v30, v24, v25
	v_mul_f32_e32 v25, v25, v25
	v_fmac_f32_e32 v25, v24, v24
	v_add_f32_e32 v30, v26, v30
	v_fmac_f32_e32 v25, v26, v26
	v_add_f32_e32 v26, v20, v21
	v_mul_f32_e32 v21, v21, v21
	v_add_f32_e32 v28, v31, v46
	v_fmac_f32_e32 v21, v20, v20
	v_sub_f32_e32 v43, v199, v51
	v_add_f32_e32 v28, 0, v28
	v_fmac_f32_e32 v29, v31, v31
	v_add_f32_e32 v24, v27, v30
	v_fmac_f32_e32 v25, v27, v27
	v_add_f32_e32 v26, v22, v26
	v_fmac_f32_e32 v21, v22, v22
	v_pk_mul_f32 v[42:43], v[50:51], v[42:43] op_sel_hi:[0,1]
	v_add_f32_e32 v24, v24, v28
	v_add_f32_e32 v25, v29, v25
	v_add_f32_e32 v20, v23, v26
	v_fmac_f32_e32 v21, v23, v23
	v_sub_f32_e32 v45, v201, v51
	v_sub_f32_e32 v44, v200, v51
	v_add_f32_e32 v24, v24, v20
	v_add_f32_e32 v25, v25, v21
	v_pk_mul_f32 v[44:45], v[50:51], v[44:45] op_sel_hi:[0,1]
	s_waitcnt vmcnt(0)
	v_pk_fma_f32 v[20:21], v[34:35], v[42:43], v[38:39]
	s_nop 0
	v_pk_fma_f32 v[20:21], v[20:21], s[24:25], v[16:17] op_sel_hi:[1,0,1]
	v_pk_fma_f32 v[22:23], v[36:37], v[44:45], v[40:41]
	v_mul_f32_e32 v17, v21, v21
	v_pk_fma_f32 v[22:23], v[22:23], s[24:25], v[18:19] op_sel_hi:[1,0,1]
	v_add_f32_e32 v16, v20, v21
	v_fmac_f32_e32 v17, v20, v20
	v_add_f32_e32 v16, v22, v16
	v_fmac_f32_e32 v17, v22, v22
	v_add_f32_e32 v16, v23, v16
	v_fmac_f32_e32 v17, v23, v23
	v_add_f32_e32 v16, v24, v16
	v_add_f32_e32 v17, v25, v17
	ds_bpermute_b32 v18, v116, v16
	ds_bpermute_b32 v19, v116, v17
	global_store_dwordx4 v[52:53], v[20:23], off offset:528
	s_waitcnt lgkmcnt(1)
	v_add_f32_e32 v16, v16, v18
	s_waitcnt lgkmcnt(0)
	v_add_f32_e32 v17, v17, v19
	ds_bpermute_b32 v18, v114, v16
	ds_bpermute_b32 v19, v114, v17
	s_and_saveexec_b64 s[28:29], s[2:3]
	s_cbranch_execz .LBB0_2859
	v_lshl_add_u64 v[20:21], s[10:11], 0, v[32:33]
	s_waitcnt lgkmcnt(1)
	v_add_f32_e32 v16, v16, v18
	s_waitcnt lgkmcnt(0)
	v_add_f32_e32 v17, v17, v19
	flat_atomic_add_f32 v[20:21], v16
	flat_atomic_add_f32 v[20:21], v17 offset:4
; DEVI unsigned pk2(float lo, float hi) { unsigned r; asm("v_cvt_pk_bf16_f32 %0, %1, %2" : "=v"(r) : "v"(lo), "v"(hi)); return r; }
;     DEVI void operator()(const f32x4 (&acc)[2][2][4][2], const pg8::Unit& u, int wr, int wc, int fr, int fq) const {
;     ...
;                 const int row = row0 + ai * 128 + m * 16; float mu, rs; row_stats(stin, row, mu, rs);
;                 float sum = 0.f, sq = 0.f;
; #pragma unroll
;                 for (int bj = 0; bj < 2; ++bj) {
;                     f32x4 z[2];
; #pragma unroll
;                     for (int n = 0; n < 2; ++n) {
;                         const int col = colb + bj * 128 + 4 * n;
;                         f32x4 xv = *(const f32x4*)(zsrc + (size_t)row * DM + col);
;                         if (stin) { const f32x4 gv = *(const f32x4*)(gin + col), bv = *(const f32x4*)(bin + col); xv = (xv - mu) * rs * gv + bv; }
;                         f32x4 zz = ALPHA * xv + acc[ai][bj][m][n];
;                         if (bias) zz += *(const f32x4*)(bias + col);
;                         *(f32x4*)(zdst + (size_t)row * DM + col) = zz;
;                         sum += zz[0] + zz[1] + zz[2] + zz[3]; sq += zz[0] * zz[0] + zz[1] * zz[1] + zz[2] * zz[2] + zz[3] * zz[3];
;                         z[n] = zz;
;                     }
;                     u32x4 o; o.x = pk2(z[0][0], z[0][1]); o.y = pk2(z[0][2], z[0][3]); o.z = pk2(z[1][0], z[1][1]); o.w = pk2(z[1][2], z[1][3]);
;                     if (zb) *(u32x4*)(zb + (size_t)row * DM + colb + bj * 128) = o;
;                 }
;                 sum += __shfl_xor(sum, 16); sq += __shfl_xor(sq, 16);
;                 sum += __shfl_xor(sum, 32); sq += __shfl_xor(sq, 32);
;                 if (fq == 0) { atomicAdd(stout + 2 * (size_t)row, sum); atomicAdd(stout + 2 * (size_t)row + 1, sq); }
.LBB0_2859:
	s_or_b64 exec, exec, s[28:29]
	s_waitcnt lgkmcnt(0)
	v_add_u32_e32 v18, 0xb0, v154
	v_ashrrev_i32_e32 v19, 31, v18
	v_lshlrev_b64 v[16:17], 3, v[18:19]
	v_lshl_add_u64 v[20:21], s[12:13], 0, v[16:17]
	flat_load_dwordx2 v[34:35], v[20:21]
	v_lshlrev_b64 v[18:19], 12, v[18:19]
	v_lshl_add_u64 v[18:19], s[46:47], 0, v[18:19]
	v_lshl_add_u64 v[36:37], v[144:145], 2, v[18:19]
	global_load_dwordx4 v[18:21], v[36:37], off
	global_load_dwordx4 v[22:25], v[150:151], off
	global_load_dwordx4 v[26:29], v[152:153], off
	global_load_dwordx4 v[30:33], v[36:37], off offset:16
	global_load_dwordx4 v[194:197], v[36:37], off offset:512
	global_load_dwordx4 v[198:201], v[36:37], off offset:528
	s_waitcnt vmcnt(0) lgkmcnt(0)
	v_pk_mul_f32 v[34:35], v[34:35], s[22:23] op_sel:[1,0] op_sel_hi:[0,0]
	v_fma_f32 v34, -v35, v35, v34
	v_max_f32_e32 v34, 0, v34
	v_add_f32_e32 v34, 0x3727c5ac, v34
	v_mul_f32_e32 v38, 0x4b800000, v34
	v_cmp_gt_f32_e32 vcc, s55, v34
	v_sub_f32_e32 v19, v19, v35
	v_sub_f32_e32 v18, v18, v35
	v_cndmask_b32_e32 v34, v34, v38, vcc
	v_rsq_f32_e32 v34, v34
	v_sub_f32_e32 v21, v21, v35
	v_sub_f32_e32 v20, v20, v35
	v_sub_f32_e32 v31, v31, v35
	v_mul_f32_e32 v38, 0x45800000, v34
	v_cndmask_b32_e32 v34, v34, v38, vcc
	v_pk_mul_f32 v[20:21], v[20:21], v[34:35] op_sel_hi:[1,0]
	v_pk_mul_f32 v[18:19], v[18:19], v[34:35] op_sel_hi:[1,0]
	v_pk_fma_f32 v[20:21], v[24:25], v[20:21], v[28:29]
	v_pk_fma_f32 v[18:19], v[22:23], v[18:19], v[26:27]
	v_pk_fma_f32 v[14:15], v[20:21], s[24:25], v[14:15] op_sel_hi:[1,0,1]
	v_pk_fma_f32 v[12:13], v[18:19], s[24:25], v[12:13] op_sel_hi:[1,0,1]
	global_store_dwordx4 v[36:37], v[12:15], off
	global_load_dwordx4 v[18:21], v[146:147], off
	global_load_dwordx4 v[22:25], v[148:149], off
	v_sub_f32_e32 v30, v30, v35
	v_sub_f32_e32 v33, v33, v35
	v_sub_f32_e32 v32, v32, v35
	v_pk_mul_f32 v[32:33], v[32:33], v[34:35] op_sel_hi:[1,0]
	v_pk_mul_f32 v[30:31], v[30:31], v[34:35] op_sel_hi:[1,0]
	s_waitcnt vmcnt(0)
	v_pk_fma_f32 v[20:21], v[20:21], v[32:33], v[24:25]
	v_pk_fma_f32 v[18:19], v[18:19], v[30:31], v[22:23]
	v_pk_fma_f32 v[10:11], v[20:21], s[24:25], v[10:11] op_sel_hi:[1,0,1]
	v_pk_fma_f32 v[8:9], v[18:19], s[24:25], v[8:9] op_sel_hi:[1,0,1]
	global_store_dwordx4 v[36:37], v[8:11], off offset:16
	global_load_dwordx4 v[18:21], v[124:125], off
	global_load_dwordx4 v[22:25], v[126:127], off
	s_waitcnt vmcnt(2)
	v_sub_f32_e32 v27, v195, v35
	v_sub_f32_e32 v26, v194, v35
	v_sub_f32_e32 v29, v197, v35
	v_sub_f32_e32 v28, v196, v35
	v_pk_mul_f32 v[28:29], v[34:35], v[28:29] op_sel_hi:[0,1]
	v_pk_mul_f32 v[26:27], v[34:35], v[26:27] op_sel_hi:[0,1]
	s_waitcnt vmcnt(0)
	v_pk_fma_f32 v[18:19], v[18:19], v[26:27], v[22:23]
	v_pk_fma_f32 v[20:21], v[20:21], v[28:29], v[24:25]
	v_pk_fma_f32 v[4:5], v[18:19], s[24:25], v[4:5] op_sel_hi:[1,0,1]
	v_pk_fma_f32 v[6:7], v[20:21], s[24:25], v[6:7] op_sel_hi:[1,0,1]
	global_store_dwordx4 v[36:37], v[4:7], off offset:512
	global_load_dwordx4 v[18:21], v[120:121], off
	global_load_dwordx4 v[22:25], v[122:123], off
	s_waitcnt vmcnt(1)
	v_sub_f32_e32 v26, v198, v35
	v_add_f32_e32 v30, v12, v13
	v_mul_f32_e32 v13, v13, v13
	v_fmac_f32_e32 v13, v12, v12
	v_add_f32_e32 v30, v14, v30
	v_fmac_f32_e32 v13, v14, v14
	v_add_f32_e32 v14, v8, v9
	v_mul_f32_e32 v9, v9, v9
	v_fmac_f32_e32 v9, v8, v8
	v_add_f32_e32 v14, v10, v14
	v_fmac_f32_e32 v9, v10, v10
	v_add_f32_e32 v10, v4, v5
	v_mul_f32_e32 v5, v5, v5
	v_add_f32_e32 v12, v15, v30
	v_fmac_f32_e32 v5, v4, v4
	v_sub_f32_e32 v27, v199, v35
	v_add_f32_e32 v12, 0, v12
	v_fmac_f32_e32 v13, v15, v15
	v_add_f32_e32 v8, v11, v14
	v_fmac_f32_e32 v9, v11, v11
	v_add_f32_e32 v10, v6, v10
	v_fmac_f32_e32 v5, v6, v6
	v_pk_mul_f32 v[26:27], v[34:35], v[26:27] op_sel_hi:[0,1]
	v_add_f32_e32 v8, v8, v12
	v_add_f32_e32 v9, v13, v9
	v_add_f32_e32 v4, v7, v10
	v_fmac_f32_e32 v5, v7, v7
	v_sub_f32_e32 v29, v201, v35
	v_sub_f32_e32 v28, v200, v35
	v_add_f32_e32 v8, v8, v4
	v_add_f32_e32 v9, v9, v5
	v_pk_mul_f32 v[28:29], v[34:35], v[28:29] op_sel_hi:[0,1]
	s_waitcnt vmcnt(0)
	v_pk_fma_f32 v[4:5], v[18:19], v[26:27], v[22:23]
	s_nop 0
	v_pk_fma_f32 v[4:5], v[4:5], s[24:25], v[0:1] op_sel_hi:[1,0,1]
	v_pk_fma_f32 v[6:7], v[20:21], v[28:29], v[24:25]
	v_mul_f32_e32 v1, v5, v5
	v_pk_fma_f32 v[6:7], v[6:7], s[24:25], v[2:3] op_sel_hi:[1,0,1]
	v_add_f32_e32 v0, v4, v5
	v_fmac_f32_e32 v1, v4, v4
	v_add_f32_e32 v0, v6, v0
	v_fmac_f32_e32 v1, v6, v6
	v_add_f32_e32 v0, v7, v0
	v_fmac_f32_e32 v1, v7, v7
	v_add_f32_e32 v0, v8, v0
	v_add_f32_e32 v1, v9, v1
	ds_bpermute_b32 v2, v116, v0
	ds_bpermute_b32 v3, v116, v1
	global_store_dwordx4 v[36:37], v[4:7], off offset:528
	s_waitcnt lgkmcnt(1)
	v_add_f32_e32 v0, v0, v2
	s_waitcnt lgkmcnt(0)
	v_add_f32_e32 v1, v1, v3
	ds_bpermute_b32 v2, v114, v0
	ds_bpermute_b32 v3, v114, v1
	s_and_saveexec_b64 s[28:29], s[2:3]
	s_cbranch_execz .LBB0_2861
	v_lshl_add_u64 v[4:5], s[10:11], 0, v[16:17]
	s_waitcnt lgkmcnt(1)
	v_add_f32_e32 v0, v0, v2
	s_waitcnt lgkmcnt(0)
	v_add_f32_e32 v1, v1, v3
	flat_atomic_add_f32 v[4:5], v0
	flat_atomic_add_f32 v[4:5], v1 offset:4
